# strategy 4: all per-segment s_setprio flips removed, one static s_setprio 1 for waves 4-7 at entry
# speedup vs baseline: 1.0026x; 1.0026x over previous
_Z14fwd_megakernel4Args:
	v_readfirstlane_b32 s98, v0
	s_nop 3
	s_and_b32 s98, s98, 0x3ff
	s_lshr_b32 s98, s98, 8
	s_cmp_eq_u32 s98, 1
	s_cbranch_scc0 .Lprio_done
	s_setprio 1
.Lprio_done:
	s_load_dwordx8 s[36:43], s[0:1], 0x80
	s_load_dword s3, s[0:1], 0xa8
	s_load_dwordx2 s[14:15], s[0:1], 0xa0
	s_add_u32 s6, s0, 0xa0
	v_and_b32_e32 v241, 0x3ff, v0
	s_addc_u32 s7, s1, 0
	v_cmp_gt_u32_e32 vcc, 64, v241
	s_and_saveexec_b64 s[4:5], vcc
	v_lshl_add_u32 v1, v241, 2, 0
	v_add_u32_e32 v1, 0x20000, v1
	v_mov_b32_e32 v2, 0
	ds_write_b32 v1, v2
	s_or_b64 exec, exec, s[4:5]
	s_waitcnt lgkmcnt(0)
	s_barrier
	s_add_u32 s34, s42, 0xe0000
	s_getreg_b32 s4, hwreg(HW_REG_XCC_ID, 0, 4)
	s_addc_u32 s35, s43, 0
	s_and_b32 s52, s4, 15
	v_cmp_eq_u32_e64 s[62:63], 0, v241
	s_and_saveexec_b64 s[4:5], s[62:63]
	s_cbranch_execz .LBB0_5
	s_mov_b64 s[8:9], exec
	v_mbcnt_lo_u32_b32 v1, s8, 0
	v_mbcnt_hi_u32_b32 v1, s9, v1
	v_cmp_eq_u32_e32 vcc, 0, v1
	s_and_b64 s[10:11], exec, vcc
	s_mov_b64 exec, s[10:11]
	s_cbranch_execz .LBB0_5
	s_lshl_b32 s10, s52, 8
	s_bcnt1_i32_b64 s8, s[8:9]
	v_mov_b32_e32 v1, s10
	v_mov_b32_e32 v2, s8
	global_atomic_add v1, v2, s[34:35] offset:1024

.LBB0_191:
	s_ashr_i32 s39, s38, 31
	s_lshl_b64 s[40:41], s[38:39], 19
	s_add_u32 s40, s65, s40
	s_addc_u32 s41, s64, s41
	s_and_b64 s[42:43], s[4:5], exec
	s_cselect_b32 s39, s41, s47
	s_cselect_b32 s78, s40, s46
	s_ashr_i32 s37, s36, 31
	s_lshl_b64 s[42:43], s[36:37], 19
	s_add_u32 s42, s67, s42
	s_addc_u32 s43, s66, s43
	s_and_b64 s[80:81], s[4:5], exec
	s_cselect_b32 s37, s43, s49
	s_cselect_b32 s79, s42, s48
	s_add_u32 s46, s46, 0x40080
	s_addc_u32 s47, s47, 0
	s_add_u32 s80, s48, 0x100
	s_addc_u32 s81, s49, 0
	s_mov_b32 s82, -2
	s_add_u32 s48, s46, 0xfffc0080
	s_addc_u32 s49, s47, -1
	s_add_i32 s83, 0, 0x10000
	s_cmp_eq_u32 s82, 12
	s_cselect_b32 s49, s39, s49
	s_cselect_b32 s48, s78, s48
	v_add_u32_e32 v140, s83, v146
	s_cselect_b32 s85, s37, s81
	s_cselect_b32 s84, s79, s80
	s_add_i32 s86, 0, 0x14000
	ds_read_b128 v[136:139], v140
	ds_read_b128 v[152:155], v140 offset:1024
	ds_read_b128 v[156:159], v140 offset:2048
	ds_read_b128 v[160:163], v140 offset:3072
	v_add_u32_e32 v140, s86, v146
	ds_read_b128 v[164:167], v140
	ds_read_b128 v[168:171], v140 offset:1024
	ds_read_b128 v[172:175], v140 offset:2048
	ds_read_b128 v[176:179], v140 offset:3072
	v_lshl_add_u64 v[140:141], s[46:47], 0, v[132:133]
	s_add_i32 m0, s45, 0xc000
	ds_read_b128 v[180:183], v150
	ds_read_b128 v[184:187], v150 offset:1024
	ds_read_b128 v[188:191], v150 offset:2048
	ds_read_b128 v[192:195], v150 offset:3072
	ds_read_b128 v[196:199], v150 offset:4096
	ds_read_b128 v[200:203], v150 offset:5120
	ds_read_b128 v[204:207], v150 offset:6144
	ds_read_b128 v[208:211], v150 offset:7168
	global_load_lds_dwordx4 v[140:141], off
	v_lshl_add_u64 v[140:141], v[140:141], 0, s[12:13]
	s_add_i32 m0, s45, 0xe000
	s_nop 0
	global_load_lds_dwordx4 v[140:141], off
	s_waitcnt vmcnt(8)
	s_waitcnt lgkmcnt(0)
	s_barrier
	s_waitcnt lgkmcnt(0)
	v_mfma_f32_16x16x32_bf16 v[124:127], v[136:139], v[180:183], 0
	v_mfma_f32_16x16x32_bf16 v[120:123], v[156:159], v[180:183], 0
	v_mfma_f32_16x16x32_bf16 v[112:115], v[136:139], v[188:191], 0
	v_mfma_f32_16x16x32_bf16 v[104:107], v[156:159], v[188:191], 0
	v_mfma_f32_16x16x32_bf16 v[96:99], v[136:139], v[196:199], 0
	v_mfma_f32_16x16x32_bf16 v[88:91], v[156:159], v[196:199], 0
	v_mfma_f32_16x16x32_bf16 v[80:83], v[136:139], v[204:207], 0
	v_mfma_f32_16x16x32_bf16 v[72:75], v[156:159], v[204:207], 0
	v_mfma_f32_16x16x32_bf16 v[124:127], v[152:155], v[184:187], v[124:127]
	v_mfma_f32_16x16x32_bf16 v[120:123], v[160:163], v[184:187], v[120:123]
	v_mfma_f32_16x16x32_bf16 v[112:115], v[152:155], v[192:195], v[112:115]
	v_mfma_f32_16x16x32_bf16 v[104:107], v[160:163], v[192:195], v[104:107]
	v_mfma_f32_16x16x32_bf16 v[96:99], v[152:155], v[200:203], v[96:99]
	v_mfma_f32_16x16x32_bf16 v[88:91], v[160:163], v[200:203], v[88:91]
	v_mfma_f32_16x16x32_bf16 v[80:83], v[152:155], v[208:211], v[80:83]
	v_mfma_f32_16x16x32_bf16 v[72:75], v[160:163], v[208:211], v[72:75]
	v_mfma_f32_16x16x32_bf16 v[116:119], v[164:167], v[180:183], 0
	v_mfma_f32_16x16x32_bf16 v[108:111], v[172:175], v[180:183], 0
	v_mfma_f32_16x16x32_bf16 v[100:103], v[164:167], v[188:191], 0
	v_mfma_f32_16x16x32_bf16 v[92:95], v[172:175], v[188:191], 0
	v_mfma_f32_16x16x32_bf16 v[84:87], v[164:167], v[196:199], 0
	v_mfma_f32_16x16x32_bf16 v[76:79], v[172:175], v[196:199], 0
	v_mfma_f32_16x16x32_bf16 v[68:71], v[164:167], v[204:207], 0
	v_mfma_f32_16x16x32_bf16 v[64:67], v[172:175], v[204:207], 0
	v_mfma_f32_16x16x32_bf16 v[116:119], v[168:171], v[184:187], v[116:119]
	v_mfma_f32_16x16x32_bf16 v[108:111], v[176:179], v[184:187], v[108:111]
	v_mfma_f32_16x16x32_bf16 v[100:103], v[168:171], v[192:195], v[100:103]
	v_mfma_f32_16x16x32_bf16 v[92:95], v[176:179], v[192:195], v[92:95]
	v_mfma_f32_16x16x32_bf16 v[84:87], v[168:171], v[200:203], v[84:87]
	v_mfma_f32_16x16x32_bf16 v[76:79], v[176:179], v[200:203], v[76:79]
	v_mfma_f32_16x16x32_bf16 v[68:71], v[168:171], v[208:211], v[68:71]
	v_mfma_f32_16x16x32_bf16 v[64:67], v[176:179], v[208:211], v[64:67]
	s_barrier
	s_add_i32 s83, s83, s69
	v_lshl_add_u64 v[140:141], s[84:85], 0, v[128:129]
	s_mov_b32 m0, s83
	ds_read_b128 v[180:183], v150 offset:16384
	ds_read_b128 v[184:187], v150 offset:17408
	ds_read_b128 v[188:191], v150 offset:18432
	ds_read_b128 v[192:195], v150 offset:19456
	ds_read_b128 v[196:199], v150 offset:20480
	ds_read_b128 v[200:203], v150 offset:21504
	ds_read_b128 v[204:207], v150 offset:22528
	ds_read_b128 v[208:211], v150 offset:23552
	global_load_lds_dwordx4 v[140:141], off
	v_lshl_add_u64 v[212:213], v[140:141], 0, s[12:13]
	s_add_i32 m0, s83, 0x2000
	s_add_i32 s83, s86, s69
	global_load_lds_dwordx4 v[212:213], off
	v_lshl_add_u64 v[212:213], v[140:141], 0, s[14:15]
	s_mov_b32 m0, s83
	s_nop 0
	global_load_lds_dwordx4 v[212:213], off
	v_lshl_add_u64 v[212:213], v[140:141], 0, s[16:17]
	s_add_i32 m0, s83, 0x2000
	s_nop 0
	global_load_lds_dwordx4 v[212:213], off
	v_lshl_add_u64 v[212:213], s[48:49], 0, v[130:131]
	s_mov_b32 m0, s45
	v_lshl_add_u64 v[214:215], v[212:213], 0, s[12:13]
	global_load_lds_dwordx4 v[212:213], off
	s_mov_b32 m0, s71
	s_nop 0
	global_load_lds_dwordx4 v[214:215], off
	s_waitcnt vmcnt(8)
	s_waitcnt lgkmcnt(0)
	s_barrier
	s_waitcnt lgkmcnt(0)
	v_mfma_f32_16x16x32_bf16 v[60:63], v[136:139], v[180:183], 0
	v_mfma_f32_16x16x32_bf16 v[56:59], v[156:159], v[180:183], 0
	v_mfma_f32_16x16x32_bf16 v[48:51], v[136:139], v[188:191], 0
	v_mfma_f32_16x16x32_bf16 v[40:43], v[156:159], v[188:191], 0
	v_mfma_f32_16x16x32_bf16 v[32:35], v[136:139], v[196:199], 0
	v_mfma_f32_16x16x32_bf16 v[24:27], v[156:159], v[196:199], 0
	v_mfma_f32_16x16x32_bf16 v[16:19], v[136:139], v[204:207], 0
	v_mfma_f32_16x16x32_bf16 v[8:11], v[156:159], v[204:207], 0
	v_mfma_f32_16x16x32_bf16 v[60:63], v[152:155], v[184:187], v[60:63]
	v_mfma_f32_16x16x32_bf16 v[56:59], v[160:163], v[184:187], v[56:59]
	v_mfma_f32_16x16x32_bf16 v[48:51], v[152:155], v[192:195], v[48:51]
	v_mfma_f32_16x16x32_bf16 v[40:43], v[160:163], v[192:195], v[40:43]
	v_mfma_f32_16x16x32_bf16 v[32:35], v[152:155], v[200:203], v[32:35]
	v_mfma_f32_16x16x32_bf16 v[24:27], v[160:163], v[200:203], v[24:27]
	v_mfma_f32_16x16x32_bf16 v[16:19], v[152:155], v[208:211], v[16:19]
	v_mfma_f32_16x16x32_bf16 v[8:11], v[160:163], v[208:211], v[8:11]
	v_mfma_f32_16x16x32_bf16 v[52:55], v[164:167], v[180:183], 0
	v_mfma_f32_16x16x32_bf16 v[44:47], v[172:175], v[180:183], 0
	v_mfma_f32_16x16x32_bf16 v[36:39], v[164:167], v[188:191], 0
	v_mfma_f32_16x16x32_bf16 v[28:31], v[172:175], v[188:191], 0
	v_mfma_f32_16x16x32_bf16 v[20:23], v[164:167], v[196:199], 0
	v_mfma_f32_16x16x32_bf16 v[12:15], v[172:175], v[196:199], 0
	v_mfma_f32_16x16x32_bf16 v[4:7], v[164:167], v[204:207], 0
	v_mfma_f32_16x16x32_bf16 v[0:3], v[172:175], v[204:207], 0
	v_mfma_f32_16x16x32_bf16 v[52:55], v[168:171], v[184:187], v[52:55]
	v_mfma_f32_16x16x32_bf16 v[44:47], v[176:179], v[184:187], v[44:47]
	v_mfma_f32_16x16x32_bf16 v[36:39], v[168:171], v[192:195], v[36:39]
	v_mfma_f32_16x16x32_bf16 v[28:31], v[176:179], v[192:195], v[28:31]
	v_mfma_f32_16x16x32_bf16 v[20:23], v[168:171], v[200:203], v[20:23]
	v_mfma_f32_16x16x32_bf16 v[12:15], v[176:179], v[200:203], v[12:15]
	v_mfma_f32_16x16x32_bf16 v[4:7], v[168:171], v[208:211], v[4:7]
	v_mfma_f32_16x16x32_bf16 v[0:3], v[176:179], v[208:211], v[0:3]
	s_barrier
	s_add_i32 s48, 0, 0x18000
	v_add_u32_e32 v151, s48, v146
	s_add_i32 s49, 0, 0x1c000
	ds_read_b128 v[136:139], v151
	ds_read_b128 v[152:155], v151 offset:1024
	ds_read_b128 v[156:159], v151 offset:2048
	ds_read_b128 v[160:163], v151 offset:3072
	v_add_u32_e32 v151, s49, v146
	ds_read_b128 v[164:167], v151
	ds_read_b128 v[168:171], v151 offset:1024
	ds_read_b128 v[172:175], v151 offset:2048
	ds_read_b128 v[176:179], v151 offset:3072
	s_mov_b32 m0, s72
	v_lshl_add_u64 v[214:215], v[212:213], 0, s[14:15]
	ds_read_b128 v[180:183], v150 offset:32768
	ds_read_b128 v[184:187], v150 offset:33792
	ds_read_b128 v[188:191], v150 offset:34816
	ds_read_b128 v[192:195], v150 offset:35840
	ds_read_b128 v[196:199], v150 offset:36864
	ds_read_b128 v[200:203], v150 offset:37888
	ds_read_b128 v[204:207], v150 offset:38912
	ds_read_b128 v[208:211], v150 offset:39936
	global_load_lds_dwordx4 v[214:215], off
	v_lshl_add_u64 v[214:215], v[212:213], 0, s[16:17]
	s_mov_b32 m0, s73
	s_nop 0
	global_load_lds_dwordx4 v[214:215], off
	s_waitcnt vmcnt(8)
	s_waitcnt lgkmcnt(0)
	s_barrier
	s_waitcnt lgkmcnt(0)
	v_mfma_f32_16x16x32_bf16 v[124:127], v[136:139], v[180:183], v[124:127]
	v_mfma_f32_16x16x32_bf16 v[120:123], v[156:159], v[180:183], v[120:123]
	v_mfma_f32_16x16x32_bf16 v[112:115], v[136:139], v[188:191], v[112:115]
	v_mfma_f32_16x16x32_bf16 v[104:107], v[156:159], v[188:191], v[104:107]
	v_mfma_f32_16x16x32_bf16 v[96:99], v[136:139], v[196:199], v[96:99]
	v_mfma_f32_16x16x32_bf16 v[88:91], v[156:159], v[196:199], v[88:91]
	v_mfma_f32_16x16x32_bf16 v[80:83], v[136:139], v[204:207], v[80:83]
	v_mfma_f32_16x16x32_bf16 v[72:75], v[156:159], v[204:207], v[72:75]
	v_mfma_f32_16x16x32_bf16 v[124:127], v[152:155], v[184:187], v[124:127]
	v_mfma_f32_16x16x32_bf16 v[120:123], v[160:163], v[184:187], v[120:123]
	v_mfma_f32_16x16x32_bf16 v[112:115], v[152:155], v[192:195], v[112:115]
	v_mfma_f32_16x16x32_bf16 v[104:107], v[160:163], v[192:195], v[104:107]
	v_mfma_f32_16x16x32_bf16 v[96:99], v[152:155], v[200:203], v[96:99]
	v_mfma_f32_16x16x32_bf16 v[88:91], v[160:163], v[200:203], v[88:91]
	v_mfma_f32_16x16x32_bf16 v[80:83], v[152:155], v[208:211], v[80:83]
	v_mfma_f32_16x16x32_bf16 v[72:75], v[160:163], v[208:211], v[72:75]
	v_mfma_f32_16x16x32_bf16 v[116:119], v[164:167], v[180:183], v[116:119]
	v_mfma_f32_16x16x32_bf16 v[108:111], v[172:175], v[180:183], v[108:111]
	v_mfma_f32_16x16x32_bf16 v[100:103], v[164:167], v[188:191], v[100:103]
	v_mfma_f32_16x16x32_bf16 v[92:95], v[172:175], v[188:191], v[92:95]
	v_mfma_f32_16x16x32_bf16 v[84:87], v[164:167], v[196:199], v[84:87]
	v_mfma_f32_16x16x32_bf16 v[76:79], v[172:175], v[196:199], v[76:79]
	v_mfma_f32_16x16x32_bf16 v[68:71], v[164:167], v[204:207], v[68:71]
	v_mfma_f32_16x16x32_bf16 v[64:67], v[172:175], v[204:207], v[64:67]
	v_mfma_f32_16x16x32_bf16 v[116:119], v[168:171], v[184:187], v[116:119]
	v_mfma_f32_16x16x32_bf16 v[108:111], v[176:179], v[184:187], v[108:111]
	v_mfma_f32_16x16x32_bf16 v[100:103], v[168:171], v[192:195], v[100:103]
	v_mfma_f32_16x16x32_bf16 v[92:95], v[176:179], v[192:195], v[92:95]
	v_mfma_f32_16x16x32_bf16 v[84:87], v[168:171], v[200:203], v[84:87]
	v_mfma_f32_16x16x32_bf16 v[76:79], v[176:179], v[200:203], v[76:79]
	v_mfma_f32_16x16x32_bf16 v[68:71], v[168:171], v[208:211], v[68:71]
	v_mfma_f32_16x16x32_bf16 v[64:67], v[176:179], v[208:211], v[64:67]
	s_barrier
	s_add_i32 s48, s48, s69
	v_lshl_add_u64 v[214:215], v[140:141], 0, s[18:19]
	s_mov_b32 m0, s48
	ds_read_b128 v[180:183], v150 offset:49152
	ds_read_b128 v[184:187], v150 offset:50176
	ds_read_b128 v[188:191], v150 offset:51200
	ds_read_b128 v[192:195], v150 offset:52224
	ds_read_b128 v[196:199], v150 offset:53248
	ds_read_b128 v[200:203], v150 offset:54272
	ds_read_b128 v[204:207], v150 offset:55296
	ds_read_b128 v[208:211], v150 offset:56320
	global_load_lds_dwordx4 v[214:215], off
	v_lshl_add_u64 v[214:215], v[140:141], 0, s[20:21]
	s_add_i32 m0, s48, 0x2000
	s_add_i32 s48, s49, s69
	global_load_lds_dwordx4 v[214:215], off
	v_lshl_add_u64 v[214:215], v[140:141], 0, s[22:23]
	s_mov_b32 m0, s48
	v_lshl_add_u64 v[140:141], v[140:141], 0, s[24:25]
	global_load_lds_dwordx4 v[214:215], off
	s_add_i32 m0, s48, 0x2000
	s_nop 0
	global_load_lds_dwordx4 v[140:141], off
	v_lshl_add_u64 v[140:141], v[212:213], 0, s[18:19]
	s_mov_b32 m0, s10
	s_nop 0
	global_load_lds_dwordx4 v[140:141], off
	v_lshl_add_u64 v[140:141], v[212:213], 0, s[20:21]
	s_mov_b32 m0, s74
	s_nop 0
	global_load_lds_dwordx4 v[140:141], off
	s_waitcnt vmcnt(8)
	s_waitcnt lgkmcnt(0)
	s_barrier
	s_waitcnt lgkmcnt(0)
	v_mfma_f32_16x16x32_bf16 v[60:63], v[136:139], v[180:183], v[60:63]
	v_mfma_f32_16x16x32_bf16 v[56:59], v[156:159], v[180:183], v[56:59]
	v_mfma_f32_16x16x32_bf16 v[48:51], v[136:139], v[188:191], v[48:51]
	v_mfma_f32_16x16x32_bf16 v[40:43], v[156:159], v[188:191], v[40:43]
	v_mfma_f32_16x16x32_bf16 v[32:35], v[136:139], v[196:199], v[32:35]
	v_mfma_f32_16x16x32_bf16 v[24:27], v[156:159], v[196:199], v[24:27]
	v_mfma_f32_16x16x32_bf16 v[16:19], v[136:139], v[204:207], v[16:19]
	v_mfma_f32_16x16x32_bf16 v[8:11], v[156:159], v[204:207], v[8:11]
	v_mfma_f32_16x16x32_bf16 v[60:63], v[152:155], v[184:187], v[60:63]
	v_mfma_f32_16x16x32_bf16 v[56:59], v[160:163], v[184:187], v[56:59]
	v_mfma_f32_16x16x32_bf16 v[48:51], v[152:155], v[192:195], v[48:51]
	v_mfma_f32_16x16x32_bf16 v[40:43], v[160:163], v[192:195], v[40:43]
	v_mfma_f32_16x16x32_bf16 v[32:35], v[152:155], v[200:203], v[32:35]
	v_mfma_f32_16x16x32_bf16 v[24:27], v[160:163], v[200:203], v[24:27]
	v_mfma_f32_16x16x32_bf16 v[16:19], v[152:155], v[208:211], v[16:19]
	v_mfma_f32_16x16x32_bf16 v[8:11], v[160:163], v[208:211], v[8:11]
	v_mfma_f32_16x16x32_bf16 v[52:55], v[164:167], v[180:183], v[52:55]
	v_mfma_f32_16x16x32_bf16 v[44:47], v[172:175], v[180:183], v[44:47]
	v_mfma_f32_16x16x32_bf16 v[36:39], v[164:167], v[188:191], v[36:39]
	v_mfma_f32_16x16x32_bf16 v[28:31], v[172:175], v[188:191], v[28:31]
	v_mfma_f32_16x16x32_bf16 v[20:23], v[164:167], v[196:199], v[20:23]
	v_mfma_f32_16x16x32_bf16 v[12:15], v[172:175], v[196:199], v[12:15]
	v_mfma_f32_16x16x32_bf16 v[4:7], v[164:167], v[204:207], v[4:7]
	v_mfma_f32_16x16x32_bf16 v[0:3], v[172:175], v[204:207], v[0:3]
	v_mfma_f32_16x16x32_bf16 v[52:55], v[168:171], v[184:187], v[52:55]
	v_mfma_f32_16x16x32_bf16 v[44:47], v[176:179], v[184:187], v[44:47]
	v_mfma_f32_16x16x32_bf16 v[36:39], v[168:171], v[192:195], v[36:39]
	v_mfma_f32_16x16x32_bf16 v[28:31], v[176:179], v[192:195], v[28:31]
	v_mfma_f32_16x16x32_bf16 v[20:23], v[168:171], v[200:203], v[20:23]
	v_mfma_f32_16x16x32_bf16 v[12:15], v[176:179], v[200:203], v[12:15]
	v_mfma_f32_16x16x32_bf16 v[4:7], v[168:171], v[208:211], v[4:7]
	v_mfma_f32_16x16x32_bf16 v[0:3], v[176:179], v[208:211], v[0:3]
	s_barrier
	s_add_i32 s82, s82, 2
	s_add_u32 s46, s46, 0x100
	s_addc_u32 s47, s47, 0
	s_add_u32 s80, s80, 0x100
	s_addc_u32 s81, s81, 0
	s_cmp_gt_u32 s82, 13
.LBB0_192:
	s_add_u32 s48, s46, 0xfffc0080
	s_addc_u32 s49, s47, -1
	s_add_i32 s83, 0, 0x10000
	s_cmp_eq_u32 s82, 12
	s_cselect_b32 s49, s39, s49
	s_cselect_b32 s48, s78, s48
	v_add_u32_e32 v140, s83, v146
	s_cselect_b32 s85, s37, s81
	s_cselect_b32 s84, s79, s80
	s_add_i32 s86, 0, 0x14000
	ds_read_b128 v[136:139], v140
	ds_read_b128 v[152:155], v140 offset:1024
	ds_read_b128 v[156:159], v140 offset:2048
	ds_read_b128 v[160:163], v140 offset:3072
	v_add_u32_e32 v140, s86, v146
	ds_read_b128 v[164:167], v140
	ds_read_b128 v[168:171], v140 offset:1024
	ds_read_b128 v[172:175], v140 offset:2048
	ds_read_b128 v[176:179], v140 offset:3072
	v_lshl_add_u64 v[140:141], s[46:47], 0, v[132:133]
	s_add_i32 m0, s45, 0xc000
	ds_read_b128 v[180:183], v150
	ds_read_b128 v[184:187], v150 offset:1024
	ds_read_b128 v[188:191], v150 offset:2048
	ds_read_b128 v[192:195], v150 offset:3072
	ds_read_b128 v[196:199], v150 offset:4096
	ds_read_b128 v[200:203], v150 offset:5120
	ds_read_b128 v[204:207], v150 offset:6144
	ds_read_b128 v[208:211], v150 offset:7168
	global_load_lds_dwordx4 v[140:141], off
	v_lshl_add_u64 v[140:141], v[140:141], 0, s[12:13]
	s_add_i32 m0, s45, 0xe000
	s_nop 0
	global_load_lds_dwordx4 v[140:141], off
	s_waitcnt vmcnt(8)
	s_waitcnt lgkmcnt(0)
	s_barrier
	s_waitcnt lgkmcnt(0)
	v_mfma_f32_16x16x32_bf16 v[124:127], v[136:139], v[180:183], v[124:127]
	v_mfma_f32_16x16x32_bf16 v[120:123], v[156:159], v[180:183], v[120:123]
	v_mfma_f32_16x16x32_bf16 v[112:115], v[136:139], v[188:191], v[112:115]
	v_mfma_f32_16x16x32_bf16 v[104:107], v[156:159], v[188:191], v[104:107]
	v_mfma_f32_16x16x32_bf16 v[96:99], v[136:139], v[196:199], v[96:99]
	v_mfma_f32_16x16x32_bf16 v[88:91], v[156:159], v[196:199], v[88:91]
	v_mfma_f32_16x16x32_bf16 v[80:83], v[136:139], v[204:207], v[80:83]
	v_mfma_f32_16x16x32_bf16 v[72:75], v[156:159], v[204:207], v[72:75]
	v_mfma_f32_16x16x32_bf16 v[124:127], v[152:155], v[184:187], v[124:127]
	v_mfma_f32_16x16x32_bf16 v[120:123], v[160:163], v[184:187], v[120:123]
	v_mfma_f32_16x16x32_bf16 v[112:115], v[152:155], v[192:195], v[112:115]
	v_mfma_f32_16x16x32_bf16 v[104:107], v[160:163], v[192:195], v[104:107]
	v_mfma_f32_16x16x32_bf16 v[96:99], v[152:155], v[200:203], v[96:99]
	v_mfma_f32_16x16x32_bf16 v[88:91], v[160:163], v[200:203], v[88:91]
	v_mfma_f32_16x16x32_bf16 v[80:83], v[152:155], v[208:211], v[80:83]
	v_mfma_f32_16x16x32_bf16 v[72:75], v[160:163], v[208:211], v[72:75]
	v_mfma_f32_16x16x32_bf16 v[116:119], v[164:167], v[180:183], v[116:119]
	v_mfma_f32_16x16x32_bf16 v[108:111], v[172:175], v[180:183], v[108:111]
	v_mfma_f32_16x16x32_bf16 v[100:103], v[164:167], v[188:191], v[100:103]
	v_mfma_f32_16x16x32_bf16 v[92:95], v[172:175], v[188:191], v[92:95]
	v_mfma_f32_16x16x32_bf16 v[84:87], v[164:167], v[196:199], v[84:87]
	v_mfma_f32_16x16x32_bf16 v[76:79], v[172:175], v[196:199], v[76:79]
	v_mfma_f32_16x16x32_bf16 v[68:71], v[164:167], v[204:207], v[68:71]
	v_mfma_f32_16x16x32_bf16 v[64:67], v[172:175], v[204:207], v[64:67]
	v_mfma_f32_16x16x32_bf16 v[116:119], v[168:171], v[184:187], v[116:119]
	v_mfma_f32_16x16x32_bf16 v[108:111], v[176:179], v[184:187], v[108:111]
	v_mfma_f32_16x16x32_bf16 v[100:103], v[168:171], v[192:195], v[100:103]
	v_mfma_f32_16x16x32_bf16 v[92:95], v[176:179], v[192:195], v[92:95]
	v_mfma_f32_16x16x32_bf16 v[84:87], v[168:171], v[200:203], v[84:87]
	v_mfma_f32_16x16x32_bf16 v[76:79], v[176:179], v[200:203], v[76:79]
	v_mfma_f32_16x16x32_bf16 v[68:71], v[168:171], v[208:211], v[68:71]
	v_mfma_f32_16x16x32_bf16 v[64:67], v[176:179], v[208:211], v[64:67]
	s_barrier
	s_add_i32 s83, s83, s69
	v_lshl_add_u64 v[140:141], s[84:85], 0, v[128:129]
	s_mov_b32 m0, s83
	ds_read_b128 v[180:183], v150 offset:16384
	ds_read_b128 v[184:187], v150 offset:17408
	ds_read_b128 v[188:191], v150 offset:18432
	ds_read_b128 v[192:195], v150 offset:19456
	ds_read_b128 v[196:199], v150 offset:20480
	ds_read_b128 v[200:203], v150 offset:21504
	ds_read_b128 v[204:207], v150 offset:22528
	ds_read_b128 v[208:211], v150 offset:23552
	global_load_lds_dwordx4 v[140:141], off
	v_lshl_add_u64 v[212:213], v[140:141], 0, s[12:13]
	s_add_i32 m0, s83, 0x2000
	s_add_i32 s83, s86, s69
	global_load_lds_dwordx4 v[212:213], off
	v_lshl_add_u64 v[212:213], v[140:141], 0, s[14:15]
	s_mov_b32 m0, s83
	s_nop 0
	global_load_lds_dwordx4 v[212:213], off
	v_lshl_add_u64 v[212:213], v[140:141], 0, s[16:17]
	s_add_i32 m0, s83, 0x2000
	s_nop 0
	global_load_lds_dwordx4 v[212:213], off
	v_lshl_add_u64 v[212:213], s[48:49], 0, v[130:131]
	s_mov_b32 m0, s45
	v_lshl_add_u64 v[214:215], v[212:213], 0, s[12:13]
	global_load_lds_dwordx4 v[212:213], off
	s_mov_b32 m0, s71
	s_nop 0
	global_load_lds_dwordx4 v[214:215], off
	s_waitcnt vmcnt(8)
	s_waitcnt lgkmcnt(0)
	s_barrier
	s_waitcnt lgkmcnt(0)
	v_mfma_f32_16x16x32_bf16 v[60:63], v[136:139], v[180:183], v[60:63]
	v_mfma_f32_16x16x32_bf16 v[56:59], v[156:159], v[180:183], v[56:59]
	v_mfma_f32_16x16x32_bf16 v[48:51], v[136:139], v[188:191], v[48:51]
	v_mfma_f32_16x16x32_bf16 v[40:43], v[156:159], v[188:191], v[40:43]
	v_mfma_f32_16x16x32_bf16 v[32:35], v[136:139], v[196:199], v[32:35]
	v_mfma_f32_16x16x32_bf16 v[24:27], v[156:159], v[196:199], v[24:27]
	v_mfma_f32_16x16x32_bf16 v[16:19], v[136:139], v[204:207], v[16:19]
	v_mfma_f32_16x16x32_bf16 v[8:11], v[156:159], v[204:207], v[8:11]
	v_mfma_f32_16x16x32_bf16 v[60:63], v[152:155], v[184:187], v[60:63]
	v_mfma_f32_16x16x32_bf16 v[56:59], v[160:163], v[184:187], v[56:59]
	v_mfma_f32_16x16x32_bf16 v[48:51], v[152:155], v[192:195], v[48:51]
	v_mfma_f32_16x16x32_bf16 v[40:43], v[160:163], v[192:195], v[40:43]
	v_mfma_f32_16x16x32_bf16 v[32:35], v[152:155], v[200:203], v[32:35]
	v_mfma_f32_16x16x32_bf16 v[24:27], v[160:163], v[200:203], v[24:27]
	v_mfma_f32_16x16x32_bf16 v[16:19], v[152:155], v[208:211], v[16:19]
	v_mfma_f32_16x16x32_bf16 v[8:11], v[160:163], v[208:211], v[8:11]
	v_mfma_f32_16x16x32_bf16 v[52:55], v[164:167], v[180:183], v[52:55]
	v_mfma_f32_16x16x32_bf16 v[44:47], v[172:175], v[180:183], v[44:47]
	v_mfma_f32_16x16x32_bf16 v[36:39], v[164:167], v[188:191], v[36:39]
	v_mfma_f32_16x16x32_bf16 v[28:31], v[172:175], v[188:191], v[28:31]
	v_mfma_f32_16x16x32_bf16 v[20:23], v[164:167], v[196:199], v[20:23]
	v_mfma_f32_16x16x32_bf16 v[12:15], v[172:175], v[196:199], v[12:15]
	v_mfma_f32_16x16x32_bf16 v[4:7], v[164:167], v[204:207], v[4:7]
	v_mfma_f32_16x16x32_bf16 v[0:3], v[172:175], v[204:207], v[0:3]
	v_mfma_f32_16x16x32_bf16 v[52:55], v[168:171], v[184:187], v[52:55]
	v_mfma_f32_16x16x32_bf16 v[44:47], v[176:179], v[184:187], v[44:47]
	v_mfma_f32_16x16x32_bf16 v[36:39], v[168:171], v[192:195], v[36:39]
	v_mfma_f32_16x16x32_bf16 v[28:31], v[176:179], v[192:195], v[28:31]
	v_mfma_f32_16x16x32_bf16 v[20:23], v[168:171], v[200:203], v[20:23]
	v_mfma_f32_16x16x32_bf16 v[12:15], v[176:179], v[200:203], v[12:15]
	v_mfma_f32_16x16x32_bf16 v[4:7], v[168:171], v[208:211], v[4:7]
	v_mfma_f32_16x16x32_bf16 v[0:3], v[176:179], v[208:211], v[0:3]
	s_barrier
	s_add_i32 s48, 0, 0x18000
	v_add_u32_e32 v151, s48, v146
	s_add_i32 s49, 0, 0x1c000
	ds_read_b128 v[136:139], v151
	ds_read_b128 v[152:155], v151 offset:1024
	ds_read_b128 v[156:159], v151 offset:2048
	ds_read_b128 v[160:163], v151 offset:3072
	v_add_u32_e32 v151, s49, v146
	ds_read_b128 v[164:167], v151
	ds_read_b128 v[168:171], v151 offset:1024
	ds_read_b128 v[172:175], v151 offset:2048
	ds_read_b128 v[176:179], v151 offset:3072
	s_mov_b32 m0, s72
	v_lshl_add_u64 v[214:215], v[212:213], 0, s[14:15]
	ds_read_b128 v[180:183], v150 offset:32768
	ds_read_b128 v[184:187], v150 offset:33792
	ds_read_b128 v[188:191], v150 offset:34816
	ds_read_b128 v[192:195], v150 offset:35840
	ds_read_b128 v[196:199], v150 offset:36864
	ds_read_b128 v[200:203], v150 offset:37888
	ds_read_b128 v[204:207], v150 offset:38912
	ds_read_b128 v[208:211], v150 offset:39936
	global_load_lds_dwordx4 v[214:215], off
	v_lshl_add_u64 v[214:215], v[212:213], 0, s[16:17]
	s_mov_b32 m0, s73
	s_nop 0
	global_load_lds_dwordx4 v[214:215], off
	s_waitcnt vmcnt(8)
	s_waitcnt lgkmcnt(0)
	s_barrier
	s_waitcnt lgkmcnt(0)
	v_mfma_f32_16x16x32_bf16 v[124:127], v[136:139], v[180:183], v[124:127]
	v_mfma_f32_16x16x32_bf16 v[120:123], v[156:159], v[180:183], v[120:123]
	v_mfma_f32_16x16x32_bf16 v[112:115], v[136:139], v[188:191], v[112:115]
	v_mfma_f32_16x16x32_bf16 v[104:107], v[156:159], v[188:191], v[104:107]
	v_mfma_f32_16x16x32_bf16 v[96:99], v[136:139], v[196:199], v[96:99]
	v_mfma_f32_16x16x32_bf16 v[88:91], v[156:159], v[196:199], v[88:91]
	v_mfma_f32_16x16x32_bf16 v[80:83], v[136:139], v[204:207], v[80:83]
	v_mfma_f32_16x16x32_bf16 v[72:75], v[156:159], v[204:207], v[72:75]
	v_mfma_f32_16x16x32_bf16 v[124:127], v[152:155], v[184:187], v[124:127]
	v_mfma_f32_16x16x32_bf16 v[120:123], v[160:163], v[184:187], v[120:123]
	v_mfma_f32_16x16x32_bf16 v[112:115], v[152:155], v[192:195], v[112:115]
	v_mfma_f32_16x16x32_bf16 v[104:107], v[160:163], v[192:195], v[104:107]
	v_mfma_f32_16x16x32_bf16 v[96:99], v[152:155], v[200:203], v[96:99]
	v_mfma_f32_16x16x32_bf16 v[88:91], v[160:163], v[200:203], v[88:91]
	v_mfma_f32_16x16x32_bf16 v[80:83], v[152:155], v[208:211], v[80:83]
	v_mfma_f32_16x16x32_bf16 v[72:75], v[160:163], v[208:211], v[72:75]
	v_mfma_f32_16x16x32_bf16 v[116:119], v[164:167], v[180:183], v[116:119]
	v_mfma_f32_16x16x32_bf16 v[108:111], v[172:175], v[180:183], v[108:111]
	v_mfma_f32_16x16x32_bf16 v[100:103], v[164:167], v[188:191], v[100:103]
	v_mfma_f32_16x16x32_bf16 v[92:95], v[172:175], v[188:191], v[92:95]
	v_mfma_f32_16x16x32_bf16 v[84:87], v[164:167], v[196:199], v[84:87]
	v_mfma_f32_16x16x32_bf16 v[76:79], v[172:175], v[196:199], v[76:79]
	v_mfma_f32_16x16x32_bf16 v[68:71], v[164:167], v[204:207], v[68:71]
	v_mfma_f32_16x16x32_bf16 v[64:67], v[172:175], v[204:207], v[64:67]
	v_mfma_f32_16x16x32_bf16 v[116:119], v[168:171], v[184:187], v[116:119]
	v_mfma_f32_16x16x32_bf16 v[108:111], v[176:179], v[184:187], v[108:111]
	v_mfma_f32_16x16x32_bf16 v[100:103], v[168:171], v[192:195], v[100:103]
	v_mfma_f32_16x16x32_bf16 v[92:95], v[176:179], v[192:195], v[92:95]
	v_mfma_f32_16x16x32_bf16 v[84:87], v[168:171], v[200:203], v[84:87]
	v_mfma_f32_16x16x32_bf16 v[76:79], v[176:179], v[200:203], v[76:79]
	v_mfma_f32_16x16x32_bf16 v[68:71], v[168:171], v[208:211], v[68:71]
	v_mfma_f32_16x16x32_bf16 v[64:67], v[176:179], v[208:211], v[64:67]
	s_barrier
	s_add_i32 s48, s48, s69
	v_lshl_add_u64 v[214:215], v[140:141], 0, s[18:19]
	s_mov_b32 m0, s48
	ds_read_b128 v[180:183], v150 offset:49152
	ds_read_b128 v[184:187], v150 offset:50176
	ds_read_b128 v[188:191], v150 offset:51200
	ds_read_b128 v[192:195], v150 offset:52224
	ds_read_b128 v[196:199], v150 offset:53248
	ds_read_b128 v[200:203], v150 offset:54272
	ds_read_b128 v[204:207], v150 offset:55296
	ds_read_b128 v[208:211], v150 offset:56320
	global_load_lds_dwordx4 v[214:215], off
	v_lshl_add_u64 v[214:215], v[140:141], 0, s[20:21]
	s_add_i32 m0, s48, 0x2000
	s_add_i32 s48, s49, s69
	global_load_lds_dwordx4 v[214:215], off
	v_lshl_add_u64 v[214:215], v[140:141], 0, s[22:23]
	s_mov_b32 m0, s48
	v_lshl_add_u64 v[140:141], v[140:141], 0, s[24:25]
	global_load_lds_dwordx4 v[214:215], off
	s_add_i32 m0, s48, 0x2000
	s_nop 0
	global_load_lds_dwordx4 v[140:141], off
	v_lshl_add_u64 v[140:141], v[212:213], 0, s[18:19]
	s_mov_b32 m0, s10
	s_nop 0
	global_load_lds_dwordx4 v[140:141], off
	v_lshl_add_u64 v[140:141], v[212:213], 0, s[20:21]
	s_mov_b32 m0, s74
	s_nop 0
	global_load_lds_dwordx4 v[140:141], off
	s_waitcnt vmcnt(8)
	s_waitcnt lgkmcnt(0)
	s_barrier
	s_waitcnt lgkmcnt(0)
	v_mfma_f32_16x16x32_bf16 v[60:63], v[136:139], v[180:183], v[60:63]
	v_mfma_f32_16x16x32_bf16 v[56:59], v[156:159], v[180:183], v[56:59]
	v_mfma_f32_16x16x32_bf16 v[48:51], v[136:139], v[188:191], v[48:51]
	v_mfma_f32_16x16x32_bf16 v[40:43], v[156:159], v[188:191], v[40:43]
	v_mfma_f32_16x16x32_bf16 v[32:35], v[136:139], v[196:199], v[32:35]
	v_mfma_f32_16x16x32_bf16 v[24:27], v[156:159], v[196:199], v[24:27]
	v_mfma_f32_16x16x32_bf16 v[16:19], v[136:139], v[204:207], v[16:19]
	v_mfma_f32_16x16x32_bf16 v[8:11], v[156:159], v[204:207], v[8:11]
	v_mfma_f32_16x16x32_bf16 v[60:63], v[152:155], v[184:187], v[60:63]
	v_mfma_f32_16x16x32_bf16 v[56:59], v[160:163], v[184:187], v[56:59]
	v_mfma_f32_16x16x32_bf16 v[48:51], v[152:155], v[192:195], v[48:51]
	v_mfma_f32_16x16x32_bf16 v[40:43], v[160:163], v[192:195], v[40:43]
	v_mfma_f32_16x16x32_bf16 v[32:35], v[152:155], v[200:203], v[32:35]
	v_mfma_f32_16x16x32_bf16 v[24:27], v[160:163], v[200:203], v[24:27]
	v_mfma_f32_16x16x32_bf16 v[16:19], v[152:155], v[208:211], v[16:19]
	v_mfma_f32_16x16x32_bf16 v[8:11], v[160:163], v[208:211], v[8:11]
	v_mfma_f32_16x16x32_bf16 v[52:55], v[164:167], v[180:183], v[52:55]
	v_mfma_f32_16x16x32_bf16 v[44:47], v[172:175], v[180:183], v[44:47]
	v_mfma_f32_16x16x32_bf16 v[36:39], v[164:167], v[188:191], v[36:39]
	v_mfma_f32_16x16x32_bf16 v[28:31], v[172:175], v[188:191], v[28:31]
	v_mfma_f32_16x16x32_bf16 v[20:23], v[164:167], v[196:199], v[20:23]
	v_mfma_f32_16x16x32_bf16 v[12:15], v[172:175], v[196:199], v[12:15]
	v_mfma_f32_16x16x32_bf16 v[4:7], v[164:167], v[204:207], v[4:7]
	v_mfma_f32_16x16x32_bf16 v[0:3], v[172:175], v[204:207], v[0:3]
	v_mfma_f32_16x16x32_bf16 v[52:55], v[168:171], v[184:187], v[52:55]
	v_mfma_f32_16x16x32_bf16 v[44:47], v[176:179], v[184:187], v[44:47]
	v_mfma_f32_16x16x32_bf16 v[36:39], v[168:171], v[192:195], v[36:39]
	v_mfma_f32_16x16x32_bf16 v[28:31], v[176:179], v[192:195], v[28:31]
	v_mfma_f32_16x16x32_bf16 v[20:23], v[168:171], v[200:203], v[20:23]
	v_mfma_f32_16x16x32_bf16 v[12:15], v[176:179], v[200:203], v[12:15]
	v_mfma_f32_16x16x32_bf16 v[4:7], v[168:171], v[208:211], v[4:7]
	v_mfma_f32_16x16x32_bf16 v[0:3], v[176:179], v[208:211], v[0:3]
	s_barrier
	s_add_i32 s82, s82, 2
	s_add_u32 s46, s46, 0x100
	s_addc_u32 s47, s47, 0
	s_add_u32 s80, s80, 0x100
	s_addc_u32 s81, s81, 0
	s_cmp_gt_u32 s82, 13
	s_cbranch_scc0 .LBB0_192
	s_and_b64 vcc, exec, s[30:31]
	s_cbranch_vccz .LBB0_195
	s_barrier

.LBB0_228:
	s_ashr_i32 s45, s44, 31
	s_lshl_b64 s[46:47], s[44:45], 19
	s_add_u32 s46, s64, s46
	s_addc_u32 s47, s65, s47
	s_and_b64 s[48:49], s[38:39], exec
	s_cselect_b32 s22, s47, s15
	s_cselect_b32 s45, s46, s14
	s_ashr_i32 s43, s42, 31
	s_lshl_b64 s[48:49], s[42:43], 19
	s_add_u32 s48, s6, s48
	s_addc_u32 s49, s19, s49
	s_and_b64 s[60:61], s[38:39], exec
	s_cselect_b32 s43, s49, s17
	s_cselect_b32 s84, s48, s16
	s_add_u32 s60, s14, 0x40080
	s_addc_u32 s61, s15, 0
	s_add_u32 s16, s16, 0x100
	s_addc_u32 s17, s17, 0
	s_mov_b32 s85, -2
	s_add_u32 s14, s60, 0xfffc0080
	s_addc_u32 s15, s61, -1
	s_add_i32 s18, 0, 0x10000
	s_cmp_eq_u32 s85, 12
	s_cselect_b32 s15, s22, s15
	s_cselect_b32 s14, s45, s14
	v_add_u32_e32 v137, s18, v141
	s_cselect_b32 vcc_hi, s43, s17
	s_cselect_b32 vcc_lo, s84, s16
	s_add_i32 s21, 0, 0x14000
	ds_read_b128 v[146:149], v137
	ds_read_b128 v[150:153], v137 offset:1024
	ds_read_b128 v[154:157], v137 offset:2048
	ds_read_b128 v[158:161], v137 offset:3072
	v_add_u32_e32 v137, s21, v141
	ds_read_b128 v[162:165], v137
	ds_read_b128 v[166:169], v137 offset:1024
	ds_read_b128 v[170:173], v137 offset:2048
	ds_read_b128 v[174:177], v137 offset:3072
	v_lshl_add_u64 v[138:139], s[60:61], 0, v[184:185]
	s_add_i32 m0, s25, 0xc000
	ds_read_b128 v[178:181], v145
	ds_read_b128 v[194:197], v145 offset:1024
	ds_read_b128 v[198:201], v145 offset:2048
	ds_read_b128 v[202:205], v145 offset:3072
	ds_read_b128 v[206:209], v145 offset:4096
	ds_read_b128 v[210:213], v145 offset:5120
	ds_read_b128 v[214:217], v145 offset:6144
	ds_read_b128 v[218:221], v145 offset:7168
	global_load_lds_dwordx4 v[138:139], off
	v_lshl_add_u64 v[138:139], v[138:139], 0, s[34:35]
	s_add_i32 m0, s25, 0xe000
	s_nop 0
	global_load_lds_dwordx4 v[138:139], off
	s_waitcnt vmcnt(8)
	s_waitcnt lgkmcnt(0)
	s_barrier
	s_waitcnt lgkmcnt(0)
	v_mfma_f32_16x16x32_bf16 v[124:127], v[146:149], v[178:181], 0
	v_mfma_f32_16x16x32_bf16 v[120:123], v[154:157], v[178:181], 0
	v_mfma_f32_16x16x32_bf16 v[112:115], v[146:149], v[198:201], 0
	v_mfma_f32_16x16x32_bf16 v[104:107], v[154:157], v[198:201], 0
	v_mfma_f32_16x16x32_bf16 v[96:99], v[146:149], v[206:209], 0
	v_mfma_f32_16x16x32_bf16 v[88:91], v[154:157], v[206:209], 0
	v_mfma_f32_16x16x32_bf16 v[80:83], v[146:149], v[214:217], 0
	v_mfma_f32_16x16x32_bf16 v[72:75], v[154:157], v[214:217], 0
	v_mfma_f32_16x16x32_bf16 v[124:127], v[150:153], v[194:197], v[124:127]
	v_mfma_f32_16x16x32_bf16 v[120:123], v[158:161], v[194:197], v[120:123]
	v_mfma_f32_16x16x32_bf16 v[112:115], v[150:153], v[202:205], v[112:115]
	v_mfma_f32_16x16x32_bf16 v[104:107], v[158:161], v[202:205], v[104:107]
	v_mfma_f32_16x16x32_bf16 v[96:99], v[150:153], v[210:213], v[96:99]
	v_mfma_f32_16x16x32_bf16 v[88:91], v[158:161], v[210:213], v[88:91]
	v_mfma_f32_16x16x32_bf16 v[80:83], v[150:153], v[218:221], v[80:83]
	v_mfma_f32_16x16x32_bf16 v[72:75], v[158:161], v[218:221], v[72:75]
	v_mfma_f32_16x16x32_bf16 v[116:119], v[162:165], v[178:181], 0
	v_mfma_f32_16x16x32_bf16 v[108:111], v[170:173], v[178:181], 0
	v_mfma_f32_16x16x32_bf16 v[100:103], v[162:165], v[198:201], 0
	v_mfma_f32_16x16x32_bf16 v[92:95], v[170:173], v[198:201], 0
	v_mfma_f32_16x16x32_bf16 v[84:87], v[162:165], v[206:209], 0
	v_mfma_f32_16x16x32_bf16 v[76:79], v[170:173], v[206:209], 0
	v_mfma_f32_16x16x32_bf16 v[68:71], v[162:165], v[214:217], 0
	v_mfma_f32_16x16x32_bf16 v[64:67], v[170:173], v[214:217], 0
	v_mfma_f32_16x16x32_bf16 v[116:119], v[166:169], v[194:197], v[116:119]
	v_mfma_f32_16x16x32_bf16 v[108:111], v[174:177], v[194:197], v[108:111]
	v_mfma_f32_16x16x32_bf16 v[100:103], v[166:169], v[202:205], v[100:103]
	v_mfma_f32_16x16x32_bf16 v[92:95], v[174:177], v[202:205], v[92:95]
	v_mfma_f32_16x16x32_bf16 v[84:87], v[166:169], v[210:213], v[84:87]
	v_mfma_f32_16x16x32_bf16 v[76:79], v[174:177], v[210:213], v[76:79]
	v_mfma_f32_16x16x32_bf16 v[68:71], v[166:169], v[218:221], v[68:71]
	v_mfma_f32_16x16x32_bf16 v[64:67], v[174:177], v[218:221], v[64:67]
	s_barrier
	s_add_i32 s18, s18, s23
	v_lshl_add_u64 v[138:139], vcc, 0, v[128:129]
	s_mov_b32 m0, s18
	ds_read_b128 v[178:181], v145 offset:16384
	ds_read_b128 v[194:197], v145 offset:17408
	ds_read_b128 v[198:201], v145 offset:18432
	ds_read_b128 v[202:205], v145 offset:19456
	ds_read_b128 v[206:209], v145 offset:20480
	ds_read_b128 v[210:213], v145 offset:21504
	ds_read_b128 v[214:217], v145 offset:22528
	ds_read_b128 v[218:221], v145 offset:23552
	global_load_lds_dwordx4 v[138:139], off
	v_lshl_add_u64 v[182:183], v[138:139], 0, s[34:35]
	s_add_i32 m0, s18, 0x2000
	s_add_i32 s18, s21, s23
	global_load_lds_dwordx4 v[182:183], off
	v_lshl_add_u64 v[182:183], v[138:139], 0, s[92:93]
	s_mov_b32 m0, s18
	s_nop 0
	global_load_lds_dwordx4 v[182:183], off
	v_lshl_add_u64 v[182:183], v[138:139], 0, s[52:53]
	s_add_i32 m0, s18, 0x2000
	s_nop 0
	global_load_lds_dwordx4 v[182:183], off
	v_lshl_add_u64 v[182:183], s[14:15], 0, v[130:131]
	s_mov_b32 m0, s25
	v_lshl_add_u64 v[186:187], v[182:183], 0, s[34:35]
	global_load_lds_dwordx4 v[182:183], off
	s_mov_b32 m0, s26
	s_nop 0
	global_load_lds_dwordx4 v[186:187], off
	s_waitcnt vmcnt(8)
	s_waitcnt lgkmcnt(0)
	s_barrier
	s_waitcnt lgkmcnt(0)
	v_mfma_f32_16x16x32_bf16 v[60:63], v[146:149], v[178:181], 0
	v_mfma_f32_16x16x32_bf16 v[56:59], v[154:157], v[178:181], 0
	v_mfma_f32_16x16x32_bf16 v[48:51], v[146:149], v[198:201], 0
	v_mfma_f32_16x16x32_bf16 v[40:43], v[154:157], v[198:201], 0
	v_mfma_f32_16x16x32_bf16 v[32:35], v[146:149], v[206:209], 0
	v_mfma_f32_16x16x32_bf16 v[24:27], v[154:157], v[206:209], 0
	v_mfma_f32_16x16x32_bf16 v[16:19], v[146:149], v[214:217], 0
	v_mfma_f32_16x16x32_bf16 v[8:11], v[154:157], v[214:217], 0
	v_mfma_f32_16x16x32_bf16 v[60:63], v[150:153], v[194:197], v[60:63]
	v_mfma_f32_16x16x32_bf16 v[56:59], v[158:161], v[194:197], v[56:59]
	v_mfma_f32_16x16x32_bf16 v[48:51], v[150:153], v[202:205], v[48:51]
	v_mfma_f32_16x16x32_bf16 v[40:43], v[158:161], v[202:205], v[40:43]
	v_mfma_f32_16x16x32_bf16 v[32:35], v[150:153], v[210:213], v[32:35]
	v_mfma_f32_16x16x32_bf16 v[24:27], v[158:161], v[210:213], v[24:27]
	v_mfma_f32_16x16x32_bf16 v[16:19], v[150:153], v[218:221], v[16:19]
	v_mfma_f32_16x16x32_bf16 v[8:11], v[158:161], v[218:221], v[8:11]
	v_mfma_f32_16x16x32_bf16 v[52:55], v[162:165], v[178:181], 0
	v_mfma_f32_16x16x32_bf16 v[44:47], v[170:173], v[178:181], 0
	v_mfma_f32_16x16x32_bf16 v[36:39], v[162:165], v[198:201], 0
	v_mfma_f32_16x16x32_bf16 v[28:31], v[170:173], v[198:201], 0
	v_mfma_f32_16x16x32_bf16 v[20:23], v[162:165], v[206:209], 0
	v_mfma_f32_16x16x32_bf16 v[12:15], v[170:173], v[206:209], 0
	v_mfma_f32_16x16x32_bf16 v[4:7], v[162:165], v[214:217], 0
	v_mfma_f32_16x16x32_bf16 v[0:3], v[170:173], v[214:217], 0
	v_mfma_f32_16x16x32_bf16 v[52:55], v[166:169], v[194:197], v[52:55]
	v_mfma_f32_16x16x32_bf16 v[44:47], v[174:177], v[194:197], v[44:47]
	v_mfma_f32_16x16x32_bf16 v[36:39], v[166:169], v[202:205], v[36:39]
	v_mfma_f32_16x16x32_bf16 v[28:31], v[174:177], v[202:205], v[28:31]
	v_mfma_f32_16x16x32_bf16 v[20:23], v[166:169], v[210:213], v[20:23]
	v_mfma_f32_16x16x32_bf16 v[12:15], v[174:177], v[210:213], v[12:15]
	v_mfma_f32_16x16x32_bf16 v[4:7], v[166:169], v[218:221], v[4:7]
	v_mfma_f32_16x16x32_bf16 v[0:3], v[174:177], v[218:221], v[0:3]
	s_barrier
	s_add_i32 s14, 0, 0x18000
	v_add_u32_e32 v137, s14, v141
	s_add_i32 s15, 0, 0x1c000
	ds_read_b128 v[146:149], v137
	ds_read_b128 v[150:153], v137 offset:1024
	ds_read_b128 v[154:157], v137 offset:2048
	ds_read_b128 v[158:161], v137 offset:3072
	v_add_u32_e32 v137, s15, v141
	ds_read_b128 v[162:165], v137
	ds_read_b128 v[166:169], v137 offset:1024
	ds_read_b128 v[170:173], v137 offset:2048
	ds_read_b128 v[174:177], v137 offset:3072
	s_mov_b32 m0, s27
	v_lshl_add_u64 v[186:187], v[182:183], 0, s[92:93]
	ds_read_b128 v[178:181], v145 offset:32768
	ds_read_b128 v[194:197], v145 offset:33792
	ds_read_b128 v[198:201], v145 offset:34816
	ds_read_b128 v[202:205], v145 offset:35840
	ds_read_b128 v[206:209], v145 offset:36864
	ds_read_b128 v[210:213], v145 offset:37888
	ds_read_b128 v[214:217], v145 offset:38912
	ds_read_b128 v[218:221], v145 offset:39936
	global_load_lds_dwordx4 v[186:187], off
	v_lshl_add_u64 v[186:187], v[182:183], 0, s[52:53]
	s_mov_b32 m0, s28
	s_nop 0
	global_load_lds_dwordx4 v[186:187], off
	s_waitcnt vmcnt(8)
	s_waitcnt lgkmcnt(0)
	s_barrier
	s_waitcnt lgkmcnt(0)
	v_mfma_f32_16x16x32_bf16 v[124:127], v[146:149], v[178:181], v[124:127]
	v_mfma_f32_16x16x32_bf16 v[120:123], v[154:157], v[178:181], v[120:123]
	v_mfma_f32_16x16x32_bf16 v[112:115], v[146:149], v[198:201], v[112:115]
	v_mfma_f32_16x16x32_bf16 v[104:107], v[154:157], v[198:201], v[104:107]
	v_mfma_f32_16x16x32_bf16 v[96:99], v[146:149], v[206:209], v[96:99]
	v_mfma_f32_16x16x32_bf16 v[88:91], v[154:157], v[206:209], v[88:91]
	v_mfma_f32_16x16x32_bf16 v[80:83], v[146:149], v[214:217], v[80:83]
	v_mfma_f32_16x16x32_bf16 v[72:75], v[154:157], v[214:217], v[72:75]
	v_mfma_f32_16x16x32_bf16 v[124:127], v[150:153], v[194:197], v[124:127]
	v_mfma_f32_16x16x32_bf16 v[120:123], v[158:161], v[194:197], v[120:123]
	v_mfma_f32_16x16x32_bf16 v[112:115], v[150:153], v[202:205], v[112:115]
	v_mfma_f32_16x16x32_bf16 v[104:107], v[158:161], v[202:205], v[104:107]
	v_mfma_f32_16x16x32_bf16 v[96:99], v[150:153], v[210:213], v[96:99]
	v_mfma_f32_16x16x32_bf16 v[88:91], v[158:161], v[210:213], v[88:91]
	v_mfma_f32_16x16x32_bf16 v[80:83], v[150:153], v[218:221], v[80:83]
	v_mfma_f32_16x16x32_bf16 v[72:75], v[158:161], v[218:221], v[72:75]
	v_mfma_f32_16x16x32_bf16 v[116:119], v[162:165], v[178:181], v[116:119]
	v_mfma_f32_16x16x32_bf16 v[108:111], v[170:173], v[178:181], v[108:111]
	v_mfma_f32_16x16x32_bf16 v[100:103], v[162:165], v[198:201], v[100:103]
	v_mfma_f32_16x16x32_bf16 v[92:95], v[170:173], v[198:201], v[92:95]
	v_mfma_f32_16x16x32_bf16 v[84:87], v[162:165], v[206:209], v[84:87]
	v_mfma_f32_16x16x32_bf16 v[76:79], v[170:173], v[206:209], v[76:79]
	v_mfma_f32_16x16x32_bf16 v[68:71], v[162:165], v[214:217], v[68:71]
	v_mfma_f32_16x16x32_bf16 v[64:67], v[170:173], v[214:217], v[64:67]
	v_mfma_f32_16x16x32_bf16 v[116:119], v[166:169], v[194:197], v[116:119]
	v_mfma_f32_16x16x32_bf16 v[108:111], v[174:177], v[194:197], v[108:111]
	v_mfma_f32_16x16x32_bf16 v[100:103], v[166:169], v[202:205], v[100:103]
	v_mfma_f32_16x16x32_bf16 v[92:95], v[174:177], v[202:205], v[92:95]
	v_mfma_f32_16x16x32_bf16 v[84:87], v[166:169], v[210:213], v[84:87]
	v_mfma_f32_16x16x32_bf16 v[76:79], v[174:177], v[210:213], v[76:79]
	v_mfma_f32_16x16x32_bf16 v[68:71], v[166:169], v[218:221], v[68:71]
	v_mfma_f32_16x16x32_bf16 v[64:67], v[174:177], v[218:221], v[64:67]
	s_barrier
	s_add_i32 s14, s14, s23
	v_lshl_add_u64 v[186:187], v[138:139], 0, s[56:57]
	s_mov_b32 m0, s14
	ds_read_b128 v[178:181], v145 offset:49152
	ds_read_b128 v[194:197], v145 offset:50176
	ds_read_b128 v[198:201], v145 offset:51200
	ds_read_b128 v[202:205], v145 offset:52224
	ds_read_b128 v[206:209], v145 offset:53248
	ds_read_b128 v[210:213], v145 offset:54272
	ds_read_b128 v[214:217], v145 offset:55296
	ds_read_b128 v[218:221], v145 offset:56320
	global_load_lds_dwordx4 v[186:187], off
	v_lshl_add_u64 v[186:187], v[138:139], 0, s[96:97]
	s_add_i32 m0, s14, 0x2000
	s_add_i32 s14, s15, s23
	global_load_lds_dwordx4 v[186:187], off
	v_lshl_add_u64 v[186:187], v[138:139], 0, s[88:89]
	s_mov_b32 m0, s14
	v_lshl_add_u64 v[138:139], v[138:139], 0, s[68:69]
	global_load_lds_dwordx4 v[186:187], off
	s_add_i32 m0, s14, 0x2000
	s_nop 0
	global_load_lds_dwordx4 v[138:139], off
	v_lshl_add_u64 v[138:139], v[182:183], 0, s[56:57]
	s_mov_b32 m0, s29
	s_nop 0
	global_load_lds_dwordx4 v[138:139], off
	v_lshl_add_u64 v[138:139], v[182:183], 0, s[96:97]
	s_mov_b32 m0, s30
	s_nop 0
	global_load_lds_dwordx4 v[138:139], off
	s_waitcnt vmcnt(8)
	s_waitcnt lgkmcnt(0)
	s_barrier
	s_waitcnt lgkmcnt(0)
	v_mfma_f32_16x16x32_bf16 v[60:63], v[146:149], v[178:181], v[60:63]
	v_mfma_f32_16x16x32_bf16 v[56:59], v[154:157], v[178:181], v[56:59]
	v_mfma_f32_16x16x32_bf16 v[48:51], v[146:149], v[198:201], v[48:51]
	v_mfma_f32_16x16x32_bf16 v[40:43], v[154:157], v[198:201], v[40:43]
	v_mfma_f32_16x16x32_bf16 v[32:35], v[146:149], v[206:209], v[32:35]
	v_mfma_f32_16x16x32_bf16 v[24:27], v[154:157], v[206:209], v[24:27]
	v_mfma_f32_16x16x32_bf16 v[16:19], v[146:149], v[214:217], v[16:19]
	v_mfma_f32_16x16x32_bf16 v[8:11], v[154:157], v[214:217], v[8:11]
	v_mfma_f32_16x16x32_bf16 v[60:63], v[150:153], v[194:197], v[60:63]
	v_mfma_f32_16x16x32_bf16 v[56:59], v[158:161], v[194:197], v[56:59]
	v_mfma_f32_16x16x32_bf16 v[48:51], v[150:153], v[202:205], v[48:51]
	v_mfma_f32_16x16x32_bf16 v[40:43], v[158:161], v[202:205], v[40:43]
	v_mfma_f32_16x16x32_bf16 v[32:35], v[150:153], v[210:213], v[32:35]
	v_mfma_f32_16x16x32_bf16 v[24:27], v[158:161], v[210:213], v[24:27]
	v_mfma_f32_16x16x32_bf16 v[16:19], v[150:153], v[218:221], v[16:19]
	v_mfma_f32_16x16x32_bf16 v[8:11], v[158:161], v[218:221], v[8:11]
	v_mfma_f32_16x16x32_bf16 v[52:55], v[162:165], v[178:181], v[52:55]
	v_mfma_f32_16x16x32_bf16 v[44:47], v[170:173], v[178:181], v[44:47]
	v_mfma_f32_16x16x32_bf16 v[36:39], v[162:165], v[198:201], v[36:39]
	v_mfma_f32_16x16x32_bf16 v[28:31], v[170:173], v[198:201], v[28:31]
	v_mfma_f32_16x16x32_bf16 v[20:23], v[162:165], v[206:209], v[20:23]
	v_mfma_f32_16x16x32_bf16 v[12:15], v[170:173], v[206:209], v[12:15]
	v_mfma_f32_16x16x32_bf16 v[4:7], v[162:165], v[214:217], v[4:7]
	v_mfma_f32_16x16x32_bf16 v[0:3], v[170:173], v[214:217], v[0:3]
	v_mfma_f32_16x16x32_bf16 v[52:55], v[166:169], v[194:197], v[52:55]
	v_mfma_f32_16x16x32_bf16 v[44:47], v[174:177], v[194:197], v[44:47]
	v_mfma_f32_16x16x32_bf16 v[36:39], v[166:169], v[202:205], v[36:39]
	v_mfma_f32_16x16x32_bf16 v[28:31], v[174:177], v[202:205], v[28:31]
	v_mfma_f32_16x16x32_bf16 v[20:23], v[166:169], v[210:213], v[20:23]
	v_mfma_f32_16x16x32_bf16 v[12:15], v[174:177], v[210:213], v[12:15]
	v_mfma_f32_16x16x32_bf16 v[4:7], v[166:169], v[218:221], v[4:7]
	v_mfma_f32_16x16x32_bf16 v[0:3], v[174:177], v[218:221], v[0:3]
	s_barrier
	s_add_i32 s85, s85, 2
	s_add_u32 s60, s60, 0x100
	s_addc_u32 s61, s61, 0
	s_add_u32 s16, s16, 0x100
	s_addc_u32 s17, s17, 0
	s_cmp_gt_u32 s85, 13
.LBB0_229:
	s_add_u32 s14, s60, 0xfffc0080
	s_addc_u32 s15, s61, -1
	s_add_i32 s18, 0, 0x10000
	s_cmp_eq_u32 s85, 12
	s_cselect_b32 s15, s22, s15
	s_cselect_b32 s14, s45, s14
	v_add_u32_e32 v137, s18, v141
	s_cselect_b32 vcc_hi, s43, s17
	s_cselect_b32 vcc_lo, s84, s16
	s_add_i32 s21, 0, 0x14000
	ds_read_b128 v[146:149], v137
	ds_read_b128 v[150:153], v137 offset:1024
	ds_read_b128 v[154:157], v137 offset:2048
	ds_read_b128 v[158:161], v137 offset:3072
	v_add_u32_e32 v137, s21, v141
	ds_read_b128 v[162:165], v137
	ds_read_b128 v[166:169], v137 offset:1024
	ds_read_b128 v[170:173], v137 offset:2048
	ds_read_b128 v[174:177], v137 offset:3072
	v_lshl_add_u64 v[138:139], s[60:61], 0, v[184:185]
	s_add_i32 m0, s25, 0xc000
	ds_read_b128 v[178:181], v145
	ds_read_b128 v[194:197], v145 offset:1024
	ds_read_b128 v[198:201], v145 offset:2048
	ds_read_b128 v[202:205], v145 offset:3072
	ds_read_b128 v[206:209], v145 offset:4096
	ds_read_b128 v[210:213], v145 offset:5120
	ds_read_b128 v[214:217], v145 offset:6144
	ds_read_b128 v[218:221], v145 offset:7168
	global_load_lds_dwordx4 v[138:139], off
	v_lshl_add_u64 v[138:139], v[138:139], 0, s[34:35]
	s_add_i32 m0, s25, 0xe000
	s_nop 0
	global_load_lds_dwordx4 v[138:139], off
	s_waitcnt vmcnt(8)
	s_waitcnt lgkmcnt(0)
	s_barrier
	s_waitcnt lgkmcnt(0)
	v_mfma_f32_16x16x32_bf16 v[124:127], v[146:149], v[178:181], v[124:127]
	v_mfma_f32_16x16x32_bf16 v[120:123], v[154:157], v[178:181], v[120:123]
	v_mfma_f32_16x16x32_bf16 v[112:115], v[146:149], v[198:201], v[112:115]
	v_mfma_f32_16x16x32_bf16 v[104:107], v[154:157], v[198:201], v[104:107]
	v_mfma_f32_16x16x32_bf16 v[96:99], v[146:149], v[206:209], v[96:99]
	v_mfma_f32_16x16x32_bf16 v[88:91], v[154:157], v[206:209], v[88:91]
	v_mfma_f32_16x16x32_bf16 v[80:83], v[146:149], v[214:217], v[80:83]
	v_mfma_f32_16x16x32_bf16 v[72:75], v[154:157], v[214:217], v[72:75]
	v_mfma_f32_16x16x32_bf16 v[124:127], v[150:153], v[194:197], v[124:127]
	v_mfma_f32_16x16x32_bf16 v[120:123], v[158:161], v[194:197], v[120:123]
	v_mfma_f32_16x16x32_bf16 v[112:115], v[150:153], v[202:205], v[112:115]
	v_mfma_f32_16x16x32_bf16 v[104:107], v[158:161], v[202:205], v[104:107]
	v_mfma_f32_16x16x32_bf16 v[96:99], v[150:153], v[210:213], v[96:99]
	v_mfma_f32_16x16x32_bf16 v[88:91], v[158:161], v[210:213], v[88:91]
	v_mfma_f32_16x16x32_bf16 v[80:83], v[150:153], v[218:221], v[80:83]
	v_mfma_f32_16x16x32_bf16 v[72:75], v[158:161], v[218:221], v[72:75]
	v_mfma_f32_16x16x32_bf16 v[116:119], v[162:165], v[178:181], v[116:119]
	v_mfma_f32_16x16x32_bf16 v[108:111], v[170:173], v[178:181], v[108:111]
	v_mfma_f32_16x16x32_bf16 v[100:103], v[162:165], v[198:201], v[100:103]
	v_mfma_f32_16x16x32_bf16 v[92:95], v[170:173], v[198:201], v[92:95]
	v_mfma_f32_16x16x32_bf16 v[84:87], v[162:165], v[206:209], v[84:87]
	v_mfma_f32_16x16x32_bf16 v[76:79], v[170:173], v[206:209], v[76:79]
	v_mfma_f32_16x16x32_bf16 v[68:71], v[162:165], v[214:217], v[68:71]
	v_mfma_f32_16x16x32_bf16 v[64:67], v[170:173], v[214:217], v[64:67]
	v_mfma_f32_16x16x32_bf16 v[116:119], v[166:169], v[194:197], v[116:119]
	v_mfma_f32_16x16x32_bf16 v[108:111], v[174:177], v[194:197], v[108:111]
	v_mfma_f32_16x16x32_bf16 v[100:103], v[166:169], v[202:205], v[100:103]
	v_mfma_f32_16x16x32_bf16 v[92:95], v[174:177], v[202:205], v[92:95]
	v_mfma_f32_16x16x32_bf16 v[84:87], v[166:169], v[210:213], v[84:87]
	v_mfma_f32_16x16x32_bf16 v[76:79], v[174:177], v[210:213], v[76:79]
	v_mfma_f32_16x16x32_bf16 v[68:71], v[166:169], v[218:221], v[68:71]
	v_mfma_f32_16x16x32_bf16 v[64:67], v[174:177], v[218:221], v[64:67]
	s_barrier
	s_add_i32 s18, s18, s23
	v_lshl_add_u64 v[138:139], vcc, 0, v[128:129]
	s_mov_b32 m0, s18
	ds_read_b128 v[178:181], v145 offset:16384
	ds_read_b128 v[194:197], v145 offset:17408
	ds_read_b128 v[198:201], v145 offset:18432
	ds_read_b128 v[202:205], v145 offset:19456
	ds_read_b128 v[206:209], v145 offset:20480
	ds_read_b128 v[210:213], v145 offset:21504
	ds_read_b128 v[214:217], v145 offset:22528
	ds_read_b128 v[218:221], v145 offset:23552
	global_load_lds_dwordx4 v[138:139], off
	v_lshl_add_u64 v[182:183], v[138:139], 0, s[34:35]
	s_add_i32 m0, s18, 0x2000
	s_add_i32 s18, s21, s23
	global_load_lds_dwordx4 v[182:183], off
	v_lshl_add_u64 v[182:183], v[138:139], 0, s[92:93]
	s_mov_b32 m0, s18
	s_nop 0
	global_load_lds_dwordx4 v[182:183], off
	v_lshl_add_u64 v[182:183], v[138:139], 0, s[52:53]
	s_add_i32 m0, s18, 0x2000
	s_nop 0
	global_load_lds_dwordx4 v[182:183], off
	v_lshl_add_u64 v[182:183], s[14:15], 0, v[130:131]
	s_mov_b32 m0, s25
	v_lshl_add_u64 v[186:187], v[182:183], 0, s[34:35]
	global_load_lds_dwordx4 v[182:183], off
	s_mov_b32 m0, s26
	s_nop 0
	global_load_lds_dwordx4 v[186:187], off
	s_waitcnt vmcnt(8)
	s_waitcnt lgkmcnt(0)
	s_barrier
	s_waitcnt lgkmcnt(0)
	v_mfma_f32_16x16x32_bf16 v[60:63], v[146:149], v[178:181], v[60:63]
	v_mfma_f32_16x16x32_bf16 v[56:59], v[154:157], v[178:181], v[56:59]
	v_mfma_f32_16x16x32_bf16 v[48:51], v[146:149], v[198:201], v[48:51]
	v_mfma_f32_16x16x32_bf16 v[40:43], v[154:157], v[198:201], v[40:43]
	v_mfma_f32_16x16x32_bf16 v[32:35], v[146:149], v[206:209], v[32:35]
	v_mfma_f32_16x16x32_bf16 v[24:27], v[154:157], v[206:209], v[24:27]
	v_mfma_f32_16x16x32_bf16 v[16:19], v[146:149], v[214:217], v[16:19]
	v_mfma_f32_16x16x32_bf16 v[8:11], v[154:157], v[214:217], v[8:11]
	v_mfma_f32_16x16x32_bf16 v[60:63], v[150:153], v[194:197], v[60:63]
	v_mfma_f32_16x16x32_bf16 v[56:59], v[158:161], v[194:197], v[56:59]
	v_mfma_f32_16x16x32_bf16 v[48:51], v[150:153], v[202:205], v[48:51]
	v_mfma_f32_16x16x32_bf16 v[40:43], v[158:161], v[202:205], v[40:43]
	v_mfma_f32_16x16x32_bf16 v[32:35], v[150:153], v[210:213], v[32:35]
	v_mfma_f32_16x16x32_bf16 v[24:27], v[158:161], v[210:213], v[24:27]
	v_mfma_f32_16x16x32_bf16 v[16:19], v[150:153], v[218:221], v[16:19]
	v_mfma_f32_16x16x32_bf16 v[8:11], v[158:161], v[218:221], v[8:11]
	v_mfma_f32_16x16x32_bf16 v[52:55], v[162:165], v[178:181], v[52:55]
	v_mfma_f32_16x16x32_bf16 v[44:47], v[170:173], v[178:181], v[44:47]
	v_mfma_f32_16x16x32_bf16 v[36:39], v[162:165], v[198:201], v[36:39]
	v_mfma_f32_16x16x32_bf16 v[28:31], v[170:173], v[198:201], v[28:31]
	v_mfma_f32_16x16x32_bf16 v[20:23], v[162:165], v[206:209], v[20:23]
	v_mfma_f32_16x16x32_bf16 v[12:15], v[170:173], v[206:209], v[12:15]
	v_mfma_f32_16x16x32_bf16 v[4:7], v[162:165], v[214:217], v[4:7]
	v_mfma_f32_16x16x32_bf16 v[0:3], v[170:173], v[214:217], v[0:3]
	v_mfma_f32_16x16x32_bf16 v[52:55], v[166:169], v[194:197], v[52:55]
	v_mfma_f32_16x16x32_bf16 v[44:47], v[174:177], v[194:197], v[44:47]
	v_mfma_f32_16x16x32_bf16 v[36:39], v[166:169], v[202:205], v[36:39]
	v_mfma_f32_16x16x32_bf16 v[28:31], v[174:177], v[202:205], v[28:31]
	v_mfma_f32_16x16x32_bf16 v[20:23], v[166:169], v[210:213], v[20:23]
	v_mfma_f32_16x16x32_bf16 v[12:15], v[174:177], v[210:213], v[12:15]
	v_mfma_f32_16x16x32_bf16 v[4:7], v[166:169], v[218:221], v[4:7]
	v_mfma_f32_16x16x32_bf16 v[0:3], v[174:177], v[218:221], v[0:3]
	s_barrier
	s_add_i32 s14, 0, 0x18000
	v_add_u32_e32 v137, s14, v141
	s_add_i32 s15, 0, 0x1c000
	ds_read_b128 v[146:149], v137
	ds_read_b128 v[150:153], v137 offset:1024
	ds_read_b128 v[154:157], v137 offset:2048
	ds_read_b128 v[158:161], v137 offset:3072
	v_add_u32_e32 v137, s15, v141
	ds_read_b128 v[162:165], v137
	ds_read_b128 v[166:169], v137 offset:1024
	ds_read_b128 v[170:173], v137 offset:2048
	ds_read_b128 v[174:177], v137 offset:3072
	s_mov_b32 m0, s27
	v_lshl_add_u64 v[186:187], v[182:183], 0, s[92:93]
	ds_read_b128 v[178:181], v145 offset:32768
	ds_read_b128 v[194:197], v145 offset:33792
	ds_read_b128 v[198:201], v145 offset:34816
	ds_read_b128 v[202:205], v145 offset:35840
	ds_read_b128 v[206:209], v145 offset:36864
	ds_read_b128 v[210:213], v145 offset:37888
	ds_read_b128 v[214:217], v145 offset:38912
	ds_read_b128 v[218:221], v145 offset:39936
	global_load_lds_dwordx4 v[186:187], off
	v_lshl_add_u64 v[186:187], v[182:183], 0, s[52:53]
	s_mov_b32 m0, s28
	s_nop 0
	global_load_lds_dwordx4 v[186:187], off
	s_waitcnt vmcnt(8)
	s_waitcnt lgkmcnt(0)
	s_barrier
	s_waitcnt lgkmcnt(0)
	v_mfma_f32_16x16x32_bf16 v[124:127], v[146:149], v[178:181], v[124:127]
	v_mfma_f32_16x16x32_bf16 v[120:123], v[154:157], v[178:181], v[120:123]
	v_mfma_f32_16x16x32_bf16 v[112:115], v[146:149], v[198:201], v[112:115]
	v_mfma_f32_16x16x32_bf16 v[104:107], v[154:157], v[198:201], v[104:107]
	v_mfma_f32_16x16x32_bf16 v[96:99], v[146:149], v[206:209], v[96:99]
	v_mfma_f32_16x16x32_bf16 v[88:91], v[154:157], v[206:209], v[88:91]
	v_mfma_f32_16x16x32_bf16 v[80:83], v[146:149], v[214:217], v[80:83]
	v_mfma_f32_16x16x32_bf16 v[72:75], v[154:157], v[214:217], v[72:75]
	v_mfma_f32_16x16x32_bf16 v[124:127], v[150:153], v[194:197], v[124:127]
	v_mfma_f32_16x16x32_bf16 v[120:123], v[158:161], v[194:197], v[120:123]
	v_mfma_f32_16x16x32_bf16 v[112:115], v[150:153], v[202:205], v[112:115]
	v_mfma_f32_16x16x32_bf16 v[104:107], v[158:161], v[202:205], v[104:107]
	v_mfma_f32_16x16x32_bf16 v[96:99], v[150:153], v[210:213], v[96:99]
	v_mfma_f32_16x16x32_bf16 v[88:91], v[158:161], v[210:213], v[88:91]
	v_mfma_f32_16x16x32_bf16 v[80:83], v[150:153], v[218:221], v[80:83]
	v_mfma_f32_16x16x32_bf16 v[72:75], v[158:161], v[218:221], v[72:75]
	v_mfma_f32_16x16x32_bf16 v[116:119], v[162:165], v[178:181], v[116:119]
	v_mfma_f32_16x16x32_bf16 v[108:111], v[170:173], v[178:181], v[108:111]
	v_mfma_f32_16x16x32_bf16 v[100:103], v[162:165], v[198:201], v[100:103]
	v_mfma_f32_16x16x32_bf16 v[92:95], v[170:173], v[198:201], v[92:95]
	v_mfma_f32_16x16x32_bf16 v[84:87], v[162:165], v[206:209], v[84:87]
	v_mfma_f32_16x16x32_bf16 v[76:79], v[170:173], v[206:209], v[76:79]
	v_mfma_f32_16x16x32_bf16 v[68:71], v[162:165], v[214:217], v[68:71]
	v_mfma_f32_16x16x32_bf16 v[64:67], v[170:173], v[214:217], v[64:67]
	v_mfma_f32_16x16x32_bf16 v[116:119], v[166:169], v[194:197], v[116:119]
	v_mfma_f32_16x16x32_bf16 v[108:111], v[174:177], v[194:197], v[108:111]
	v_mfma_f32_16x16x32_bf16 v[100:103], v[166:169], v[202:205], v[100:103]
	v_mfma_f32_16x16x32_bf16 v[92:95], v[174:177], v[202:205], v[92:95]
	v_mfma_f32_16x16x32_bf16 v[84:87], v[166:169], v[210:213], v[84:87]
	v_mfma_f32_16x16x32_bf16 v[76:79], v[174:177], v[210:213], v[76:79]
	v_mfma_f32_16x16x32_bf16 v[68:71], v[166:169], v[218:221], v[68:71]
	v_mfma_f32_16x16x32_bf16 v[64:67], v[174:177], v[218:221], v[64:67]
	s_barrier
	s_add_i32 s14, s14, s23
	v_lshl_add_u64 v[186:187], v[138:139], 0, s[56:57]
	s_mov_b32 m0, s14
	ds_read_b128 v[178:181], v145 offset:49152
	ds_read_b128 v[194:197], v145 offset:50176
	ds_read_b128 v[198:201], v145 offset:51200
	ds_read_b128 v[202:205], v145 offset:52224
	ds_read_b128 v[206:209], v145 offset:53248
	ds_read_b128 v[210:213], v145 offset:54272
	ds_read_b128 v[214:217], v145 offset:55296
	ds_read_b128 v[218:221], v145 offset:56320
	global_load_lds_dwordx4 v[186:187], off
	v_lshl_add_u64 v[186:187], v[138:139], 0, s[96:97]
	s_add_i32 m0, s14, 0x2000
	s_add_i32 s14, s15, s23
	global_load_lds_dwordx4 v[186:187], off
	v_lshl_add_u64 v[186:187], v[138:139], 0, s[88:89]
	s_mov_b32 m0, s14
	v_lshl_add_u64 v[138:139], v[138:139], 0, s[68:69]
	global_load_lds_dwordx4 v[186:187], off
	s_add_i32 m0, s14, 0x2000
	s_nop 0
	global_load_lds_dwordx4 v[138:139], off
	v_lshl_add_u64 v[138:139], v[182:183], 0, s[56:57]
	s_mov_b32 m0, s29
	s_nop 0
	global_load_lds_dwordx4 v[138:139], off
	v_lshl_add_u64 v[138:139], v[182:183], 0, s[96:97]
	s_mov_b32 m0, s30
	s_nop 0
	global_load_lds_dwordx4 v[138:139], off
	s_waitcnt vmcnt(8)
	s_waitcnt lgkmcnt(0)
	s_barrier
	s_waitcnt lgkmcnt(0)
	v_mfma_f32_16x16x32_bf16 v[60:63], v[146:149], v[178:181], v[60:63]
	v_mfma_f32_16x16x32_bf16 v[56:59], v[154:157], v[178:181], v[56:59]
	v_mfma_f32_16x16x32_bf16 v[48:51], v[146:149], v[198:201], v[48:51]
	v_mfma_f32_16x16x32_bf16 v[40:43], v[154:157], v[198:201], v[40:43]
	v_mfma_f32_16x16x32_bf16 v[32:35], v[146:149], v[206:209], v[32:35]
	v_mfma_f32_16x16x32_bf16 v[24:27], v[154:157], v[206:209], v[24:27]
	v_mfma_f32_16x16x32_bf16 v[16:19], v[146:149], v[214:217], v[16:19]
	v_mfma_f32_16x16x32_bf16 v[8:11], v[154:157], v[214:217], v[8:11]
	v_mfma_f32_16x16x32_bf16 v[60:63], v[150:153], v[194:197], v[60:63]
	v_mfma_f32_16x16x32_bf16 v[56:59], v[158:161], v[194:197], v[56:59]
	v_mfma_f32_16x16x32_bf16 v[48:51], v[150:153], v[202:205], v[48:51]
	v_mfma_f32_16x16x32_bf16 v[40:43], v[158:161], v[202:205], v[40:43]
	v_mfma_f32_16x16x32_bf16 v[32:35], v[150:153], v[210:213], v[32:35]
	v_mfma_f32_16x16x32_bf16 v[24:27], v[158:161], v[210:213], v[24:27]
	v_mfma_f32_16x16x32_bf16 v[16:19], v[150:153], v[218:221], v[16:19]
	v_mfma_f32_16x16x32_bf16 v[8:11], v[158:161], v[218:221], v[8:11]
	v_mfma_f32_16x16x32_bf16 v[52:55], v[162:165], v[178:181], v[52:55]
	v_mfma_f32_16x16x32_bf16 v[44:47], v[170:173], v[178:181], v[44:47]
	v_mfma_f32_16x16x32_bf16 v[36:39], v[162:165], v[198:201], v[36:39]
	v_mfma_f32_16x16x32_bf16 v[28:31], v[170:173], v[198:201], v[28:31]
	v_mfma_f32_16x16x32_bf16 v[20:23], v[162:165], v[206:209], v[20:23]
	v_mfma_f32_16x16x32_bf16 v[12:15], v[170:173], v[206:209], v[12:15]
	v_mfma_f32_16x16x32_bf16 v[4:7], v[162:165], v[214:217], v[4:7]
	v_mfma_f32_16x16x32_bf16 v[0:3], v[170:173], v[214:217], v[0:3]
	v_mfma_f32_16x16x32_bf16 v[52:55], v[166:169], v[194:197], v[52:55]
	v_mfma_f32_16x16x32_bf16 v[44:47], v[174:177], v[194:197], v[44:47]
	v_mfma_f32_16x16x32_bf16 v[36:39], v[166:169], v[202:205], v[36:39]
	v_mfma_f32_16x16x32_bf16 v[28:31], v[174:177], v[202:205], v[28:31]
	v_mfma_f32_16x16x32_bf16 v[20:23], v[166:169], v[210:213], v[20:23]
	v_mfma_f32_16x16x32_bf16 v[12:15], v[174:177], v[210:213], v[12:15]
	v_mfma_f32_16x16x32_bf16 v[4:7], v[166:169], v[218:221], v[4:7]
	v_mfma_f32_16x16x32_bf16 v[0:3], v[174:177], v[218:221], v[0:3]
	s_barrier
	s_add_i32 s85, s85, 2
	s_add_u32 s60, s60, 0x100
	s_addc_u32 s61, s61, 0
	s_add_u32 s16, s16, 0x100
	s_addc_u32 s17, s17, 0
	s_cmp_gt_u32 s85, 13
	s_cbranch_scc0 .LBB0_229
	s_and_b64 vcc, exec, s[40:41]
	s_cbranch_vccz .LBB0_232
	s_barrier

.LBB0_248:
	s_ashr_i32 s45, s44, 31
	s_lshl_b64 s[46:47], s[44:45], 19
	s_add_u32 s46, s64, s46
	s_addc_u32 s47, s65, s47
	s_and_b64 s[48:49], s[38:39], exec
	s_cselect_b32 s22, s47, s15
	s_cselect_b32 s45, s46, s14
	s_ashr_i32 s43, s42, 31
	s_lshl_b64 s[48:49], s[42:43], 19
	s_add_u32 s48, s6, s48
	s_addc_u32 s49, s19, s49
	s_and_b64 s[60:61], s[38:39], exec
	s_cselect_b32 s43, s49, s17
	s_cselect_b32 s84, s48, s16
	s_add_u32 s60, s14, 0x40080
	s_addc_u32 s61, s15, 0
	s_add_u32 s16, s16, 0x100
	s_addc_u32 s17, s17, 0
	s_mov_b32 s85, -2
	s_add_u32 s14, s60, 0xfffc0080
	s_addc_u32 s15, s61, -1
	s_add_i32 s18, 0, 0x10000
	s_cmp_eq_u32 s85, 12
	s_cselect_b32 s15, s22, s15
	s_cselect_b32 s14, s45, s14
	s_waitcnt lgkmcnt(0)
	v_add_u32_e32 v137, s18, v149
	s_cselect_b32 vcc_hi, s43, s17
	s_cselect_b32 vcc_lo, s84, s16
	s_add_i32 s21, 0, 0x14000
	ds_read_b128 v[138:141], v137
	ds_read_b128 v[142:145], v137 offset:1024
	ds_read_b128 v[154:157], v137 offset:2048
	ds_read_b128 v[158:161], v137 offset:3072
	v_add_u32_e32 v137, s21, v149
	ds_read_b128 v[162:165], v137
	ds_read_b128 v[166:169], v137 offset:1024
	ds_read_b128 v[170:173], v137 offset:2048
	ds_read_b128 v[174:177], v137 offset:3072
	v_lshl_add_u64 v[146:147], s[60:61], 0, v[134:135]
	s_add_i32 m0, s25, 0xc000
	ds_read_b128 v[178:181], v153
	ds_read_b128 v[194:197], v153 offset:1024
	ds_read_b128 v[198:201], v153 offset:2048
	ds_read_b128 v[202:205], v153 offset:3072
	ds_read_b128 v[206:209], v153 offset:4096
	ds_read_b128 v[210:213], v153 offset:5120
	ds_read_b128 v[214:217], v153 offset:6144
	ds_read_b128 v[218:221], v153 offset:7168
	global_load_lds_dwordx4 v[146:147], off
	v_lshl_add_u64 v[146:147], v[146:147], 0, s[34:35]
	s_add_i32 m0, s25, 0xe000
	s_nop 0
	global_load_lds_dwordx4 v[146:147], off
	s_waitcnt vmcnt(8)
	s_waitcnt lgkmcnt(0)
	s_barrier
	s_waitcnt lgkmcnt(0)
	v_mfma_f32_16x16x32_bf16 v[124:127], v[138:141], v[178:181], 0
	v_mfma_f32_16x16x32_bf16 v[120:123], v[154:157], v[178:181], 0
	v_mfma_f32_16x16x32_bf16 v[108:111], v[138:141], v[198:201], 0
	v_mfma_f32_16x16x32_bf16 v[104:107], v[154:157], v[198:201], 0
	v_mfma_f32_16x16x32_bf16 v[96:99], v[138:141], v[206:209], 0
	v_mfma_f32_16x16x32_bf16 v[88:91], v[154:157], v[206:209], 0
	v_mfma_f32_16x16x32_bf16 v[80:83], v[138:141], v[214:217], 0
	v_mfma_f32_16x16x32_bf16 v[72:75], v[154:157], v[214:217], 0
	v_mfma_f32_16x16x32_bf16 v[124:127], v[142:145], v[194:197], v[124:127]
	v_mfma_f32_16x16x32_bf16 v[120:123], v[158:161], v[194:197], v[120:123]
	v_mfma_f32_16x16x32_bf16 v[108:111], v[142:145], v[202:205], v[108:111]
	v_mfma_f32_16x16x32_bf16 v[104:107], v[158:161], v[202:205], v[104:107]
	v_mfma_f32_16x16x32_bf16 v[96:99], v[142:145], v[210:213], v[96:99]
	v_mfma_f32_16x16x32_bf16 v[88:91], v[158:161], v[210:213], v[88:91]
	v_mfma_f32_16x16x32_bf16 v[80:83], v[142:145], v[218:221], v[80:83]
	v_mfma_f32_16x16x32_bf16 v[72:75], v[158:161], v[218:221], v[72:75]
	v_mfma_f32_16x16x32_bf16 v[116:119], v[162:165], v[178:181], 0
	v_mfma_f32_16x16x32_bf16 v[112:115], v[170:173], v[178:181], 0
	v_mfma_f32_16x16x32_bf16 v[100:103], v[162:165], v[198:201], 0
	v_mfma_f32_16x16x32_bf16 v[92:95], v[170:173], v[198:201], 0
	v_mfma_f32_16x16x32_bf16 v[84:87], v[162:165], v[206:209], 0
	v_mfma_f32_16x16x32_bf16 v[76:79], v[170:173], v[206:209], 0
	v_mfma_f32_16x16x32_bf16 v[68:71], v[162:165], v[214:217], 0
	v_mfma_f32_16x16x32_bf16 v[64:67], v[170:173], v[214:217], 0
	v_mfma_f32_16x16x32_bf16 v[116:119], v[166:169], v[194:197], v[116:119]
	v_mfma_f32_16x16x32_bf16 v[112:115], v[174:177], v[194:197], v[112:115]
	v_mfma_f32_16x16x32_bf16 v[100:103], v[166:169], v[202:205], v[100:103]
	v_mfma_f32_16x16x32_bf16 v[92:95], v[174:177], v[202:205], v[92:95]
	v_mfma_f32_16x16x32_bf16 v[84:87], v[166:169], v[210:213], v[84:87]
	v_mfma_f32_16x16x32_bf16 v[76:79], v[174:177], v[210:213], v[76:79]
	v_mfma_f32_16x16x32_bf16 v[68:71], v[166:169], v[218:221], v[68:71]
	v_mfma_f32_16x16x32_bf16 v[64:67], v[174:177], v[218:221], v[64:67]
	s_barrier
	s_add_i32 s18, s18, s23
	v_lshl_add_u64 v[146:147], vcc, 0, v[128:129]
	s_mov_b32 m0, s18
	ds_read_b128 v[178:181], v153 offset:16384
	ds_read_b128 v[194:197], v153 offset:17408
	ds_read_b128 v[198:201], v153 offset:18432
	ds_read_b128 v[202:205], v153 offset:19456
	ds_read_b128 v[206:209], v153 offset:20480
	ds_read_b128 v[210:213], v153 offset:21504
	ds_read_b128 v[214:217], v153 offset:22528
	ds_read_b128 v[218:221], v153 offset:23552
	global_load_lds_dwordx4 v[146:147], off
	v_lshl_add_u64 v[182:183], v[146:147], 0, s[34:35]
	s_add_i32 m0, s18, 0x2000
	s_add_i32 s18, s21, s23
	global_load_lds_dwordx4 v[182:183], off
	v_lshl_add_u64 v[182:183], v[146:147], 0, s[92:93]
	s_mov_b32 m0, s18
	s_nop 0
	global_load_lds_dwordx4 v[182:183], off
	v_lshl_add_u64 v[182:183], v[146:147], 0, s[52:53]
	s_add_i32 m0, s18, 0x2000
	s_nop 0
	global_load_lds_dwordx4 v[182:183], off
	v_lshl_add_u64 v[182:183], s[14:15], 0, v[130:131]
	s_mov_b32 m0, s25
	v_lshl_add_u64 v[186:187], v[182:183], 0, s[34:35]
	global_load_lds_dwordx4 v[182:183], off
	s_mov_b32 m0, s26
	s_nop 0
	global_load_lds_dwordx4 v[186:187], off
	s_waitcnt vmcnt(8)
	s_waitcnt lgkmcnt(0)
	s_barrier
	s_waitcnt lgkmcnt(0)
	v_mfma_f32_16x16x32_bf16 v[60:63], v[138:141], v[178:181], 0
	v_mfma_f32_16x16x32_bf16 v[56:59], v[154:157], v[178:181], 0
	v_mfma_f32_16x16x32_bf16 v[48:51], v[138:141], v[198:201], 0
	v_mfma_f32_16x16x32_bf16 v[40:43], v[154:157], v[198:201], 0
	v_mfma_f32_16x16x32_bf16 v[32:35], v[138:141], v[206:209], 0
	v_mfma_f32_16x16x32_bf16 v[24:27], v[154:157], v[206:209], 0
	v_mfma_f32_16x16x32_bf16 v[16:19], v[138:141], v[214:217], 0
	v_mfma_f32_16x16x32_bf16 v[8:11], v[154:157], v[214:217], 0
	v_mfma_f32_16x16x32_bf16 v[60:63], v[142:145], v[194:197], v[60:63]
	v_mfma_f32_16x16x32_bf16 v[56:59], v[158:161], v[194:197], v[56:59]
	v_mfma_f32_16x16x32_bf16 v[48:51], v[142:145], v[202:205], v[48:51]
	v_mfma_f32_16x16x32_bf16 v[40:43], v[158:161], v[202:205], v[40:43]
	v_mfma_f32_16x16x32_bf16 v[32:35], v[142:145], v[210:213], v[32:35]
	v_mfma_f32_16x16x32_bf16 v[24:27], v[158:161], v[210:213], v[24:27]
	v_mfma_f32_16x16x32_bf16 v[16:19], v[142:145], v[218:221], v[16:19]
	v_mfma_f32_16x16x32_bf16 v[8:11], v[158:161], v[218:221], v[8:11]
	v_mfma_f32_16x16x32_bf16 v[52:55], v[162:165], v[178:181], 0
	v_mfma_f32_16x16x32_bf16 v[44:47], v[170:173], v[178:181], 0
	v_mfma_f32_16x16x32_bf16 v[36:39], v[162:165], v[198:201], 0
	v_mfma_f32_16x16x32_bf16 v[28:31], v[170:173], v[198:201], 0
	v_mfma_f32_16x16x32_bf16 v[20:23], v[162:165], v[206:209], 0
	v_mfma_f32_16x16x32_bf16 v[12:15], v[170:173], v[206:209], 0
	v_mfma_f32_16x16x32_bf16 v[4:7], v[162:165], v[214:217], 0
	v_mfma_f32_16x16x32_bf16 v[0:3], v[170:173], v[214:217], 0
	v_mfma_f32_16x16x32_bf16 v[52:55], v[166:169], v[194:197], v[52:55]
	v_mfma_f32_16x16x32_bf16 v[44:47], v[174:177], v[194:197], v[44:47]
	v_mfma_f32_16x16x32_bf16 v[36:39], v[166:169], v[202:205], v[36:39]
	v_mfma_f32_16x16x32_bf16 v[28:31], v[174:177], v[202:205], v[28:31]
	v_mfma_f32_16x16x32_bf16 v[20:23], v[166:169], v[210:213], v[20:23]
	v_mfma_f32_16x16x32_bf16 v[12:15], v[174:177], v[210:213], v[12:15]
	v_mfma_f32_16x16x32_bf16 v[4:7], v[166:169], v[218:221], v[4:7]
	v_mfma_f32_16x16x32_bf16 v[0:3], v[174:177], v[218:221], v[0:3]
	s_barrier
	s_add_i32 s14, 0, 0x18000
	v_add_u32_e32 v137, s14, v149
	s_add_i32 s15, 0, 0x1c000
	ds_read_b128 v[138:141], v137
	ds_read_b128 v[142:145], v137 offset:1024
	ds_read_b128 v[154:157], v137 offset:2048
	ds_read_b128 v[158:161], v137 offset:3072
	v_add_u32_e32 v137, s15, v149
	ds_read_b128 v[162:165], v137
	ds_read_b128 v[166:169], v137 offset:1024
	ds_read_b128 v[170:173], v137 offset:2048
	ds_read_b128 v[174:177], v137 offset:3072
	s_mov_b32 m0, s27
	v_lshl_add_u64 v[186:187], v[182:183], 0, s[92:93]
	ds_read_b128 v[178:181], v153 offset:32768
	ds_read_b128 v[194:197], v153 offset:33792
	ds_read_b128 v[198:201], v153 offset:34816
	ds_read_b128 v[202:205], v153 offset:35840
	ds_read_b128 v[206:209], v153 offset:36864
	ds_read_b128 v[210:213], v153 offset:37888
	ds_read_b128 v[214:217], v153 offset:38912
	ds_read_b128 v[218:221], v153 offset:39936
	global_load_lds_dwordx4 v[186:187], off
	v_lshl_add_u64 v[186:187], v[182:183], 0, s[52:53]
	s_mov_b32 m0, s28
	s_nop 0
	global_load_lds_dwordx4 v[186:187], off
	s_waitcnt vmcnt(8)
	s_waitcnt lgkmcnt(0)
	s_barrier
	s_waitcnt lgkmcnt(0)
	v_mfma_f32_16x16x32_bf16 v[124:127], v[138:141], v[178:181], v[124:127]
	v_mfma_f32_16x16x32_bf16 v[120:123], v[154:157], v[178:181], v[120:123]
	v_mfma_f32_16x16x32_bf16 v[108:111], v[138:141], v[198:201], v[108:111]
	v_mfma_f32_16x16x32_bf16 v[104:107], v[154:157], v[198:201], v[104:107]
	v_mfma_f32_16x16x32_bf16 v[96:99], v[138:141], v[206:209], v[96:99]
	v_mfma_f32_16x16x32_bf16 v[88:91], v[154:157], v[206:209], v[88:91]
	v_mfma_f32_16x16x32_bf16 v[80:83], v[138:141], v[214:217], v[80:83]
	v_mfma_f32_16x16x32_bf16 v[72:75], v[154:157], v[214:217], v[72:75]
	v_mfma_f32_16x16x32_bf16 v[124:127], v[142:145], v[194:197], v[124:127]
	v_mfma_f32_16x16x32_bf16 v[120:123], v[158:161], v[194:197], v[120:123]
	v_mfma_f32_16x16x32_bf16 v[108:111], v[142:145], v[202:205], v[108:111]
	v_mfma_f32_16x16x32_bf16 v[104:107], v[158:161], v[202:205], v[104:107]
	v_mfma_f32_16x16x32_bf16 v[96:99], v[142:145], v[210:213], v[96:99]
	v_mfma_f32_16x16x32_bf16 v[88:91], v[158:161], v[210:213], v[88:91]
	v_mfma_f32_16x16x32_bf16 v[80:83], v[142:145], v[218:221], v[80:83]
	v_mfma_f32_16x16x32_bf16 v[72:75], v[158:161], v[218:221], v[72:75]
	v_mfma_f32_16x16x32_bf16 v[116:119], v[162:165], v[178:181], v[116:119]
	v_mfma_f32_16x16x32_bf16 v[112:115], v[170:173], v[178:181], v[112:115]
	v_mfma_f32_16x16x32_bf16 v[100:103], v[162:165], v[198:201], v[100:103]
	v_mfma_f32_16x16x32_bf16 v[92:95], v[170:173], v[198:201], v[92:95]
	v_mfma_f32_16x16x32_bf16 v[84:87], v[162:165], v[206:209], v[84:87]
	v_mfma_f32_16x16x32_bf16 v[76:79], v[170:173], v[206:209], v[76:79]
	v_mfma_f32_16x16x32_bf16 v[68:71], v[162:165], v[214:217], v[68:71]
	v_mfma_f32_16x16x32_bf16 v[64:67], v[170:173], v[214:217], v[64:67]
	v_mfma_f32_16x16x32_bf16 v[116:119], v[166:169], v[194:197], v[116:119]
	v_mfma_f32_16x16x32_bf16 v[112:115], v[174:177], v[194:197], v[112:115]
	v_mfma_f32_16x16x32_bf16 v[100:103], v[166:169], v[202:205], v[100:103]
	v_mfma_f32_16x16x32_bf16 v[92:95], v[174:177], v[202:205], v[92:95]
	v_mfma_f32_16x16x32_bf16 v[84:87], v[166:169], v[210:213], v[84:87]
	v_mfma_f32_16x16x32_bf16 v[76:79], v[174:177], v[210:213], v[76:79]
	v_mfma_f32_16x16x32_bf16 v[68:71], v[166:169], v[218:221], v[68:71]
	v_mfma_f32_16x16x32_bf16 v[64:67], v[174:177], v[218:221], v[64:67]
	s_barrier
	s_add_i32 s14, s14, s23
	v_lshl_add_u64 v[186:187], v[146:147], 0, s[56:57]
	s_mov_b32 m0, s14
	ds_read_b128 v[178:181], v153 offset:49152
	ds_read_b128 v[194:197], v153 offset:50176
	ds_read_b128 v[198:201], v153 offset:51200
	ds_read_b128 v[202:205], v153 offset:52224
	ds_read_b128 v[206:209], v153 offset:53248
	ds_read_b128 v[210:213], v153 offset:54272
	ds_read_b128 v[214:217], v153 offset:55296
	ds_read_b128 v[218:221], v153 offset:56320
	global_load_lds_dwordx4 v[186:187], off
	v_lshl_add_u64 v[186:187], v[146:147], 0, s[96:97]
	s_add_i32 m0, s14, 0x2000
	s_add_i32 s14, s15, s23
	global_load_lds_dwordx4 v[186:187], off
	v_lshl_add_u64 v[186:187], v[146:147], 0, s[88:89]
	s_mov_b32 m0, s14
	v_lshl_add_u64 v[146:147], v[146:147], 0, s[68:69]
	global_load_lds_dwordx4 v[186:187], off
	s_add_i32 m0, s14, 0x2000
	s_nop 0
	global_load_lds_dwordx4 v[146:147], off
	v_lshl_add_u64 v[146:147], v[182:183], 0, s[56:57]
	s_mov_b32 m0, s29
	s_nop 0
	global_load_lds_dwordx4 v[146:147], off
	v_lshl_add_u64 v[146:147], v[182:183], 0, s[96:97]
	s_mov_b32 m0, s30
	s_nop 0
	global_load_lds_dwordx4 v[146:147], off
	s_waitcnt vmcnt(8)
	s_waitcnt lgkmcnt(0)
	s_barrier
	s_waitcnt lgkmcnt(0)
	v_mfma_f32_16x16x32_bf16 v[60:63], v[138:141], v[178:181], v[60:63]
	v_mfma_f32_16x16x32_bf16 v[56:59], v[154:157], v[178:181], v[56:59]
	v_mfma_f32_16x16x32_bf16 v[48:51], v[138:141], v[198:201], v[48:51]
	v_mfma_f32_16x16x32_bf16 v[40:43], v[154:157], v[198:201], v[40:43]
	v_mfma_f32_16x16x32_bf16 v[32:35], v[138:141], v[206:209], v[32:35]
	v_mfma_f32_16x16x32_bf16 v[24:27], v[154:157], v[206:209], v[24:27]
	v_mfma_f32_16x16x32_bf16 v[16:19], v[138:141], v[214:217], v[16:19]
	v_mfma_f32_16x16x32_bf16 v[8:11], v[154:157], v[214:217], v[8:11]
	v_mfma_f32_16x16x32_bf16 v[60:63], v[142:145], v[194:197], v[60:63]
	v_mfma_f32_16x16x32_bf16 v[56:59], v[158:161], v[194:197], v[56:59]
	v_mfma_f32_16x16x32_bf16 v[48:51], v[142:145], v[202:205], v[48:51]
	v_mfma_f32_16x16x32_bf16 v[40:43], v[158:161], v[202:205], v[40:43]
	v_mfma_f32_16x16x32_bf16 v[32:35], v[142:145], v[210:213], v[32:35]
	v_mfma_f32_16x16x32_bf16 v[24:27], v[158:161], v[210:213], v[24:27]
	v_mfma_f32_16x16x32_bf16 v[16:19], v[142:145], v[218:221], v[16:19]
	v_mfma_f32_16x16x32_bf16 v[8:11], v[158:161], v[218:221], v[8:11]
	v_mfma_f32_16x16x32_bf16 v[52:55], v[162:165], v[178:181], v[52:55]
	v_mfma_f32_16x16x32_bf16 v[44:47], v[170:173], v[178:181], v[44:47]
	v_mfma_f32_16x16x32_bf16 v[36:39], v[162:165], v[198:201], v[36:39]
	v_mfma_f32_16x16x32_bf16 v[28:31], v[170:173], v[198:201], v[28:31]
	v_mfma_f32_16x16x32_bf16 v[20:23], v[162:165], v[206:209], v[20:23]
	v_mfma_f32_16x16x32_bf16 v[12:15], v[170:173], v[206:209], v[12:15]
	v_mfma_f32_16x16x32_bf16 v[4:7], v[162:165], v[214:217], v[4:7]
	v_mfma_f32_16x16x32_bf16 v[0:3], v[170:173], v[214:217], v[0:3]
	v_mfma_f32_16x16x32_bf16 v[52:55], v[166:169], v[194:197], v[52:55]
	v_mfma_f32_16x16x32_bf16 v[44:47], v[174:177], v[194:197], v[44:47]
	v_mfma_f32_16x16x32_bf16 v[36:39], v[166:169], v[202:205], v[36:39]
	v_mfma_f32_16x16x32_bf16 v[28:31], v[174:177], v[202:205], v[28:31]
	v_mfma_f32_16x16x32_bf16 v[20:23], v[166:169], v[210:213], v[20:23]
	v_mfma_f32_16x16x32_bf16 v[12:15], v[174:177], v[210:213], v[12:15]
	v_mfma_f32_16x16x32_bf16 v[4:7], v[166:169], v[218:221], v[4:7]
	v_mfma_f32_16x16x32_bf16 v[0:3], v[174:177], v[218:221], v[0:3]
	s_barrier
	s_add_i32 s85, s85, 2
	s_add_u32 s60, s60, 0x100
	s_addc_u32 s61, s61, 0
	s_add_u32 s16, s16, 0x100
	s_addc_u32 s17, s17, 0
	s_cmp_gt_u32 s85, 13
.LBB0_249:
	s_add_u32 s14, s60, 0xfffc0080
	s_addc_u32 s15, s61, -1
	s_add_i32 s18, 0, 0x10000
	s_cmp_eq_u32 s85, 12
	s_cselect_b32 s15, s22, s15
	s_cselect_b32 s14, s45, s14
	s_waitcnt lgkmcnt(0)
	v_add_u32_e32 v137, s18, v149
	s_cselect_b32 vcc_hi, s43, s17
	s_cselect_b32 vcc_lo, s84, s16
	s_add_i32 s21, 0, 0x14000
	ds_read_b128 v[138:141], v137
	ds_read_b128 v[142:145], v137 offset:1024
	ds_read_b128 v[154:157], v137 offset:2048
	ds_read_b128 v[158:161], v137 offset:3072
	v_add_u32_e32 v137, s21, v149
	ds_read_b128 v[162:165], v137
	ds_read_b128 v[166:169], v137 offset:1024
	ds_read_b128 v[170:173], v137 offset:2048
	ds_read_b128 v[174:177], v137 offset:3072
	v_lshl_add_u64 v[146:147], s[60:61], 0, v[134:135]
	s_add_i32 m0, s25, 0xc000
	ds_read_b128 v[178:181], v153
	ds_read_b128 v[194:197], v153 offset:1024
	ds_read_b128 v[198:201], v153 offset:2048
	ds_read_b128 v[202:205], v153 offset:3072
	ds_read_b128 v[206:209], v153 offset:4096
	ds_read_b128 v[210:213], v153 offset:5120
	ds_read_b128 v[214:217], v153 offset:6144
	ds_read_b128 v[218:221], v153 offset:7168
	global_load_lds_dwordx4 v[146:147], off
	v_lshl_add_u64 v[146:147], v[146:147], 0, s[34:35]
	s_add_i32 m0, s25, 0xe000
	s_nop 0
	global_load_lds_dwordx4 v[146:147], off
	s_waitcnt vmcnt(8)
	s_waitcnt lgkmcnt(0)
	s_barrier
	s_waitcnt lgkmcnt(0)
	v_mfma_f32_16x16x32_bf16 v[124:127], v[138:141], v[178:181], v[124:127]
	v_mfma_f32_16x16x32_bf16 v[120:123], v[154:157], v[178:181], v[120:123]
	v_mfma_f32_16x16x32_bf16 v[108:111], v[138:141], v[198:201], v[108:111]
	v_mfma_f32_16x16x32_bf16 v[104:107], v[154:157], v[198:201], v[104:107]
	v_mfma_f32_16x16x32_bf16 v[96:99], v[138:141], v[206:209], v[96:99]
	v_mfma_f32_16x16x32_bf16 v[88:91], v[154:157], v[206:209], v[88:91]
	v_mfma_f32_16x16x32_bf16 v[80:83], v[138:141], v[214:217], v[80:83]
	v_mfma_f32_16x16x32_bf16 v[72:75], v[154:157], v[214:217], v[72:75]
	v_mfma_f32_16x16x32_bf16 v[124:127], v[142:145], v[194:197], v[124:127]
	v_mfma_f32_16x16x32_bf16 v[120:123], v[158:161], v[194:197], v[120:123]
	v_mfma_f32_16x16x32_bf16 v[108:111], v[142:145], v[202:205], v[108:111]
	v_mfma_f32_16x16x32_bf16 v[104:107], v[158:161], v[202:205], v[104:107]
	v_mfma_f32_16x16x32_bf16 v[96:99], v[142:145], v[210:213], v[96:99]
	v_mfma_f32_16x16x32_bf16 v[88:91], v[158:161], v[210:213], v[88:91]
	v_mfma_f32_16x16x32_bf16 v[80:83], v[142:145], v[218:221], v[80:83]
	v_mfma_f32_16x16x32_bf16 v[72:75], v[158:161], v[218:221], v[72:75]
	v_mfma_f32_16x16x32_bf16 v[116:119], v[162:165], v[178:181], v[116:119]
	v_mfma_f32_16x16x32_bf16 v[112:115], v[170:173], v[178:181], v[112:115]
	v_mfma_f32_16x16x32_bf16 v[100:103], v[162:165], v[198:201], v[100:103]
	v_mfma_f32_16x16x32_bf16 v[92:95], v[170:173], v[198:201], v[92:95]
	v_mfma_f32_16x16x32_bf16 v[84:87], v[162:165], v[206:209], v[84:87]
	v_mfma_f32_16x16x32_bf16 v[76:79], v[170:173], v[206:209], v[76:79]
	v_mfma_f32_16x16x32_bf16 v[68:71], v[162:165], v[214:217], v[68:71]
	v_mfma_f32_16x16x32_bf16 v[64:67], v[170:173], v[214:217], v[64:67]
	v_mfma_f32_16x16x32_bf16 v[116:119], v[166:169], v[194:197], v[116:119]
	v_mfma_f32_16x16x32_bf16 v[112:115], v[174:177], v[194:197], v[112:115]
	v_mfma_f32_16x16x32_bf16 v[100:103], v[166:169], v[202:205], v[100:103]
	v_mfma_f32_16x16x32_bf16 v[92:95], v[174:177], v[202:205], v[92:95]
	v_mfma_f32_16x16x32_bf16 v[84:87], v[166:169], v[210:213], v[84:87]
	v_mfma_f32_16x16x32_bf16 v[76:79], v[174:177], v[210:213], v[76:79]
	v_mfma_f32_16x16x32_bf16 v[68:71], v[166:169], v[218:221], v[68:71]
	v_mfma_f32_16x16x32_bf16 v[64:67], v[174:177], v[218:221], v[64:67]
	s_barrier
	s_add_i32 s18, s18, s23
	v_lshl_add_u64 v[146:147], vcc, 0, v[128:129]
	s_mov_b32 m0, s18
	ds_read_b128 v[178:181], v153 offset:16384
	ds_read_b128 v[194:197], v153 offset:17408
	ds_read_b128 v[198:201], v153 offset:18432
	ds_read_b128 v[202:205], v153 offset:19456
	ds_read_b128 v[206:209], v153 offset:20480
	ds_read_b128 v[210:213], v153 offset:21504
	ds_read_b128 v[214:217], v153 offset:22528
	ds_read_b128 v[218:221], v153 offset:23552
	global_load_lds_dwordx4 v[146:147], off
	v_lshl_add_u64 v[182:183], v[146:147], 0, s[34:35]
	s_add_i32 m0, s18, 0x2000
	s_add_i32 s18, s21, s23
	global_load_lds_dwordx4 v[182:183], off
	v_lshl_add_u64 v[182:183], v[146:147], 0, s[92:93]
	s_mov_b32 m0, s18
	s_nop 0
	global_load_lds_dwordx4 v[182:183], off
	v_lshl_add_u64 v[182:183], v[146:147], 0, s[52:53]
	s_add_i32 m0, s18, 0x2000
	s_nop 0
	global_load_lds_dwordx4 v[182:183], off
	v_lshl_add_u64 v[182:183], s[14:15], 0, v[130:131]
	s_mov_b32 m0, s25
	v_lshl_add_u64 v[186:187], v[182:183], 0, s[34:35]
	global_load_lds_dwordx4 v[182:183], off
	s_mov_b32 m0, s26
	s_nop 0
	global_load_lds_dwordx4 v[186:187], off
	s_waitcnt vmcnt(8)
	s_waitcnt lgkmcnt(0)
	s_barrier
	s_waitcnt lgkmcnt(0)
	v_mfma_f32_16x16x32_bf16 v[60:63], v[138:141], v[178:181], v[60:63]
	v_mfma_f32_16x16x32_bf16 v[56:59], v[154:157], v[178:181], v[56:59]
	v_mfma_f32_16x16x32_bf16 v[48:51], v[138:141], v[198:201], v[48:51]
	v_mfma_f32_16x16x32_bf16 v[40:43], v[154:157], v[198:201], v[40:43]
	v_mfma_f32_16x16x32_bf16 v[32:35], v[138:141], v[206:209], v[32:35]
	v_mfma_f32_16x16x32_bf16 v[24:27], v[154:157], v[206:209], v[24:27]
	v_mfma_f32_16x16x32_bf16 v[16:19], v[138:141], v[214:217], v[16:19]
	v_mfma_f32_16x16x32_bf16 v[8:11], v[154:157], v[214:217], v[8:11]
	v_mfma_f32_16x16x32_bf16 v[60:63], v[142:145], v[194:197], v[60:63]
	v_mfma_f32_16x16x32_bf16 v[56:59], v[158:161], v[194:197], v[56:59]
	v_mfma_f32_16x16x32_bf16 v[48:51], v[142:145], v[202:205], v[48:51]
	v_mfma_f32_16x16x32_bf16 v[40:43], v[158:161], v[202:205], v[40:43]
	v_mfma_f32_16x16x32_bf16 v[32:35], v[142:145], v[210:213], v[32:35]
	v_mfma_f32_16x16x32_bf16 v[24:27], v[158:161], v[210:213], v[24:27]
	v_mfma_f32_16x16x32_bf16 v[16:19], v[142:145], v[218:221], v[16:19]
	v_mfma_f32_16x16x32_bf16 v[8:11], v[158:161], v[218:221], v[8:11]
	v_mfma_f32_16x16x32_bf16 v[52:55], v[162:165], v[178:181], v[52:55]
	v_mfma_f32_16x16x32_bf16 v[44:47], v[170:173], v[178:181], v[44:47]
	v_mfma_f32_16x16x32_bf16 v[36:39], v[162:165], v[198:201], v[36:39]
	v_mfma_f32_16x16x32_bf16 v[28:31], v[170:173], v[198:201], v[28:31]
	v_mfma_f32_16x16x32_bf16 v[20:23], v[162:165], v[206:209], v[20:23]
	v_mfma_f32_16x16x32_bf16 v[12:15], v[170:173], v[206:209], v[12:15]
	v_mfma_f32_16x16x32_bf16 v[4:7], v[162:165], v[214:217], v[4:7]
	v_mfma_f32_16x16x32_bf16 v[0:3], v[170:173], v[214:217], v[0:3]
	v_mfma_f32_16x16x32_bf16 v[52:55], v[166:169], v[194:197], v[52:55]
	v_mfma_f32_16x16x32_bf16 v[44:47], v[174:177], v[194:197], v[44:47]
	v_mfma_f32_16x16x32_bf16 v[36:39], v[166:169], v[202:205], v[36:39]
	v_mfma_f32_16x16x32_bf16 v[28:31], v[174:177], v[202:205], v[28:31]
	v_mfma_f32_16x16x32_bf16 v[20:23], v[166:169], v[210:213], v[20:23]
	v_mfma_f32_16x16x32_bf16 v[12:15], v[174:177], v[210:213], v[12:15]
	v_mfma_f32_16x16x32_bf16 v[4:7], v[166:169], v[218:221], v[4:7]
	v_mfma_f32_16x16x32_bf16 v[0:3], v[174:177], v[218:221], v[0:3]
	s_barrier
	s_add_i32 s14, 0, 0x18000
	v_add_u32_e32 v137, s14, v149
	s_add_i32 s15, 0, 0x1c000
	ds_read_b128 v[138:141], v137
	ds_read_b128 v[142:145], v137 offset:1024
	ds_read_b128 v[154:157], v137 offset:2048
	ds_read_b128 v[158:161], v137 offset:3072
	v_add_u32_e32 v137, s15, v149
	ds_read_b128 v[162:165], v137
	ds_read_b128 v[166:169], v137 offset:1024
	ds_read_b128 v[170:173], v137 offset:2048
	ds_read_b128 v[174:177], v137 offset:3072
	s_mov_b32 m0, s27
	v_lshl_add_u64 v[186:187], v[182:183], 0, s[92:93]
	ds_read_b128 v[178:181], v153 offset:32768
	ds_read_b128 v[194:197], v153 offset:33792
	ds_read_b128 v[198:201], v153 offset:34816
	ds_read_b128 v[202:205], v153 offset:35840
	ds_read_b128 v[206:209], v153 offset:36864
	ds_read_b128 v[210:213], v153 offset:37888
	ds_read_b128 v[214:217], v153 offset:38912
	ds_read_b128 v[218:221], v153 offset:39936
	global_load_lds_dwordx4 v[186:187], off
	v_lshl_add_u64 v[186:187], v[182:183], 0, s[52:53]
	s_mov_b32 m0, s28
	s_nop 0
	global_load_lds_dwordx4 v[186:187], off
	s_waitcnt vmcnt(8)
	s_waitcnt lgkmcnt(0)
	s_barrier
	s_waitcnt lgkmcnt(0)
	v_mfma_f32_16x16x32_bf16 v[124:127], v[138:141], v[178:181], v[124:127]
	v_mfma_f32_16x16x32_bf16 v[120:123], v[154:157], v[178:181], v[120:123]
	v_mfma_f32_16x16x32_bf16 v[108:111], v[138:141], v[198:201], v[108:111]
	v_mfma_f32_16x16x32_bf16 v[104:107], v[154:157], v[198:201], v[104:107]
	v_mfma_f32_16x16x32_bf16 v[96:99], v[138:141], v[206:209], v[96:99]
	v_mfma_f32_16x16x32_bf16 v[88:91], v[154:157], v[206:209], v[88:91]
	v_mfma_f32_16x16x32_bf16 v[80:83], v[138:141], v[214:217], v[80:83]
	v_mfma_f32_16x16x32_bf16 v[72:75], v[154:157], v[214:217], v[72:75]
	v_mfma_f32_16x16x32_bf16 v[124:127], v[142:145], v[194:197], v[124:127]
	v_mfma_f32_16x16x32_bf16 v[120:123], v[158:161], v[194:197], v[120:123]
	v_mfma_f32_16x16x32_bf16 v[108:111], v[142:145], v[202:205], v[108:111]
	v_mfma_f32_16x16x32_bf16 v[104:107], v[158:161], v[202:205], v[104:107]
	v_mfma_f32_16x16x32_bf16 v[96:99], v[142:145], v[210:213], v[96:99]
	v_mfma_f32_16x16x32_bf16 v[88:91], v[158:161], v[210:213], v[88:91]
	v_mfma_f32_16x16x32_bf16 v[80:83], v[142:145], v[218:221], v[80:83]
	v_mfma_f32_16x16x32_bf16 v[72:75], v[158:161], v[218:221], v[72:75]
	v_mfma_f32_16x16x32_bf16 v[116:119], v[162:165], v[178:181], v[116:119]
	v_mfma_f32_16x16x32_bf16 v[112:115], v[170:173], v[178:181], v[112:115]
	v_mfma_f32_16x16x32_bf16 v[100:103], v[162:165], v[198:201], v[100:103]
	v_mfma_f32_16x16x32_bf16 v[92:95], v[170:173], v[198:201], v[92:95]
	v_mfma_f32_16x16x32_bf16 v[84:87], v[162:165], v[206:209], v[84:87]
	v_mfma_f32_16x16x32_bf16 v[76:79], v[170:173], v[206:209], v[76:79]
	v_mfma_f32_16x16x32_bf16 v[68:71], v[162:165], v[214:217], v[68:71]
	v_mfma_f32_16x16x32_bf16 v[64:67], v[170:173], v[214:217], v[64:67]
	v_mfma_f32_16x16x32_bf16 v[116:119], v[166:169], v[194:197], v[116:119]
	v_mfma_f32_16x16x32_bf16 v[112:115], v[174:177], v[194:197], v[112:115]
	v_mfma_f32_16x16x32_bf16 v[100:103], v[166:169], v[202:205], v[100:103]
	v_mfma_f32_16x16x32_bf16 v[92:95], v[174:177], v[202:205], v[92:95]
	v_mfma_f32_16x16x32_bf16 v[84:87], v[166:169], v[210:213], v[84:87]
	v_mfma_f32_16x16x32_bf16 v[76:79], v[174:177], v[210:213], v[76:79]
	v_mfma_f32_16x16x32_bf16 v[68:71], v[166:169], v[218:221], v[68:71]
	v_mfma_f32_16x16x32_bf16 v[64:67], v[174:177], v[218:221], v[64:67]
	s_barrier
	s_add_i32 s14, s14, s23
	v_lshl_add_u64 v[186:187], v[146:147], 0, s[56:57]
	s_mov_b32 m0, s14
	ds_read_b128 v[178:181], v153 offset:49152
	ds_read_b128 v[194:197], v153 offset:50176
	ds_read_b128 v[198:201], v153 offset:51200
	ds_read_b128 v[202:205], v153 offset:52224
	ds_read_b128 v[206:209], v153 offset:53248
	ds_read_b128 v[210:213], v153 offset:54272
	ds_read_b128 v[214:217], v153 offset:55296
	ds_read_b128 v[218:221], v153 offset:56320
	global_load_lds_dwordx4 v[186:187], off
	v_lshl_add_u64 v[186:187], v[146:147], 0, s[96:97]
	s_add_i32 m0, s14, 0x2000
	s_add_i32 s14, s15, s23
	global_load_lds_dwordx4 v[186:187], off
	v_lshl_add_u64 v[186:187], v[146:147], 0, s[88:89]
	s_mov_b32 m0, s14
	v_lshl_add_u64 v[146:147], v[146:147], 0, s[68:69]
	global_load_lds_dwordx4 v[186:187], off
	s_add_i32 m0, s14, 0x2000
	s_nop 0
	global_load_lds_dwordx4 v[146:147], off
	v_lshl_add_u64 v[146:147], v[182:183], 0, s[56:57]
	s_mov_b32 m0, s29
	s_nop 0
	global_load_lds_dwordx4 v[146:147], off
	v_lshl_add_u64 v[146:147], v[182:183], 0, s[96:97]
	s_mov_b32 m0, s30
	s_nop 0
	global_load_lds_dwordx4 v[146:147], off
	s_waitcnt vmcnt(8)
	s_waitcnt lgkmcnt(0)
	s_barrier
	s_waitcnt lgkmcnt(0)
	v_mfma_f32_16x16x32_bf16 v[60:63], v[138:141], v[178:181], v[60:63]
	v_mfma_f32_16x16x32_bf16 v[56:59], v[154:157], v[178:181], v[56:59]
	v_mfma_f32_16x16x32_bf16 v[48:51], v[138:141], v[198:201], v[48:51]
	v_mfma_f32_16x16x32_bf16 v[40:43], v[154:157], v[198:201], v[40:43]
	v_mfma_f32_16x16x32_bf16 v[32:35], v[138:141], v[206:209], v[32:35]
	v_mfma_f32_16x16x32_bf16 v[24:27], v[154:157], v[206:209], v[24:27]
	v_mfma_f32_16x16x32_bf16 v[16:19], v[138:141], v[214:217], v[16:19]
	v_mfma_f32_16x16x32_bf16 v[8:11], v[154:157], v[214:217], v[8:11]
	v_mfma_f32_16x16x32_bf16 v[60:63], v[142:145], v[194:197], v[60:63]
	v_mfma_f32_16x16x32_bf16 v[56:59], v[158:161], v[194:197], v[56:59]
	v_mfma_f32_16x16x32_bf16 v[48:51], v[142:145], v[202:205], v[48:51]
	v_mfma_f32_16x16x32_bf16 v[40:43], v[158:161], v[202:205], v[40:43]
	v_mfma_f32_16x16x32_bf16 v[32:35], v[142:145], v[210:213], v[32:35]
	v_mfma_f32_16x16x32_bf16 v[24:27], v[158:161], v[210:213], v[24:27]
	v_mfma_f32_16x16x32_bf16 v[16:19], v[142:145], v[218:221], v[16:19]
	v_mfma_f32_16x16x32_bf16 v[8:11], v[158:161], v[218:221], v[8:11]
	v_mfma_f32_16x16x32_bf16 v[52:55], v[162:165], v[178:181], v[52:55]
	v_mfma_f32_16x16x32_bf16 v[44:47], v[170:173], v[178:181], v[44:47]
	v_mfma_f32_16x16x32_bf16 v[36:39], v[162:165], v[198:201], v[36:39]
	v_mfma_f32_16x16x32_bf16 v[28:31], v[170:173], v[198:201], v[28:31]
	v_mfma_f32_16x16x32_bf16 v[20:23], v[162:165], v[206:209], v[20:23]
	v_mfma_f32_16x16x32_bf16 v[12:15], v[170:173], v[206:209], v[12:15]
	v_mfma_f32_16x16x32_bf16 v[4:7], v[162:165], v[214:217], v[4:7]
	v_mfma_f32_16x16x32_bf16 v[0:3], v[170:173], v[214:217], v[0:3]
	v_mfma_f32_16x16x32_bf16 v[52:55], v[166:169], v[194:197], v[52:55]
	v_mfma_f32_16x16x32_bf16 v[44:47], v[174:177], v[194:197], v[44:47]
	v_mfma_f32_16x16x32_bf16 v[36:39], v[166:169], v[202:205], v[36:39]
	v_mfma_f32_16x16x32_bf16 v[28:31], v[174:177], v[202:205], v[28:31]
	v_mfma_f32_16x16x32_bf16 v[20:23], v[166:169], v[210:213], v[20:23]
	v_mfma_f32_16x16x32_bf16 v[12:15], v[174:177], v[210:213], v[12:15]
	v_mfma_f32_16x16x32_bf16 v[4:7], v[166:169], v[218:221], v[4:7]
	v_mfma_f32_16x16x32_bf16 v[0:3], v[174:177], v[218:221], v[0:3]
	s_barrier
	s_add_i32 s85, s85, 2
	s_add_u32 s60, s60, 0x100
	s_addc_u32 s61, s61, 0
	s_add_u32 s16, s16, 0x100
	s_addc_u32 s17, s17, 0
	s_cmp_gt_u32 s85, 13
	s_cbranch_scc0 .LBB0_249
	s_and_b64 vcc, exec, s[40:41]
	s_cbranch_vccz .LBB0_252
	s_barrier

.LBB0_316:
	s_add_u32 s50, s16, 0x58080
	s_addc_u32 s51, s17, 0
	s_add_u32 s70, s14, 0x100
	s_addc_u32 s84, s15, 0
	s_mov_b32 s85, -2
	s_waitcnt lgkmcnt(0)
	s_mov_b64 vcc, 0x2c000
	s_mov_b64 s[82:83], 0x84000
	s_mov_b64 s[80:81], 0x2c080
	s_mov_b64 s[74:75], 0x58080
	s_mov_b64 s[62:63], 0x84080
	s_add_u32 s14, s50, 0xfffa8080
	s_addc_u32 s15, s51, -1
	s_add_i32 s22, 0, 0x10000
	s_cmp_eq_u32 s85, 18
	s_cselect_b32 s15, s1, s15
	s_cselect_b32 s14, s0, s14
	s_cselect_b32 s17, s49, s84
	s_cselect_b32 s16, s48, s70
	s_add_i32 s23, 0, 0x14000
	v_add_u32_e32 v0, s22, v221
	v_add_u32_e32 v4, s23, v221
	ds_read_b128 v[24:27], v0
	ds_read_b128 v[28:31], v0 offset:1024
	ds_read_b128 v[16:19], v0 offset:2048
	ds_read_b128 v[20:23], v0 offset:3072
	ds_read_b128 v[8:11], v4
	ds_read_b128 v[12:15], v4 offset:1024
	ds_read_b128 v[0:3], v4 offset:2048
	ds_read_b128 v[4:7], v4 offset:3072
	v_lshl_add_u64 v[206:207], s[50:51], 0, v[196:197]
	s_add_i32 m0, s19, 0xc000
	ds_read_b128 v[160:163], v223
	ds_read_b128 v[164:167], v223 offset:1024
	ds_read_b128 v[168:171], v223 offset:2048
	ds_read_b128 v[172:175], v223 offset:3072
	ds_read_b128 v[176:179], v223 offset:4096
	ds_read_b128 v[180:183], v223 offset:5120
	ds_read_b128 v[198:201], v223 offset:6144
	ds_read_b128 v[202:205], v223 offset:7168
	global_load_lds_dwordx4 v[206:207], off
	v_lshl_add_u64 v[206:207], v[206:207], 0, vcc
	s_add_i32 m0, s19, 0xe000
	s_nop 0
	global_load_lds_dwordx4 v[206:207], off
	s_waitcnt vmcnt(8)
	s_waitcnt lgkmcnt(0)
	s_barrier
	s_waitcnt lgkmcnt(0)
	v_mfma_scale_f32_16x16x128_f8f6f4 v[156:159], v[24:31], v[160:167], 0, v240, v240 op_sel_hi:[0,0,0]
	v_mfma_scale_f32_16x16x128_f8f6f4 v[152:155], v[16:23], v[160:167], 0, v240, v240 op_sel_hi:[0,0,0]
	v_mfma_scale_f32_16x16x128_f8f6f4 v[140:143], v[24:31], v[168:175], 0, v240, v240 op_sel_hi:[0,0,0]
	v_mfma_scale_f32_16x16x128_f8f6f4 v[136:139], v[16:23], v[168:175], 0, v240, v240 op_sel_hi:[0,0,0]
	v_mfma_scale_f32_16x16x128_f8f6f4 v[124:127], v[24:31], v[176:183], 0, v240, v240 op_sel_hi:[0,0,0]
	v_mfma_scale_f32_16x16x128_f8f6f4 v[120:123], v[16:23], v[176:183], 0, v240, v240 op_sel_hi:[0,0,0]
	v_mfma_scale_f32_16x16x128_f8f6f4 v[108:111], v[24:31], v[198:205], 0, v240, v240 op_sel_hi:[0,0,0]
	v_mfma_scale_f32_16x16x128_f8f6f4 v[104:107], v[16:23], v[198:205], 0, v240, v240 op_sel_hi:[0,0,0]
	v_mfma_scale_f32_16x16x128_f8f6f4 v[148:151], v[8:15], v[160:167], 0, v240, v240 op_sel_hi:[0,0,0]
	v_mfma_scale_f32_16x16x128_f8f6f4 v[144:147], v[0:7], v[160:167], 0, v240, v240 op_sel_hi:[0,0,0]
	v_mfma_scale_f32_16x16x128_f8f6f4 v[132:135], v[8:15], v[168:175], 0, v240, v240 op_sel_hi:[0,0,0]
	v_mfma_scale_f32_16x16x128_f8f6f4 v[128:131], v[0:7], v[168:175], 0, v240, v240 op_sel_hi:[0,0,0]
	v_mfma_scale_f32_16x16x128_f8f6f4 v[116:119], v[8:15], v[176:183], 0, v240, v240 op_sel_hi:[0,0,0]
	v_mfma_scale_f32_16x16x128_f8f6f4 v[112:115], v[0:7], v[176:183], 0, v240, v240 op_sel_hi:[0,0,0]
	v_mfma_scale_f32_16x16x128_f8f6f4 v[100:103], v[8:15], v[198:205], 0, v240, v240 op_sel_hi:[0,0,0]
	v_mfma_scale_f32_16x16x128_f8f6f4 v[96:99], v[0:7], v[198:205], 0, v240, v240 op_sel_hi:[0,0,0]
	s_barrier
	v_lshl_add_u64 v[160:161], s[16:17], 0, v[184:185]
	s_add_i32 s16, s22, s6
	s_mov_b32 m0, s16
	ds_read_b128 v[164:167], v223 offset:16384
	ds_read_b128 v[168:171], v223 offset:17408
	ds_read_b128 v[172:175], v223 offset:18432
	ds_read_b128 v[176:179], v223 offset:19456
	ds_read_b128 v[198:201], v223 offset:20480
	ds_read_b128 v[202:205], v223 offset:21504
	ds_read_b128 v[206:209], v223 offset:22528
	ds_read_b128 v[210:213], v223 offset:23552
	global_load_lds_dwordx4 v[160:161], off
	v_lshl_add_u64 v[162:163], v[160:161], 0, vcc
	s_add_i32 m0, s16, 0x2000
	s_add_i32 s16, s23, s6
	global_load_lds_dwordx4 v[162:163], off
	v_lshl_add_u64 v[162:163], v[160:161], 0, s[2:3]
	s_mov_b32 m0, s16
	s_nop 0
	global_load_lds_dwordx4 v[162:163], off
	v_lshl_add_u64 v[162:163], v[160:161], 0, s[82:83]
	s_add_i32 m0, s16, 0x2000
	s_nop 0
	global_load_lds_dwordx4 v[162:163], off
	v_lshl_add_u64 v[162:163], s[14:15], 0, v[194:195]
	s_mov_b32 m0, s19
	v_lshl_add_u64 v[180:181], v[162:163], 0, vcc
	global_load_lds_dwordx4 v[162:163], off
	s_mov_b32 m0, s20
	s_nop 0
	global_load_lds_dwordx4 v[180:181], off
	s_waitcnt vmcnt(8)
	s_waitcnt lgkmcnt(0)
	s_barrier
	s_waitcnt lgkmcnt(0)
	v_mfma_scale_f32_16x16x128_f8f6f4 v[92:95], v[24:31], v[164:171], 0, v240, v240 op_sel_hi:[0,0,0]
	v_mfma_scale_f32_16x16x128_f8f6f4 v[88:91], v[16:23], v[164:171], 0, v240, v240 op_sel_hi:[0,0,0]
	v_mfma_scale_f32_16x16x128_f8f6f4 v[76:79], v[24:31], v[172:179], 0, v240, v240 op_sel_hi:[0,0,0]
	v_mfma_scale_f32_16x16x128_f8f6f4 v[72:75], v[16:23], v[172:179], 0, v240, v240 op_sel_hi:[0,0,0]
	v_mfma_scale_f32_16x16x128_f8f6f4 v[60:63], v[24:31], v[198:205], 0, v240, v240 op_sel_hi:[0,0,0]
	v_mfma_scale_f32_16x16x128_f8f6f4 v[56:59], v[16:23], v[198:205], 0, v240, v240 op_sel_hi:[0,0,0]
	v_mfma_scale_f32_16x16x128_f8f6f4 v[44:47], v[24:31], v[206:213], 0, v240, v240 op_sel_hi:[0,0,0]
	v_mfma_scale_f32_16x16x128_f8f6f4 v[40:43], v[16:23], v[206:213], 0, v240, v240 op_sel_hi:[0,0,0]
	v_mfma_scale_f32_16x16x128_f8f6f4 v[84:87], v[8:15], v[164:171], 0, v240, v240 op_sel_hi:[0,0,0]
	v_mfma_scale_f32_16x16x128_f8f6f4 v[80:83], v[0:7], v[164:171], 0, v240, v240 op_sel_hi:[0,0,0]
	v_mfma_scale_f32_16x16x128_f8f6f4 v[68:71], v[8:15], v[172:179], 0, v240, v240 op_sel_hi:[0,0,0]
	v_mfma_scale_f32_16x16x128_f8f6f4 v[64:67], v[0:7], v[172:179], 0, v240, v240 op_sel_hi:[0,0,0]
	v_mfma_scale_f32_16x16x128_f8f6f4 v[52:55], v[8:15], v[198:205], 0, v240, v240 op_sel_hi:[0,0,0]
	v_mfma_scale_f32_16x16x128_f8f6f4 v[48:51], v[0:7], v[198:205], 0, v240, v240 op_sel_hi:[0,0,0]
	v_mfma_scale_f32_16x16x128_f8f6f4 v[36:39], v[8:15], v[206:213], 0, v240, v240 op_sel_hi:[0,0,0]
	v_mfma_scale_f32_16x16x128_f8f6f4 v[32:35], v[0:7], v[206:213], 0, v240, v240 op_sel_hi:[0,0,0]
	s_barrier
	s_add_i32 s14, 0, 0x18000
	s_add_i32 s15, 0, 0x1c000
	v_add_u32_e32 v12, s14, v221
	v_add_u32_e32 v28, s15, v221
	ds_read_b128 v[0:3], v12
	ds_read_b128 v[4:7], v12 offset:1024
	ds_read_b128 v[8:11], v12 offset:2048
	ds_read_b128 v[12:15], v12 offset:3072
	ds_read_b128 v[16:19], v28
	ds_read_b128 v[20:23], v28 offset:1024
	ds_read_b128 v[24:27], v28 offset:2048
	ds_read_b128 v[28:31], v28 offset:3072
	s_mov_b32 m0, s25
	v_lshl_add_u64 v[180:181], v[162:163], 0, s[2:3]
	ds_read_b128 v[164:167], v223 offset:32768
	ds_read_b128 v[168:171], v223 offset:33792
	ds_read_b128 v[172:175], v223 offset:34816
	ds_read_b128 v[176:179], v223 offset:35840
	ds_read_b128 v[198:201], v223 offset:36864
	ds_read_b128 v[202:205], v223 offset:37888
	ds_read_b128 v[206:209], v223 offset:38912
	ds_read_b128 v[210:213], v223 offset:39936
	global_load_lds_dwordx4 v[180:181], off
	v_lshl_add_u64 v[180:181], v[162:163], 0, s[82:83]
	s_mov_b32 m0, s26
	s_nop 0
	global_load_lds_dwordx4 v[180:181], off
	s_waitcnt vmcnt(8)
	s_waitcnt lgkmcnt(0)
	s_barrier
	s_waitcnt lgkmcnt(0)
	v_mfma_scale_f32_16x16x128_f8f6f4 v[156:159], v[0:7], v[164:171], v[156:159], v240, v240 op_sel_hi:[0,0,0]
	v_mfma_scale_f32_16x16x128_f8f6f4 v[152:155], v[8:15], v[164:171], v[152:155], v240, v240 op_sel_hi:[0,0,0]
	v_mfma_scale_f32_16x16x128_f8f6f4 v[140:143], v[0:7], v[172:179], v[140:143], v240, v240 op_sel_hi:[0,0,0]
	v_mfma_scale_f32_16x16x128_f8f6f4 v[136:139], v[8:15], v[172:179], v[136:139], v240, v240 op_sel_hi:[0,0,0]
	v_mfma_scale_f32_16x16x128_f8f6f4 v[124:127], v[0:7], v[198:205], v[124:127], v240, v240 op_sel_hi:[0,0,0]
	v_mfma_scale_f32_16x16x128_f8f6f4 v[120:123], v[8:15], v[198:205], v[120:123], v240, v240 op_sel_hi:[0,0,0]
	v_mfma_scale_f32_16x16x128_f8f6f4 v[108:111], v[0:7], v[206:213], v[108:111], v240, v240 op_sel_hi:[0,0,0]
	v_mfma_scale_f32_16x16x128_f8f6f4 v[104:107], v[8:15], v[206:213], v[104:107], v240, v240 op_sel_hi:[0,0,0]
	v_mfma_scale_f32_16x16x128_f8f6f4 v[148:151], v[16:23], v[164:171], v[148:151], v240, v240 op_sel_hi:[0,0,0]
	v_mfma_scale_f32_16x16x128_f8f6f4 v[144:147], v[24:31], v[164:171], v[144:147], v240, v240 op_sel_hi:[0,0,0]
	v_mfma_scale_f32_16x16x128_f8f6f4 v[132:135], v[16:23], v[172:179], v[132:135], v240, v240 op_sel_hi:[0,0,0]
	v_mfma_scale_f32_16x16x128_f8f6f4 v[128:131], v[24:31], v[172:179], v[128:131], v240, v240 op_sel_hi:[0,0,0]
	v_mfma_scale_f32_16x16x128_f8f6f4 v[116:119], v[16:23], v[198:205], v[116:119], v240, v240 op_sel_hi:[0,0,0]
	v_mfma_scale_f32_16x16x128_f8f6f4 v[112:115], v[24:31], v[198:205], v[112:115], v240, v240 op_sel_hi:[0,0,0]
	v_mfma_scale_f32_16x16x128_f8f6f4 v[100:103], v[16:23], v[206:213], v[100:103], v240, v240 op_sel_hi:[0,0,0]
	v_mfma_scale_f32_16x16x128_f8f6f4 v[96:99], v[24:31], v[206:213], v[96:99], v240, v240 op_sel_hi:[0,0,0]
	s_barrier
	s_add_i32 s14, s14, s6
	v_lshl_add_u64 v[180:181], v[160:161], 0, s[56:57]
	s_mov_b32 m0, s14
	ds_read_b128 v[164:167], v223 offset:49152
	ds_read_b128 v[168:171], v223 offset:50176
	ds_read_b128 v[172:175], v223 offset:51200
	ds_read_b128 v[176:179], v223 offset:52224
	ds_read_b128 v[198:201], v223 offset:53248
	ds_read_b128 v[202:205], v223 offset:54272
	ds_read_b128 v[206:209], v223 offset:55296
	ds_read_b128 v[210:213], v223 offset:56320
	global_load_lds_dwordx4 v[180:181], off
	v_lshl_add_u64 v[180:181], v[160:161], 0, s[80:81]
	s_add_i32 m0, s14, 0x2000
	s_add_i32 s14, s15, s6
	global_load_lds_dwordx4 v[180:181], off
	v_lshl_add_u64 v[180:181], v[160:161], 0, s[74:75]
	s_mov_b32 m0, s14
	v_lshl_add_u64 v[160:161], v[160:161], 0, s[62:63]
	global_load_lds_dwordx4 v[180:181], off
	s_add_i32 m0, s14, 0x2000
	s_nop 0
	global_load_lds_dwordx4 v[160:161], off
	v_lshl_add_u64 v[160:161], v[162:163], 0, s[56:57]
	s_mov_b32 m0, s28
	s_nop 0
	global_load_lds_dwordx4 v[160:161], off
	v_lshl_add_u64 v[160:161], v[162:163], 0, s[80:81]
	s_mov_b32 m0, s29
	s_nop 0
	global_load_lds_dwordx4 v[160:161], off
	s_waitcnt vmcnt(8)
	s_waitcnt lgkmcnt(0)
	s_barrier
	s_waitcnt lgkmcnt(0)
	v_mfma_scale_f32_16x16x128_f8f6f4 v[92:95], v[0:7], v[164:171], v[92:95], v240, v240 op_sel_hi:[0,0,0]
	v_mfma_scale_f32_16x16x128_f8f6f4 v[88:91], v[8:15], v[164:171], v[88:91], v240, v240 op_sel_hi:[0,0,0]
	v_mfma_scale_f32_16x16x128_f8f6f4 v[76:79], v[0:7], v[172:179], v[76:79], v240, v240 op_sel_hi:[0,0,0]
	v_mfma_scale_f32_16x16x128_f8f6f4 v[72:75], v[8:15], v[172:179], v[72:75], v240, v240 op_sel_hi:[0,0,0]
	v_mfma_scale_f32_16x16x128_f8f6f4 v[60:63], v[0:7], v[198:205], v[60:63], v240, v240 op_sel_hi:[0,0,0]
	v_mfma_scale_f32_16x16x128_f8f6f4 v[56:59], v[8:15], v[198:205], v[56:59], v240, v240 op_sel_hi:[0,0,0]
	v_mfma_scale_f32_16x16x128_f8f6f4 v[44:47], v[0:7], v[206:213], v[44:47], v240, v240 op_sel_hi:[0,0,0]
	v_mfma_scale_f32_16x16x128_f8f6f4 v[40:43], v[8:15], v[206:213], v[40:43], v240, v240 op_sel_hi:[0,0,0]
	v_mfma_scale_f32_16x16x128_f8f6f4 v[84:87], v[16:23], v[164:171], v[84:87], v240, v240 op_sel_hi:[0,0,0]
	v_mfma_scale_f32_16x16x128_f8f6f4 v[80:83], v[24:31], v[164:171], v[80:83], v240, v240 op_sel_hi:[0,0,0]
	v_mfma_scale_f32_16x16x128_f8f6f4 v[68:71], v[16:23], v[172:179], v[68:71], v240, v240 op_sel_hi:[0,0,0]
	v_mfma_scale_f32_16x16x128_f8f6f4 v[64:67], v[24:31], v[172:179], v[64:67], v240, v240 op_sel_hi:[0,0,0]
	v_mfma_scale_f32_16x16x128_f8f6f4 v[52:55], v[16:23], v[198:205], v[52:55], v240, v240 op_sel_hi:[0,0,0]
	v_mfma_scale_f32_16x16x128_f8f6f4 v[48:51], v[24:31], v[198:205], v[48:51], v240, v240 op_sel_hi:[0,0,0]
	v_mfma_scale_f32_16x16x128_f8f6f4 v[36:39], v[16:23], v[206:213], v[36:39], v240, v240 op_sel_hi:[0,0,0]
	v_mfma_scale_f32_16x16x128_f8f6f4 v[32:35], v[24:31], v[206:213], v[32:35], v240, v240 op_sel_hi:[0,0,0]
	s_barrier
	s_add_i32 s85, s85, 2
	s_add_u32 s50, s50, 0x100
	s_addc_u32 s51, s51, 0
	s_add_u32 s70, s70, 0x100
	s_addc_u32 s84, s84, 0
	s_cmp_gt_u32 s85, 19
.LBB0_317:
	s_add_u32 s14, s50, 0xfffa8080
	s_addc_u32 s15, s51, -1
	s_add_i32 s22, 0, 0x10000
	s_cmp_eq_u32 s85, 18
	s_cselect_b32 s15, s1, s15
	s_cselect_b32 s14, s0, s14
	s_cselect_b32 s17, s49, s84
	s_cselect_b32 s16, s48, s70
	s_add_i32 s23, 0, 0x14000
	v_add_u32_e32 v0, s22, v221
	v_add_u32_e32 v4, s23, v221
	ds_read_b128 v[24:27], v0
	ds_read_b128 v[28:31], v0 offset:1024
	ds_read_b128 v[16:19], v0 offset:2048
	ds_read_b128 v[20:23], v0 offset:3072
	ds_read_b128 v[8:11], v4
	ds_read_b128 v[12:15], v4 offset:1024
	ds_read_b128 v[0:3], v4 offset:2048
	ds_read_b128 v[4:7], v4 offset:3072
	v_lshl_add_u64 v[206:207], s[50:51], 0, v[196:197]
	s_add_i32 m0, s19, 0xc000
	ds_read_b128 v[160:163], v223
	ds_read_b128 v[164:167], v223 offset:1024
	ds_read_b128 v[168:171], v223 offset:2048
	ds_read_b128 v[172:175], v223 offset:3072
	ds_read_b128 v[176:179], v223 offset:4096
	ds_read_b128 v[180:183], v223 offset:5120
	ds_read_b128 v[198:201], v223 offset:6144
	ds_read_b128 v[202:205], v223 offset:7168
	global_load_lds_dwordx4 v[206:207], off
	v_lshl_add_u64 v[206:207], v[206:207], 0, vcc
	s_add_i32 m0, s19, 0xe000
	s_nop 0
	global_load_lds_dwordx4 v[206:207], off
	s_waitcnt vmcnt(8)
	s_waitcnt lgkmcnt(0)
	s_barrier
	s_waitcnt lgkmcnt(0)
	v_mfma_scale_f32_16x16x128_f8f6f4 v[156:159], v[24:31], v[160:167], v[156:159], v240, v240 op_sel_hi:[0,0,0]
	v_mfma_scale_f32_16x16x128_f8f6f4 v[152:155], v[16:23], v[160:167], v[152:155], v240, v240 op_sel_hi:[0,0,0]
	v_mfma_scale_f32_16x16x128_f8f6f4 v[140:143], v[24:31], v[168:175], v[140:143], v240, v240 op_sel_hi:[0,0,0]
	v_mfma_scale_f32_16x16x128_f8f6f4 v[136:139], v[16:23], v[168:175], v[136:139], v240, v240 op_sel_hi:[0,0,0]
	v_mfma_scale_f32_16x16x128_f8f6f4 v[124:127], v[24:31], v[176:183], v[124:127], v240, v240 op_sel_hi:[0,0,0]
	v_mfma_scale_f32_16x16x128_f8f6f4 v[120:123], v[16:23], v[176:183], v[120:123], v240, v240 op_sel_hi:[0,0,0]
	v_mfma_scale_f32_16x16x128_f8f6f4 v[108:111], v[24:31], v[198:205], v[108:111], v240, v240 op_sel_hi:[0,0,0]
	v_mfma_scale_f32_16x16x128_f8f6f4 v[104:107], v[16:23], v[198:205], v[104:107], v240, v240 op_sel_hi:[0,0,0]
	v_mfma_scale_f32_16x16x128_f8f6f4 v[148:151], v[8:15], v[160:167], v[148:151], v240, v240 op_sel_hi:[0,0,0]
	v_mfma_scale_f32_16x16x128_f8f6f4 v[144:147], v[0:7], v[160:167], v[144:147], v240, v240 op_sel_hi:[0,0,0]
	v_mfma_scale_f32_16x16x128_f8f6f4 v[132:135], v[8:15], v[168:175], v[132:135], v240, v240 op_sel_hi:[0,0,0]
	v_mfma_scale_f32_16x16x128_f8f6f4 v[128:131], v[0:7], v[168:175], v[128:131], v240, v240 op_sel_hi:[0,0,0]
	v_mfma_scale_f32_16x16x128_f8f6f4 v[116:119], v[8:15], v[176:183], v[116:119], v240, v240 op_sel_hi:[0,0,0]
	v_mfma_scale_f32_16x16x128_f8f6f4 v[112:115], v[0:7], v[176:183], v[112:115], v240, v240 op_sel_hi:[0,0,0]
	v_mfma_scale_f32_16x16x128_f8f6f4 v[100:103], v[8:15], v[198:205], v[100:103], v240, v240 op_sel_hi:[0,0,0]
	v_mfma_scale_f32_16x16x128_f8f6f4 v[96:99], v[0:7], v[198:205], v[96:99], v240, v240 op_sel_hi:[0,0,0]
	s_barrier
	v_lshl_add_u64 v[160:161], s[16:17], 0, v[184:185]
	s_add_i32 s16, s22, s6
	s_mov_b32 m0, s16
	ds_read_b128 v[164:167], v223 offset:16384
	ds_read_b128 v[168:171], v223 offset:17408
	ds_read_b128 v[172:175], v223 offset:18432
	ds_read_b128 v[176:179], v223 offset:19456
	ds_read_b128 v[198:201], v223 offset:20480
	ds_read_b128 v[202:205], v223 offset:21504
	ds_read_b128 v[206:209], v223 offset:22528
	ds_read_b128 v[210:213], v223 offset:23552
	global_load_lds_dwordx4 v[160:161], off
	v_lshl_add_u64 v[162:163], v[160:161], 0, vcc
	s_add_i32 m0, s16, 0x2000
	s_add_i32 s16, s23, s6
	global_load_lds_dwordx4 v[162:163], off
	v_lshl_add_u64 v[162:163], v[160:161], 0, s[2:3]
	s_mov_b32 m0, s16
	s_nop 0
	global_load_lds_dwordx4 v[162:163], off
	v_lshl_add_u64 v[162:163], v[160:161], 0, s[82:83]
	s_add_i32 m0, s16, 0x2000
	s_nop 0
	global_load_lds_dwordx4 v[162:163], off
	v_lshl_add_u64 v[162:163], s[14:15], 0, v[194:195]
	s_mov_b32 m0, s19
	v_lshl_add_u64 v[180:181], v[162:163], 0, vcc
	global_load_lds_dwordx4 v[162:163], off
	s_mov_b32 m0, s20
	s_nop 0
	global_load_lds_dwordx4 v[180:181], off
	s_waitcnt vmcnt(8)
	s_waitcnt lgkmcnt(0)
	s_barrier
	s_waitcnt lgkmcnt(0)
	v_mfma_scale_f32_16x16x128_f8f6f4 v[92:95], v[24:31], v[164:171], v[92:95], v240, v240 op_sel_hi:[0,0,0]
	v_mfma_scale_f32_16x16x128_f8f6f4 v[88:91], v[16:23], v[164:171], v[88:91], v240, v240 op_sel_hi:[0,0,0]
	v_mfma_scale_f32_16x16x128_f8f6f4 v[76:79], v[24:31], v[172:179], v[76:79], v240, v240 op_sel_hi:[0,0,0]
	v_mfma_scale_f32_16x16x128_f8f6f4 v[72:75], v[16:23], v[172:179], v[72:75], v240, v240 op_sel_hi:[0,0,0]
	v_mfma_scale_f32_16x16x128_f8f6f4 v[60:63], v[24:31], v[198:205], v[60:63], v240, v240 op_sel_hi:[0,0,0]
	v_mfma_scale_f32_16x16x128_f8f6f4 v[56:59], v[16:23], v[198:205], v[56:59], v240, v240 op_sel_hi:[0,0,0]
	v_mfma_scale_f32_16x16x128_f8f6f4 v[44:47], v[24:31], v[206:213], v[44:47], v240, v240 op_sel_hi:[0,0,0]
	v_mfma_scale_f32_16x16x128_f8f6f4 v[40:43], v[16:23], v[206:213], v[40:43], v240, v240 op_sel_hi:[0,0,0]
	v_mfma_scale_f32_16x16x128_f8f6f4 v[84:87], v[8:15], v[164:171], v[84:87], v240, v240 op_sel_hi:[0,0,0]
	v_mfma_scale_f32_16x16x128_f8f6f4 v[80:83], v[0:7], v[164:171], v[80:83], v240, v240 op_sel_hi:[0,0,0]
	v_mfma_scale_f32_16x16x128_f8f6f4 v[68:71], v[8:15], v[172:179], v[68:71], v240, v240 op_sel_hi:[0,0,0]
	v_mfma_scale_f32_16x16x128_f8f6f4 v[64:67], v[0:7], v[172:179], v[64:67], v240, v240 op_sel_hi:[0,0,0]
	v_mfma_scale_f32_16x16x128_f8f6f4 v[52:55], v[8:15], v[198:205], v[52:55], v240, v240 op_sel_hi:[0,0,0]
	v_mfma_scale_f32_16x16x128_f8f6f4 v[48:51], v[0:7], v[198:205], v[48:51], v240, v240 op_sel_hi:[0,0,0]
	v_mfma_scale_f32_16x16x128_f8f6f4 v[36:39], v[8:15], v[206:213], v[36:39], v240, v240 op_sel_hi:[0,0,0]
	v_mfma_scale_f32_16x16x128_f8f6f4 v[32:35], v[0:7], v[206:213], v[32:35], v240, v240 op_sel_hi:[0,0,0]
	s_barrier
	s_add_i32 s14, 0, 0x18000
	s_add_i32 s15, 0, 0x1c000
	v_add_u32_e32 v12, s14, v221
	v_add_u32_e32 v28, s15, v221
	ds_read_b128 v[0:3], v12
	ds_read_b128 v[4:7], v12 offset:1024
	ds_read_b128 v[8:11], v12 offset:2048
	ds_read_b128 v[12:15], v12 offset:3072
	ds_read_b128 v[16:19], v28
	ds_read_b128 v[20:23], v28 offset:1024
	ds_read_b128 v[24:27], v28 offset:2048
	ds_read_b128 v[28:31], v28 offset:3072
	s_mov_b32 m0, s25
	v_lshl_add_u64 v[180:181], v[162:163], 0, s[2:3]
	ds_read_b128 v[164:167], v223 offset:32768
	ds_read_b128 v[168:171], v223 offset:33792
	ds_read_b128 v[172:175], v223 offset:34816
	ds_read_b128 v[176:179], v223 offset:35840
	ds_read_b128 v[198:201], v223 offset:36864
	ds_read_b128 v[202:205], v223 offset:37888
	ds_read_b128 v[206:209], v223 offset:38912
	ds_read_b128 v[210:213], v223 offset:39936
	global_load_lds_dwordx4 v[180:181], off
	v_lshl_add_u64 v[180:181], v[162:163], 0, s[82:83]
	s_mov_b32 m0, s26
	s_nop 0
	global_load_lds_dwordx4 v[180:181], off
	s_waitcnt vmcnt(8)
	s_waitcnt lgkmcnt(0)
	s_barrier
	s_waitcnt lgkmcnt(0)
	v_mfma_scale_f32_16x16x128_f8f6f4 v[156:159], v[0:7], v[164:171], v[156:159], v240, v240 op_sel_hi:[0,0,0]
	v_mfma_scale_f32_16x16x128_f8f6f4 v[152:155], v[8:15], v[164:171], v[152:155], v240, v240 op_sel_hi:[0,0,0]
	v_mfma_scale_f32_16x16x128_f8f6f4 v[140:143], v[0:7], v[172:179], v[140:143], v240, v240 op_sel_hi:[0,0,0]
	v_mfma_scale_f32_16x16x128_f8f6f4 v[136:139], v[8:15], v[172:179], v[136:139], v240, v240 op_sel_hi:[0,0,0]
	v_mfma_scale_f32_16x16x128_f8f6f4 v[124:127], v[0:7], v[198:205], v[124:127], v240, v240 op_sel_hi:[0,0,0]
	v_mfma_scale_f32_16x16x128_f8f6f4 v[120:123], v[8:15], v[198:205], v[120:123], v240, v240 op_sel_hi:[0,0,0]
	v_mfma_scale_f32_16x16x128_f8f6f4 v[108:111], v[0:7], v[206:213], v[108:111], v240, v240 op_sel_hi:[0,0,0]
	v_mfma_scale_f32_16x16x128_f8f6f4 v[104:107], v[8:15], v[206:213], v[104:107], v240, v240 op_sel_hi:[0,0,0]
	v_mfma_scale_f32_16x16x128_f8f6f4 v[148:151], v[16:23], v[164:171], v[148:151], v240, v240 op_sel_hi:[0,0,0]
	v_mfma_scale_f32_16x16x128_f8f6f4 v[144:147], v[24:31], v[164:171], v[144:147], v240, v240 op_sel_hi:[0,0,0]
	v_mfma_scale_f32_16x16x128_f8f6f4 v[132:135], v[16:23], v[172:179], v[132:135], v240, v240 op_sel_hi:[0,0,0]
	v_mfma_scale_f32_16x16x128_f8f6f4 v[128:131], v[24:31], v[172:179], v[128:131], v240, v240 op_sel_hi:[0,0,0]
	v_mfma_scale_f32_16x16x128_f8f6f4 v[116:119], v[16:23], v[198:205], v[116:119], v240, v240 op_sel_hi:[0,0,0]
	v_mfma_scale_f32_16x16x128_f8f6f4 v[112:115], v[24:31], v[198:205], v[112:115], v240, v240 op_sel_hi:[0,0,0]
	v_mfma_scale_f32_16x16x128_f8f6f4 v[100:103], v[16:23], v[206:213], v[100:103], v240, v240 op_sel_hi:[0,0,0]
	v_mfma_scale_f32_16x16x128_f8f6f4 v[96:99], v[24:31], v[206:213], v[96:99], v240, v240 op_sel_hi:[0,0,0]
	s_barrier
	s_add_i32 s14, s14, s6
	v_lshl_add_u64 v[180:181], v[160:161], 0, s[56:57]
	s_mov_b32 m0, s14
	ds_read_b128 v[164:167], v223 offset:49152
	ds_read_b128 v[168:171], v223 offset:50176
	ds_read_b128 v[172:175], v223 offset:51200
	ds_read_b128 v[176:179], v223 offset:52224
	ds_read_b128 v[198:201], v223 offset:53248
	ds_read_b128 v[202:205], v223 offset:54272
	ds_read_b128 v[206:209], v223 offset:55296
	ds_read_b128 v[210:213], v223 offset:56320
	global_load_lds_dwordx4 v[180:181], off
	v_lshl_add_u64 v[180:181], v[160:161], 0, s[80:81]
	s_add_i32 m0, s14, 0x2000
	s_add_i32 s14, s15, s6
	global_load_lds_dwordx4 v[180:181], off
	v_lshl_add_u64 v[180:181], v[160:161], 0, s[74:75]
	s_mov_b32 m0, s14
	v_lshl_add_u64 v[160:161], v[160:161], 0, s[62:63]
	global_load_lds_dwordx4 v[180:181], off
	s_add_i32 m0, s14, 0x2000
	s_nop 0
	global_load_lds_dwordx4 v[160:161], off
	v_lshl_add_u64 v[160:161], v[162:163], 0, s[56:57]
	s_mov_b32 m0, s28
	s_nop 0
	global_load_lds_dwordx4 v[160:161], off
	v_lshl_add_u64 v[160:161], v[162:163], 0, s[80:81]
	s_mov_b32 m0, s29
	s_nop 0
	global_load_lds_dwordx4 v[160:161], off
	s_waitcnt vmcnt(8)
	s_waitcnt lgkmcnt(0)
	s_barrier
	s_waitcnt lgkmcnt(0)
	v_mfma_scale_f32_16x16x128_f8f6f4 v[92:95], v[0:7], v[164:171], v[92:95], v240, v240 op_sel_hi:[0,0,0]
	v_mfma_scale_f32_16x16x128_f8f6f4 v[88:91], v[8:15], v[164:171], v[88:91], v240, v240 op_sel_hi:[0,0,0]
	v_mfma_scale_f32_16x16x128_f8f6f4 v[76:79], v[0:7], v[172:179], v[76:79], v240, v240 op_sel_hi:[0,0,0]
	v_mfma_scale_f32_16x16x128_f8f6f4 v[72:75], v[8:15], v[172:179], v[72:75], v240, v240 op_sel_hi:[0,0,0]
	v_mfma_scale_f32_16x16x128_f8f6f4 v[60:63], v[0:7], v[198:205], v[60:63], v240, v240 op_sel_hi:[0,0,0]
	v_mfma_scale_f32_16x16x128_f8f6f4 v[56:59], v[8:15], v[198:205], v[56:59], v240, v240 op_sel_hi:[0,0,0]
	v_mfma_scale_f32_16x16x128_f8f6f4 v[44:47], v[0:7], v[206:213], v[44:47], v240, v240 op_sel_hi:[0,0,0]
	v_mfma_scale_f32_16x16x128_f8f6f4 v[40:43], v[8:15], v[206:213], v[40:43], v240, v240 op_sel_hi:[0,0,0]
	v_mfma_scale_f32_16x16x128_f8f6f4 v[84:87], v[16:23], v[164:171], v[84:87], v240, v240 op_sel_hi:[0,0,0]
	v_mfma_scale_f32_16x16x128_f8f6f4 v[80:83], v[24:31], v[164:171], v[80:83], v240, v240 op_sel_hi:[0,0,0]
	v_mfma_scale_f32_16x16x128_f8f6f4 v[68:71], v[16:23], v[172:179], v[68:71], v240, v240 op_sel_hi:[0,0,0]
	v_mfma_scale_f32_16x16x128_f8f6f4 v[64:67], v[24:31], v[172:179], v[64:67], v240, v240 op_sel_hi:[0,0,0]
	v_mfma_scale_f32_16x16x128_f8f6f4 v[52:55], v[16:23], v[198:205], v[52:55], v240, v240 op_sel_hi:[0,0,0]
	v_mfma_scale_f32_16x16x128_f8f6f4 v[48:51], v[24:31], v[198:205], v[48:51], v240, v240 op_sel_hi:[0,0,0]
	v_mfma_scale_f32_16x16x128_f8f6f4 v[36:39], v[16:23], v[206:213], v[36:39], v240, v240 op_sel_hi:[0,0,0]
	v_mfma_scale_f32_16x16x128_f8f6f4 v[32:35], v[24:31], v[206:213], v[32:35], v240, v240 op_sel_hi:[0,0,0]
	s_barrier
	s_add_i32 s85, s85, 2
	s_add_u32 s50, s50, 0x100
	s_addc_u32 s51, s51, 0
	s_add_u32 s70, s70, 0x100
	s_addc_u32 s84, s84, 0
	s_cmp_gt_u32 s85, 19
	s_cbranch_scc0 .LBB0_317
	s_and_b64 vcc, exec, s[46:47]
	s_cbranch_vccz .LBB0_320
	s_barrier

.LBB0_361:
	s_add_u32 vcc_lo, s16, 0x80
	s_addc_u32 vcc_hi, s17, 0
	s_add_u32 s16, s14, 0x100
	s_addc_u32 s17, s15, 0
	s_mov_b32 s14, 0
	s_add_i32 s24, s14, 2
	s_add_u32 s46, vcc_lo, 0x80
	s_addc_u32 s15, vcc_hi, 0
	s_add_i32 s18, 0, 0x10000
	s_cmp_eq_u32 s6, s14
	s_cselect_b32 s15, s1, s15
	s_cselect_b32 s14, s0, s46
	s_cselect_b32 s47, s13, s17
	s_cselect_b32 s46, s12, s16
	s_add_i32 s21, 0, 0x14000
	v_add_u32_e32 v140, s18, v223
	v_add_u32_e32 v156, s21, v223
	s_waitcnt lgkmcnt(0)
	ds_read_b128 v[128:131], v140
	ds_read_b128 v[132:135], v140 offset:1024
	ds_read_b128 v[136:139], v140 offset:2048
	ds_read_b128 v[140:143], v140 offset:3072
	ds_read_b128 v[144:147], v156
	ds_read_b128 v[148:151], v156 offset:1024
	ds_read_b128 v[152:155], v156 offset:2048
	ds_read_b128 v[156:159], v156 offset:3072
	v_lshl_add_u64 v[186:187], vcc, 0, v[196:197]
	s_add_i32 m0, s28, 0xc000
	ds_read_b128 v[160:163], v225
	ds_read_b128 v[164:167], v225 offset:1024
	ds_read_b128 v[168:171], v225 offset:2048
	ds_read_b128 v[172:175], v225 offset:3072
	ds_read_b128 v[176:179], v225 offset:4096
	ds_read_b128 v[180:183], v225 offset:5120
	ds_read_b128 v[200:203], v225 offset:6144
	ds_read_b128 v[204:207], v225 offset:7168
	global_load_lds_dwordx4 v[186:187], off
	v_lshl_add_u64 v[186:187], vcc, 0, v[198:199]
	s_add_i32 m0, s28, 0xe000
	s_nop 0
	global_load_lds_dwordx4 v[186:187], off
	s_waitcnt vmcnt(8)
	s_waitcnt lgkmcnt(0)
	s_barrier
	s_waitcnt lgkmcnt(0)
	v_mfma_f32_16x16x32_bf16 v[124:127], v[128:131], v[160:163], 0
	v_mfma_f32_16x16x32_bf16 v[120:123], v[136:139], v[160:163], 0
	v_mfma_f32_16x16x32_bf16 v[108:111], v[128:131], v[168:171], 0
	v_mfma_f32_16x16x32_bf16 v[104:107], v[136:139], v[168:171], 0
	v_mfma_f32_16x16x32_bf16 v[92:95], v[128:131], v[176:179], 0
	v_mfma_f32_16x16x32_bf16 v[88:91], v[136:139], v[176:179], 0
	v_mfma_f32_16x16x32_bf16 v[76:79], v[128:131], v[200:203], 0
	v_mfma_f32_16x16x32_bf16 v[72:75], v[136:139], v[200:203], 0
	v_mfma_f32_16x16x32_bf16 v[124:127], v[132:135], v[164:167], v[124:127]
	v_mfma_f32_16x16x32_bf16 v[120:123], v[140:143], v[164:167], v[120:123]
	v_mfma_f32_16x16x32_bf16 v[108:111], v[132:135], v[172:175], v[108:111]
	v_mfma_f32_16x16x32_bf16 v[104:107], v[140:143], v[172:175], v[104:107]
	v_mfma_f32_16x16x32_bf16 v[92:95], v[132:135], v[180:183], v[92:95]
	v_mfma_f32_16x16x32_bf16 v[88:91], v[140:143], v[180:183], v[88:91]
	v_mfma_f32_16x16x32_bf16 v[76:79], v[132:135], v[204:207], v[76:79]
	v_mfma_f32_16x16x32_bf16 v[72:75], v[140:143], v[204:207], v[72:75]
	v_mfma_f32_16x16x32_bf16 v[116:119], v[144:147], v[160:163], 0
	v_mfma_f32_16x16x32_bf16 v[112:115], v[152:155], v[160:163], 0
	v_mfma_f32_16x16x32_bf16 v[100:103], v[144:147], v[168:171], 0
	v_mfma_f32_16x16x32_bf16 v[96:99], v[152:155], v[168:171], 0
	v_mfma_f32_16x16x32_bf16 v[84:87], v[144:147], v[176:179], 0
	v_mfma_f32_16x16x32_bf16 v[80:83], v[152:155], v[176:179], 0
	v_mfma_f32_16x16x32_bf16 v[68:71], v[144:147], v[200:203], 0
	v_mfma_f32_16x16x32_bf16 v[64:67], v[152:155], v[200:203], 0
	v_mfma_f32_16x16x32_bf16 v[116:119], v[148:151], v[164:167], v[116:119]
	v_mfma_f32_16x16x32_bf16 v[112:115], v[156:159], v[164:167], v[112:115]
	v_mfma_f32_16x16x32_bf16 v[100:103], v[148:151], v[172:175], v[100:103]
	v_mfma_f32_16x16x32_bf16 v[96:99], v[156:159], v[172:175], v[96:99]
	v_mfma_f32_16x16x32_bf16 v[84:87], v[148:151], v[180:183], v[84:87]
	v_mfma_f32_16x16x32_bf16 v[80:83], v[156:159], v[180:183], v[80:83]
	v_mfma_f32_16x16x32_bf16 v[68:71], v[148:151], v[204:207], v[68:71]
	v_mfma_f32_16x16x32_bf16 v[64:67], v[156:159], v[204:207], v[64:67]
	s_barrier
	s_add_i32 s18, s18, s27
	v_lshl_add_u64 v[186:187], s[46:47], 0, v[184:185]
	s_mov_b32 m0, s18
	ds_read_b128 v[160:163], v225 offset:16384
	ds_read_b128 v[164:167], v225 offset:17408
	ds_read_b128 v[168:171], v225 offset:18432
	ds_read_b128 v[172:175], v225 offset:19456
	ds_read_b128 v[176:179], v225 offset:20480
	ds_read_b128 v[180:183], v225 offset:21504
	ds_read_b128 v[200:203], v225 offset:22528
	ds_read_b128 v[204:207], v225 offset:23552
	global_load_lds_dwordx4 v[186:187], off
	s_add_i32 m0, s18, 0x2000
	s_add_u32 s46, s46, s44
	v_lshl_add_u64 v[188:189], v[186:187], 0, s[70:71]
	s_addc_u32 s47, s47, 0
	s_add_i32 s18, s21, s27
	global_load_lds_dwordx4 v[188:189], off
	v_lshl_add_u64 v[208:209], s[46:47], 0, v[184:185]
	s_mov_b32 m0, s18
	v_lshl_add_u64 v[210:211], v[208:209], 0, s[70:71]
	global_load_lds_dwordx4 v[208:209], off
	s_add_i32 m0, s18, 0x2000
	v_lshl_add_u64 v[212:213], s[14:15], 0, v[194:195]
	global_load_lds_dwordx4 v[210:211], off
	s_mov_b32 m0, s28
	v_lshl_add_u64 v[214:215], v[212:213], 0, s[70:71]
	global_load_lds_dwordx4 v[212:213], off
	s_mov_b32 m0, s29
	s_nop 0
	global_load_lds_dwordx4 v[214:215], off
	s_waitcnt vmcnt(8)
	s_waitcnt lgkmcnt(0)
	s_barrier
	s_waitcnt lgkmcnt(0)
	v_mfma_f32_16x16x32_bf16 v[60:63], v[128:131], v[160:163], 0
	v_mfma_f32_16x16x32_bf16 v[56:59], v[136:139], v[160:163], 0
	v_mfma_f32_16x16x32_bf16 v[44:47], v[128:131], v[168:171], 0
	v_mfma_f32_16x16x32_bf16 v[40:43], v[136:139], v[168:171], 0
	v_mfma_f32_16x16x32_bf16 v[28:31], v[128:131], v[176:179], 0
	v_mfma_f32_16x16x32_bf16 v[24:27], v[136:139], v[176:179], 0
	v_mfma_f32_16x16x32_bf16 v[12:15], v[128:131], v[200:203], 0
	v_mfma_f32_16x16x32_bf16 v[8:11], v[136:139], v[200:203], 0
	v_mfma_f32_16x16x32_bf16 v[60:63], v[132:135], v[164:167], v[60:63]
	v_mfma_f32_16x16x32_bf16 v[56:59], v[140:143], v[164:167], v[56:59]
	v_mfma_f32_16x16x32_bf16 v[44:47], v[132:135], v[172:175], v[44:47]
	v_mfma_f32_16x16x32_bf16 v[40:43], v[140:143], v[172:175], v[40:43]
	v_mfma_f32_16x16x32_bf16 v[28:31], v[132:135], v[180:183], v[28:31]
	v_mfma_f32_16x16x32_bf16 v[24:27], v[140:143], v[180:183], v[24:27]
	v_mfma_f32_16x16x32_bf16 v[12:15], v[132:135], v[204:207], v[12:15]
	v_mfma_f32_16x16x32_bf16 v[8:11], v[140:143], v[204:207], v[8:11]
	v_mfma_f32_16x16x32_bf16 v[52:55], v[144:147], v[160:163], 0
	v_mfma_f32_16x16x32_bf16 v[48:51], v[152:155], v[160:163], 0
	v_mfma_f32_16x16x32_bf16 v[36:39], v[144:147], v[168:171], 0
	v_mfma_f32_16x16x32_bf16 v[32:35], v[152:155], v[168:171], 0
	v_mfma_f32_16x16x32_bf16 v[20:23], v[144:147], v[176:179], 0
	v_mfma_f32_16x16x32_bf16 v[16:19], v[152:155], v[176:179], 0
	v_mfma_f32_16x16x32_bf16 v[4:7], v[144:147], v[200:203], 0
	v_mfma_f32_16x16x32_bf16 v[0:3], v[152:155], v[200:203], 0
	v_mfma_f32_16x16x32_bf16 v[52:55], v[148:151], v[164:167], v[52:55]
	v_mfma_f32_16x16x32_bf16 v[48:51], v[156:159], v[164:167], v[48:51]
	v_mfma_f32_16x16x32_bf16 v[36:39], v[148:151], v[172:175], v[36:39]
	v_mfma_f32_16x16x32_bf16 v[32:35], v[156:159], v[172:175], v[32:35]
	v_mfma_f32_16x16x32_bf16 v[20:23], v[148:151], v[180:183], v[20:23]
	v_mfma_f32_16x16x32_bf16 v[16:19], v[156:159], v[180:183], v[16:19]
	v_mfma_f32_16x16x32_bf16 v[4:7], v[148:151], v[204:207], v[4:7]
	v_mfma_f32_16x16x32_bf16 v[0:3], v[156:159], v[204:207], v[0:3]
	s_barrier
	s_add_i32 s18, 0, 0x18000
	s_add_i32 s21, 0, 0x1c000
	v_add_u32_e32 v140, s18, v223
	v_add_u32_e32 v156, s21, v223
	ds_read_b128 v[128:131], v140
	ds_read_b128 v[132:135], v140 offset:1024
	ds_read_b128 v[136:139], v140 offset:2048
	ds_read_b128 v[140:143], v140 offset:3072
	ds_read_b128 v[144:147], v156
	ds_read_b128 v[148:151], v156 offset:1024
	ds_read_b128 v[152:155], v156 offset:2048
	ds_read_b128 v[156:159], v156 offset:3072
	s_add_u32 s14, s14, s44
	s_addc_u32 s15, s15, 0
	s_mov_b32 m0, s30
	v_lshl_add_u64 v[216:217], s[14:15], 0, v[194:195]
	ds_read_b128 v[160:163], v225 offset:32768
	ds_read_b128 v[164:167], v225 offset:33792
	ds_read_b128 v[168:171], v225 offset:34816
	ds_read_b128 v[172:175], v225 offset:35840
	ds_read_b128 v[176:179], v225 offset:36864
	ds_read_b128 v[180:183], v225 offset:37888
	ds_read_b128 v[200:203], v225 offset:38912
	ds_read_b128 v[204:207], v225 offset:39936
	global_load_lds_dwordx4 v[216:217], off
	v_lshl_add_u64 v[216:217], v[216:217], 0, s[70:71]
	s_mov_b32 m0, s31
	s_nop 0
	global_load_lds_dwordx4 v[216:217], off
	s_waitcnt vmcnt(8)
	s_waitcnt lgkmcnt(0)
	s_barrier
	s_waitcnt lgkmcnt(0)
	v_mfma_f32_16x16x32_bf16 v[124:127], v[128:131], v[160:163], v[124:127]
	v_mfma_f32_16x16x32_bf16 v[120:123], v[136:139], v[160:163], v[120:123]
	v_mfma_f32_16x16x32_bf16 v[108:111], v[128:131], v[168:171], v[108:111]
	v_mfma_f32_16x16x32_bf16 v[104:107], v[136:139], v[168:171], v[104:107]
	v_mfma_f32_16x16x32_bf16 v[92:95], v[128:131], v[176:179], v[92:95]
	v_mfma_f32_16x16x32_bf16 v[88:91], v[136:139], v[176:179], v[88:91]
	v_mfma_f32_16x16x32_bf16 v[76:79], v[128:131], v[200:203], v[76:79]
	v_mfma_f32_16x16x32_bf16 v[72:75], v[136:139], v[200:203], v[72:75]
	v_mfma_f32_16x16x32_bf16 v[124:127], v[132:135], v[164:167], v[124:127]
	v_mfma_f32_16x16x32_bf16 v[120:123], v[140:143], v[164:167], v[120:123]
	v_mfma_f32_16x16x32_bf16 v[108:111], v[132:135], v[172:175], v[108:111]
	v_mfma_f32_16x16x32_bf16 v[104:107], v[140:143], v[172:175], v[104:107]
	v_mfma_f32_16x16x32_bf16 v[92:95], v[132:135], v[180:183], v[92:95]
	v_mfma_f32_16x16x32_bf16 v[88:91], v[140:143], v[180:183], v[88:91]
	v_mfma_f32_16x16x32_bf16 v[76:79], v[132:135], v[204:207], v[76:79]
	v_mfma_f32_16x16x32_bf16 v[72:75], v[140:143], v[204:207], v[72:75]
	v_mfma_f32_16x16x32_bf16 v[116:119], v[144:147], v[160:163], v[116:119]
	v_mfma_f32_16x16x32_bf16 v[112:115], v[152:155], v[160:163], v[112:115]
	v_mfma_f32_16x16x32_bf16 v[100:103], v[144:147], v[168:171], v[100:103]
	v_mfma_f32_16x16x32_bf16 v[96:99], v[152:155], v[168:171], v[96:99]
	v_mfma_f32_16x16x32_bf16 v[84:87], v[144:147], v[176:179], v[84:87]
	v_mfma_f32_16x16x32_bf16 v[80:83], v[152:155], v[176:179], v[80:83]
	v_mfma_f32_16x16x32_bf16 v[68:71], v[144:147], v[200:203], v[68:71]
	v_mfma_f32_16x16x32_bf16 v[64:67], v[152:155], v[200:203], v[64:67]
	v_mfma_f32_16x16x32_bf16 v[116:119], v[148:151], v[164:167], v[116:119]
	v_mfma_f32_16x16x32_bf16 v[112:115], v[156:159], v[164:167], v[112:115]
	v_mfma_f32_16x16x32_bf16 v[100:103], v[148:151], v[172:175], v[100:103]
	v_mfma_f32_16x16x32_bf16 v[96:99], v[156:159], v[172:175], v[96:99]
	v_mfma_f32_16x16x32_bf16 v[84:87], v[148:151], v[180:183], v[84:87]
	v_mfma_f32_16x16x32_bf16 v[80:83], v[156:159], v[180:183], v[80:83]
	v_mfma_f32_16x16x32_bf16 v[68:71], v[148:151], v[204:207], v[68:71]
	v_mfma_f32_16x16x32_bf16 v[64:67], v[156:159], v[204:207], v[64:67]
	s_barrier
	s_add_i32 s14, s18, s27
	v_lshl_add_u64 v[186:187], v[186:187], 0, s[56:57]
	s_mov_b32 m0, s14
	ds_read_b128 v[160:163], v225 offset:49152
	ds_read_b128 v[164:167], v225 offset:50176
	ds_read_b128 v[168:171], v225 offset:51200
	ds_read_b128 v[172:175], v225 offset:52224
	ds_read_b128 v[176:179], v225 offset:53248
	ds_read_b128 v[180:183], v225 offset:54272
	ds_read_b128 v[200:203], v225 offset:55296
	ds_read_b128 v[204:207], v225 offset:56320
	global_load_lds_dwordx4 v[186:187], off
	v_lshl_add_u64 v[186:187], v[188:189], 0, s[56:57]
	s_add_i32 m0, s14, 0x2000
	s_add_i32 s14, s21, s27
	global_load_lds_dwordx4 v[186:187], off
	v_lshl_add_u64 v[186:187], v[208:209], 0, s[56:57]
	s_mov_b32 m0, s14
	s_nop 0
	global_load_lds_dwordx4 v[186:187], off
	v_lshl_add_u64 v[186:187], v[210:211], 0, s[56:57]
	s_add_i32 m0, s14, 0x2000
	s_nop 0
	global_load_lds_dwordx4 v[186:187], off
	v_lshl_add_u64 v[186:187], v[212:213], 0, s[56:57]
	s_mov_b32 m0, s19
	s_nop 0
	global_load_lds_dwordx4 v[186:187], off
	v_lshl_add_u64 v[186:187], v[214:215], 0, s[56:57]
	s_mov_b32 m0, s20
	s_nop 0
	global_load_lds_dwordx4 v[186:187], off
	s_waitcnt vmcnt(8)
	s_waitcnt lgkmcnt(0)
	s_barrier
	s_waitcnt lgkmcnt(0)
	v_mfma_f32_16x16x32_bf16 v[60:63], v[128:131], v[160:163], v[60:63]
	v_mfma_f32_16x16x32_bf16 v[56:59], v[136:139], v[160:163], v[56:59]
	v_mfma_f32_16x16x32_bf16 v[44:47], v[128:131], v[168:171], v[44:47]
	v_mfma_f32_16x16x32_bf16 v[40:43], v[136:139], v[168:171], v[40:43]
	v_mfma_f32_16x16x32_bf16 v[28:31], v[128:131], v[176:179], v[28:31]
	v_mfma_f32_16x16x32_bf16 v[24:27], v[136:139], v[176:179], v[24:27]
	v_mfma_f32_16x16x32_bf16 v[12:15], v[128:131], v[200:203], v[12:15]
	v_mfma_f32_16x16x32_bf16 v[8:11], v[136:139], v[200:203], v[8:11]
	v_mfma_f32_16x16x32_bf16 v[60:63], v[132:135], v[164:167], v[60:63]
	v_mfma_f32_16x16x32_bf16 v[56:59], v[140:143], v[164:167], v[56:59]
	v_mfma_f32_16x16x32_bf16 v[44:47], v[132:135], v[172:175], v[44:47]
	v_mfma_f32_16x16x32_bf16 v[40:43], v[140:143], v[172:175], v[40:43]
	v_mfma_f32_16x16x32_bf16 v[28:31], v[132:135], v[180:183], v[28:31]
	v_mfma_f32_16x16x32_bf16 v[24:27], v[140:143], v[180:183], v[24:27]
	v_mfma_f32_16x16x32_bf16 v[12:15], v[132:135], v[204:207], v[12:15]
	v_mfma_f32_16x16x32_bf16 v[8:11], v[140:143], v[204:207], v[8:11]
	v_mfma_f32_16x16x32_bf16 v[52:55], v[144:147], v[160:163], v[52:55]
	v_mfma_f32_16x16x32_bf16 v[48:51], v[152:155], v[160:163], v[48:51]
	v_mfma_f32_16x16x32_bf16 v[36:39], v[144:147], v[168:171], v[36:39]
	v_mfma_f32_16x16x32_bf16 v[32:35], v[152:155], v[168:171], v[32:35]
	v_mfma_f32_16x16x32_bf16 v[20:23], v[144:147], v[176:179], v[20:23]
	v_mfma_f32_16x16x32_bf16 v[16:19], v[152:155], v[176:179], v[16:19]
	v_mfma_f32_16x16x32_bf16 v[4:7], v[144:147], v[200:203], v[4:7]
	v_mfma_f32_16x16x32_bf16 v[0:3], v[152:155], v[200:203], v[0:3]
	v_mfma_f32_16x16x32_bf16 v[52:55], v[148:151], v[164:167], v[52:55]
	v_mfma_f32_16x16x32_bf16 v[48:51], v[156:159], v[164:167], v[48:51]
	v_mfma_f32_16x16x32_bf16 v[36:39], v[148:151], v[172:175], v[36:39]
	v_mfma_f32_16x16x32_bf16 v[32:35], v[156:159], v[172:175], v[32:35]
	v_mfma_f32_16x16x32_bf16 v[20:23], v[148:151], v[180:183], v[20:23]
	v_mfma_f32_16x16x32_bf16 v[16:19], v[156:159], v[180:183], v[16:19]
	v_mfma_f32_16x16x32_bf16 v[4:7], v[148:151], v[204:207], v[4:7]
	v_mfma_f32_16x16x32_bf16 v[0:3], v[156:159], v[204:207], v[0:3]
	s_barrier
	s_add_u32 vcc_lo, vcc_lo, 0x100
	s_addc_u32 vcc_hi, vcc_hi, 0
	s_add_u32 s16, s16, 0x100
	s_addc_u32 s17, s17, 0
	s_cmp_ge_u32 s24, s84
	s_mov_b32 s14, s24
.LBB0_362:
	s_add_i32 s24, s14, 2
	s_add_u32 s46, vcc_lo, 0x80
	s_addc_u32 s15, vcc_hi, 0
	s_add_i32 s18, 0, 0x10000
	s_cmp_eq_u32 s6, s14
	s_cselect_b32 s15, s1, s15
	s_cselect_b32 s14, s0, s46
	s_cselect_b32 s47, s13, s17
	s_cselect_b32 s46, s12, s16
	s_add_i32 s21, 0, 0x14000
	v_add_u32_e32 v140, s18, v223
	v_add_u32_e32 v156, s21, v223
	s_waitcnt lgkmcnt(0)
	ds_read_b128 v[128:131], v140
	ds_read_b128 v[132:135], v140 offset:1024
	ds_read_b128 v[136:139], v140 offset:2048
	ds_read_b128 v[140:143], v140 offset:3072
	ds_read_b128 v[144:147], v156
	ds_read_b128 v[148:151], v156 offset:1024
	ds_read_b128 v[152:155], v156 offset:2048
	ds_read_b128 v[156:159], v156 offset:3072
	v_lshl_add_u64 v[186:187], vcc, 0, v[196:197]
	s_add_i32 m0, s28, 0xc000
	ds_read_b128 v[160:163], v225
	ds_read_b128 v[164:167], v225 offset:1024
	ds_read_b128 v[168:171], v225 offset:2048
	ds_read_b128 v[172:175], v225 offset:3072
	ds_read_b128 v[176:179], v225 offset:4096
	ds_read_b128 v[180:183], v225 offset:5120
	ds_read_b128 v[200:203], v225 offset:6144
	ds_read_b128 v[204:207], v225 offset:7168
	global_load_lds_dwordx4 v[186:187], off
	v_lshl_add_u64 v[186:187], vcc, 0, v[198:199]
	s_add_i32 m0, s28, 0xe000
	s_nop 0
	global_load_lds_dwordx4 v[186:187], off
	s_waitcnt vmcnt(8)
	s_waitcnt lgkmcnt(0)
	s_barrier
	s_waitcnt lgkmcnt(0)
	v_mfma_f32_16x16x32_bf16 v[124:127], v[128:131], v[160:163], v[124:127]
	v_mfma_f32_16x16x32_bf16 v[120:123], v[136:139], v[160:163], v[120:123]
	v_mfma_f32_16x16x32_bf16 v[108:111], v[128:131], v[168:171], v[108:111]
	v_mfma_f32_16x16x32_bf16 v[104:107], v[136:139], v[168:171], v[104:107]
	v_mfma_f32_16x16x32_bf16 v[92:95], v[128:131], v[176:179], v[92:95]
	v_mfma_f32_16x16x32_bf16 v[88:91], v[136:139], v[176:179], v[88:91]
	v_mfma_f32_16x16x32_bf16 v[76:79], v[128:131], v[200:203], v[76:79]
	v_mfma_f32_16x16x32_bf16 v[72:75], v[136:139], v[200:203], v[72:75]
	v_mfma_f32_16x16x32_bf16 v[124:127], v[132:135], v[164:167], v[124:127]
	v_mfma_f32_16x16x32_bf16 v[120:123], v[140:143], v[164:167], v[120:123]
	v_mfma_f32_16x16x32_bf16 v[108:111], v[132:135], v[172:175], v[108:111]
	v_mfma_f32_16x16x32_bf16 v[104:107], v[140:143], v[172:175], v[104:107]
	v_mfma_f32_16x16x32_bf16 v[92:95], v[132:135], v[180:183], v[92:95]
	v_mfma_f32_16x16x32_bf16 v[88:91], v[140:143], v[180:183], v[88:91]
	v_mfma_f32_16x16x32_bf16 v[76:79], v[132:135], v[204:207], v[76:79]
	v_mfma_f32_16x16x32_bf16 v[72:75], v[140:143], v[204:207], v[72:75]
	v_mfma_f32_16x16x32_bf16 v[116:119], v[144:147], v[160:163], v[116:119]
	v_mfma_f32_16x16x32_bf16 v[112:115], v[152:155], v[160:163], v[112:115]
	v_mfma_f32_16x16x32_bf16 v[100:103], v[144:147], v[168:171], v[100:103]
	v_mfma_f32_16x16x32_bf16 v[96:99], v[152:155], v[168:171], v[96:99]
	v_mfma_f32_16x16x32_bf16 v[84:87], v[144:147], v[176:179], v[84:87]
	v_mfma_f32_16x16x32_bf16 v[80:83], v[152:155], v[176:179], v[80:83]
	v_mfma_f32_16x16x32_bf16 v[68:71], v[144:147], v[200:203], v[68:71]
	v_mfma_f32_16x16x32_bf16 v[64:67], v[152:155], v[200:203], v[64:67]
	v_mfma_f32_16x16x32_bf16 v[116:119], v[148:151], v[164:167], v[116:119]
	v_mfma_f32_16x16x32_bf16 v[112:115], v[156:159], v[164:167], v[112:115]
	v_mfma_f32_16x16x32_bf16 v[100:103], v[148:151], v[172:175], v[100:103]
	v_mfma_f32_16x16x32_bf16 v[96:99], v[156:159], v[172:175], v[96:99]
	v_mfma_f32_16x16x32_bf16 v[84:87], v[148:151], v[180:183], v[84:87]
	v_mfma_f32_16x16x32_bf16 v[80:83], v[156:159], v[180:183], v[80:83]
	v_mfma_f32_16x16x32_bf16 v[68:71], v[148:151], v[204:207], v[68:71]
	v_mfma_f32_16x16x32_bf16 v[64:67], v[156:159], v[204:207], v[64:67]
	s_barrier
	s_add_i32 s18, s18, s27
	v_lshl_add_u64 v[186:187], s[46:47], 0, v[184:185]
	s_mov_b32 m0, s18
	ds_read_b128 v[160:163], v225 offset:16384
	ds_read_b128 v[164:167], v225 offset:17408
	ds_read_b128 v[168:171], v225 offset:18432
	ds_read_b128 v[172:175], v225 offset:19456
	ds_read_b128 v[176:179], v225 offset:20480
	ds_read_b128 v[180:183], v225 offset:21504
	ds_read_b128 v[200:203], v225 offset:22528
	ds_read_b128 v[204:207], v225 offset:23552
	global_load_lds_dwordx4 v[186:187], off
	s_add_i32 m0, s18, 0x2000
	s_add_u32 s46, s46, s44
	v_lshl_add_u64 v[188:189], v[186:187], 0, s[70:71]
	s_addc_u32 s47, s47, 0
	s_add_i32 s18, s21, s27
	global_load_lds_dwordx4 v[188:189], off
	v_lshl_add_u64 v[208:209], s[46:47], 0, v[184:185]
	s_mov_b32 m0, s18
	v_lshl_add_u64 v[210:211], v[208:209], 0, s[70:71]
	global_load_lds_dwordx4 v[208:209], off
	s_add_i32 m0, s18, 0x2000
	v_lshl_add_u64 v[212:213], s[14:15], 0, v[194:195]
	global_load_lds_dwordx4 v[210:211], off
	s_mov_b32 m0, s28
	v_lshl_add_u64 v[214:215], v[212:213], 0, s[70:71]
	global_load_lds_dwordx4 v[212:213], off
	s_mov_b32 m0, s29
	s_nop 0
	global_load_lds_dwordx4 v[214:215], off
	s_waitcnt vmcnt(8)
	s_waitcnt lgkmcnt(0)
	s_barrier
	s_waitcnt lgkmcnt(0)
	v_mfma_f32_16x16x32_bf16 v[60:63], v[128:131], v[160:163], v[60:63]
	v_mfma_f32_16x16x32_bf16 v[56:59], v[136:139], v[160:163], v[56:59]
	v_mfma_f32_16x16x32_bf16 v[44:47], v[128:131], v[168:171], v[44:47]
	v_mfma_f32_16x16x32_bf16 v[40:43], v[136:139], v[168:171], v[40:43]
	v_mfma_f32_16x16x32_bf16 v[28:31], v[128:131], v[176:179], v[28:31]
	v_mfma_f32_16x16x32_bf16 v[24:27], v[136:139], v[176:179], v[24:27]
	v_mfma_f32_16x16x32_bf16 v[12:15], v[128:131], v[200:203], v[12:15]
	v_mfma_f32_16x16x32_bf16 v[8:11], v[136:139], v[200:203], v[8:11]
	v_mfma_f32_16x16x32_bf16 v[60:63], v[132:135], v[164:167], v[60:63]
	v_mfma_f32_16x16x32_bf16 v[56:59], v[140:143], v[164:167], v[56:59]
	v_mfma_f32_16x16x32_bf16 v[44:47], v[132:135], v[172:175], v[44:47]
	v_mfma_f32_16x16x32_bf16 v[40:43], v[140:143], v[172:175], v[40:43]
	v_mfma_f32_16x16x32_bf16 v[28:31], v[132:135], v[180:183], v[28:31]
	v_mfma_f32_16x16x32_bf16 v[24:27], v[140:143], v[180:183], v[24:27]
	v_mfma_f32_16x16x32_bf16 v[12:15], v[132:135], v[204:207], v[12:15]
	v_mfma_f32_16x16x32_bf16 v[8:11], v[140:143], v[204:207], v[8:11]
	v_mfma_f32_16x16x32_bf16 v[52:55], v[144:147], v[160:163], v[52:55]
	v_mfma_f32_16x16x32_bf16 v[48:51], v[152:155], v[160:163], v[48:51]
	v_mfma_f32_16x16x32_bf16 v[36:39], v[144:147], v[168:171], v[36:39]
	v_mfma_f32_16x16x32_bf16 v[32:35], v[152:155], v[168:171], v[32:35]
	v_mfma_f32_16x16x32_bf16 v[20:23], v[144:147], v[176:179], v[20:23]
	v_mfma_f32_16x16x32_bf16 v[16:19], v[152:155], v[176:179], v[16:19]
	v_mfma_f32_16x16x32_bf16 v[4:7], v[144:147], v[200:203], v[4:7]
	v_mfma_f32_16x16x32_bf16 v[0:3], v[152:155], v[200:203], v[0:3]
	v_mfma_f32_16x16x32_bf16 v[52:55], v[148:151], v[164:167], v[52:55]
	v_mfma_f32_16x16x32_bf16 v[48:51], v[156:159], v[164:167], v[48:51]
	v_mfma_f32_16x16x32_bf16 v[36:39], v[148:151], v[172:175], v[36:39]
	v_mfma_f32_16x16x32_bf16 v[32:35], v[156:159], v[172:175], v[32:35]
	v_mfma_f32_16x16x32_bf16 v[20:23], v[148:151], v[180:183], v[20:23]
	v_mfma_f32_16x16x32_bf16 v[16:19], v[156:159], v[180:183], v[16:19]
	v_mfma_f32_16x16x32_bf16 v[4:7], v[148:151], v[204:207], v[4:7]
	v_mfma_f32_16x16x32_bf16 v[0:3], v[156:159], v[204:207], v[0:3]
	s_barrier
	s_add_i32 s18, 0, 0x18000
	s_add_i32 s21, 0, 0x1c000
	v_add_u32_e32 v140, s18, v223
	v_add_u32_e32 v156, s21, v223
	ds_read_b128 v[128:131], v140
	ds_read_b128 v[132:135], v140 offset:1024
	ds_read_b128 v[136:139], v140 offset:2048
	ds_read_b128 v[140:143], v140 offset:3072
	ds_read_b128 v[144:147], v156
	ds_read_b128 v[148:151], v156 offset:1024
	ds_read_b128 v[152:155], v156 offset:2048
	ds_read_b128 v[156:159], v156 offset:3072
	s_add_u32 s14, s14, s44
	s_addc_u32 s15, s15, 0
	s_mov_b32 m0, s30
	v_lshl_add_u64 v[216:217], s[14:15], 0, v[194:195]
	ds_read_b128 v[160:163], v225 offset:32768
	ds_read_b128 v[164:167], v225 offset:33792
	ds_read_b128 v[168:171], v225 offset:34816
	ds_read_b128 v[172:175], v225 offset:35840
	ds_read_b128 v[176:179], v225 offset:36864
	ds_read_b128 v[180:183], v225 offset:37888
	ds_read_b128 v[200:203], v225 offset:38912
	ds_read_b128 v[204:207], v225 offset:39936
	global_load_lds_dwordx4 v[216:217], off
	v_lshl_add_u64 v[216:217], v[216:217], 0, s[70:71]
	s_mov_b32 m0, s31
	s_nop 0
	global_load_lds_dwordx4 v[216:217], off
	s_waitcnt vmcnt(8)
	s_waitcnt lgkmcnt(0)
	s_barrier
	s_waitcnt lgkmcnt(0)
	v_mfma_f32_16x16x32_bf16 v[124:127], v[128:131], v[160:163], v[124:127]
	v_mfma_f32_16x16x32_bf16 v[120:123], v[136:139], v[160:163], v[120:123]
	v_mfma_f32_16x16x32_bf16 v[108:111], v[128:131], v[168:171], v[108:111]
	v_mfma_f32_16x16x32_bf16 v[104:107], v[136:139], v[168:171], v[104:107]
	v_mfma_f32_16x16x32_bf16 v[92:95], v[128:131], v[176:179], v[92:95]
	v_mfma_f32_16x16x32_bf16 v[88:91], v[136:139], v[176:179], v[88:91]
	v_mfma_f32_16x16x32_bf16 v[76:79], v[128:131], v[200:203], v[76:79]
	v_mfma_f32_16x16x32_bf16 v[72:75], v[136:139], v[200:203], v[72:75]
	v_mfma_f32_16x16x32_bf16 v[124:127], v[132:135], v[164:167], v[124:127]
	v_mfma_f32_16x16x32_bf16 v[120:123], v[140:143], v[164:167], v[120:123]
	v_mfma_f32_16x16x32_bf16 v[108:111], v[132:135], v[172:175], v[108:111]
	v_mfma_f32_16x16x32_bf16 v[104:107], v[140:143], v[172:175], v[104:107]
	v_mfma_f32_16x16x32_bf16 v[92:95], v[132:135], v[180:183], v[92:95]
	v_mfma_f32_16x16x32_bf16 v[88:91], v[140:143], v[180:183], v[88:91]
	v_mfma_f32_16x16x32_bf16 v[76:79], v[132:135], v[204:207], v[76:79]
	v_mfma_f32_16x16x32_bf16 v[72:75], v[140:143], v[204:207], v[72:75]
	v_mfma_f32_16x16x32_bf16 v[116:119], v[144:147], v[160:163], v[116:119]
	v_mfma_f32_16x16x32_bf16 v[112:115], v[152:155], v[160:163], v[112:115]
	v_mfma_f32_16x16x32_bf16 v[100:103], v[144:147], v[168:171], v[100:103]
	v_mfma_f32_16x16x32_bf16 v[96:99], v[152:155], v[168:171], v[96:99]
	v_mfma_f32_16x16x32_bf16 v[84:87], v[144:147], v[176:179], v[84:87]
	v_mfma_f32_16x16x32_bf16 v[80:83], v[152:155], v[176:179], v[80:83]
	v_mfma_f32_16x16x32_bf16 v[68:71], v[144:147], v[200:203], v[68:71]
	v_mfma_f32_16x16x32_bf16 v[64:67], v[152:155], v[200:203], v[64:67]
	v_mfma_f32_16x16x32_bf16 v[116:119], v[148:151], v[164:167], v[116:119]
	v_mfma_f32_16x16x32_bf16 v[112:115], v[156:159], v[164:167], v[112:115]
	v_mfma_f32_16x16x32_bf16 v[100:103], v[148:151], v[172:175], v[100:103]
	v_mfma_f32_16x16x32_bf16 v[96:99], v[156:159], v[172:175], v[96:99]
	v_mfma_f32_16x16x32_bf16 v[84:87], v[148:151], v[180:183], v[84:87]
	v_mfma_f32_16x16x32_bf16 v[80:83], v[156:159], v[180:183], v[80:83]
	v_mfma_f32_16x16x32_bf16 v[68:71], v[148:151], v[204:207], v[68:71]
	v_mfma_f32_16x16x32_bf16 v[64:67], v[156:159], v[204:207], v[64:67]
	s_barrier
	s_add_i32 s14, s18, s27
	v_lshl_add_u64 v[186:187], v[186:187], 0, s[56:57]
	s_mov_b32 m0, s14
	ds_read_b128 v[160:163], v225 offset:49152
	ds_read_b128 v[164:167], v225 offset:50176
	ds_read_b128 v[168:171], v225 offset:51200
	ds_read_b128 v[172:175], v225 offset:52224
	ds_read_b128 v[176:179], v225 offset:53248
	ds_read_b128 v[180:183], v225 offset:54272
	ds_read_b128 v[200:203], v225 offset:55296
	ds_read_b128 v[204:207], v225 offset:56320
	global_load_lds_dwordx4 v[186:187], off
	v_lshl_add_u64 v[186:187], v[188:189], 0, s[56:57]
	s_add_i32 m0, s14, 0x2000
	s_add_i32 s14, s21, s27
	global_load_lds_dwordx4 v[186:187], off
	v_lshl_add_u64 v[186:187], v[208:209], 0, s[56:57]
	s_mov_b32 m0, s14
	s_nop 0
	global_load_lds_dwordx4 v[186:187], off
	v_lshl_add_u64 v[186:187], v[210:211], 0, s[56:57]
	s_add_i32 m0, s14, 0x2000
	s_nop 0
	global_load_lds_dwordx4 v[186:187], off
	v_lshl_add_u64 v[186:187], v[212:213], 0, s[56:57]
	s_mov_b32 m0, s19
	s_nop 0
	global_load_lds_dwordx4 v[186:187], off
	v_lshl_add_u64 v[186:187], v[214:215], 0, s[56:57]
	s_mov_b32 m0, s20
	s_nop 0
	global_load_lds_dwordx4 v[186:187], off
	s_waitcnt vmcnt(8)
	s_waitcnt lgkmcnt(0)
	s_barrier
	s_waitcnt lgkmcnt(0)
	v_mfma_f32_16x16x32_bf16 v[60:63], v[128:131], v[160:163], v[60:63]
	v_mfma_f32_16x16x32_bf16 v[56:59], v[136:139], v[160:163], v[56:59]
	v_mfma_f32_16x16x32_bf16 v[44:47], v[128:131], v[168:171], v[44:47]
	v_mfma_f32_16x16x32_bf16 v[40:43], v[136:139], v[168:171], v[40:43]
	v_mfma_f32_16x16x32_bf16 v[28:31], v[128:131], v[176:179], v[28:31]
	v_mfma_f32_16x16x32_bf16 v[24:27], v[136:139], v[176:179], v[24:27]
	v_mfma_f32_16x16x32_bf16 v[12:15], v[128:131], v[200:203], v[12:15]
	v_mfma_f32_16x16x32_bf16 v[8:11], v[136:139], v[200:203], v[8:11]
	v_mfma_f32_16x16x32_bf16 v[60:63], v[132:135], v[164:167], v[60:63]
	v_mfma_f32_16x16x32_bf16 v[56:59], v[140:143], v[164:167], v[56:59]
	v_mfma_f32_16x16x32_bf16 v[44:47], v[132:135], v[172:175], v[44:47]
	v_mfma_f32_16x16x32_bf16 v[40:43], v[140:143], v[172:175], v[40:43]
	v_mfma_f32_16x16x32_bf16 v[28:31], v[132:135], v[180:183], v[28:31]
	v_mfma_f32_16x16x32_bf16 v[24:27], v[140:143], v[180:183], v[24:27]
	v_mfma_f32_16x16x32_bf16 v[12:15], v[132:135], v[204:207], v[12:15]
	v_mfma_f32_16x16x32_bf16 v[8:11], v[140:143], v[204:207], v[8:11]
	v_mfma_f32_16x16x32_bf16 v[52:55], v[144:147], v[160:163], v[52:55]
	v_mfma_f32_16x16x32_bf16 v[48:51], v[152:155], v[160:163], v[48:51]
	v_mfma_f32_16x16x32_bf16 v[36:39], v[144:147], v[168:171], v[36:39]
	v_mfma_f32_16x16x32_bf16 v[32:35], v[152:155], v[168:171], v[32:35]
	v_mfma_f32_16x16x32_bf16 v[20:23], v[144:147], v[176:179], v[20:23]
	v_mfma_f32_16x16x32_bf16 v[16:19], v[152:155], v[176:179], v[16:19]
	v_mfma_f32_16x16x32_bf16 v[4:7], v[144:147], v[200:203], v[4:7]
	v_mfma_f32_16x16x32_bf16 v[0:3], v[152:155], v[200:203], v[0:3]
	v_mfma_f32_16x16x32_bf16 v[52:55], v[148:151], v[164:167], v[52:55]
	v_mfma_f32_16x16x32_bf16 v[48:51], v[156:159], v[164:167], v[48:51]
	v_mfma_f32_16x16x32_bf16 v[36:39], v[148:151], v[172:175], v[36:39]
	v_mfma_f32_16x16x32_bf16 v[32:35], v[156:159], v[172:175], v[32:35]
	v_mfma_f32_16x16x32_bf16 v[20:23], v[148:151], v[180:183], v[20:23]
	v_mfma_f32_16x16x32_bf16 v[16:19], v[156:159], v[180:183], v[16:19]
	v_mfma_f32_16x16x32_bf16 v[4:7], v[148:151], v[204:207], v[4:7]
	v_mfma_f32_16x16x32_bf16 v[0:3], v[156:159], v[204:207], v[0:3]
	s_barrier
	s_add_u32 vcc_lo, vcc_lo, 0x100
	s_addc_u32 vcc_hi, vcc_hi, 0
	s_add_u32 s16, s16, 0x100
	s_addc_u32 s17, s17, 0
	s_cmp_ge_u32 s24, s84
	s_mov_b32 s14, s24
	s_cbranch_scc0 .LBB0_362
	s_and_b64 vcc, exec, s[60:61]
	s_cbranch_vccz .LBB0_365
	s_barrier

.LBB0_421:
	s_add_u32 s44, s16, 0x80
	s_addc_u32 s45, s17, 0
	s_add_u32 s16, s14, 0x100
	s_addc_u32 s17, s15, 0
	s_mov_b32 s14, 0
	s_waitcnt lgkmcnt(0)
	s_add_i32 s23, s14, 2
	s_add_u32 s24, s44, 0x80
	s_addc_u32 s15, s45, 0
	s_add_i32 s49, 0, 0x10000
	s_cmp_eq_u32 s31, s14
	s_cselect_b32 s15, s1, s15
	s_cselect_b32 s14, s0, s24
	s_cselect_b32 s51, s43, s17
	s_cselect_b32 s50, s42, s16
	s_add_i32 s24, 0, 0x14000
	v_add_u32_e32 v108, s49, v249
	v_add_u32_e32 v140, s24, v249
	ds_read_b128 v[80:83], v108
	ds_read_b128 v[84:87], v108 offset:1024
	ds_read_b128 v[104:107], v108 offset:2048
	ds_read_b128 v[108:111], v108 offset:3072
	ds_read_b128 v[124:127], v140
	ds_read_b128 v[132:135], v140 offset:1024
	ds_read_b128 v[136:139], v140 offset:2048
	ds_read_b128 v[140:143], v140 offset:3072
	v_lshl_add_u64 v[208:209], s[44:45], 0, v[196:197]
	s_add_i32 m0, s20, 0xc000
	ds_read_b128 v[144:147], v251
	ds_read_b128 v[148:151], v251 offset:1024
	ds_read_b128 v[152:155], v251 offset:2048
	ds_read_b128 v[156:159], v251 offset:3072
	ds_read_b128 v[160:163], v251 offset:4096
	ds_read_b128 v[164:167], v251 offset:5120
	ds_read_b128 v[200:203], v251 offset:6144
	ds_read_b128 v[204:207], v251 offset:7168
	global_load_lds_dwordx4 v[208:209], off
	v_lshl_add_u64 v[208:209], s[44:45], 0, v[198:199]
	s_add_i32 m0, s20, 0xe000
	s_nop 0
	global_load_lds_dwordx4 v[208:209], off
	s_waitcnt vmcnt(8)
	s_waitcnt lgkmcnt(0)
	s_barrier
	s_waitcnt lgkmcnt(0)
	v_mfma_f32_16x16x32_bf16 v[180:183], v[80:83], v[144:147], 0
	v_mfma_f32_16x16x32_bf16 v[176:179], v[104:107], v[144:147], 0
	v_mfma_f32_16x16x32_bf16 v[128:131], v[80:83], v[152:155], 0
	v_mfma_f32_16x16x32_bf16 v[120:123], v[104:107], v[152:155], 0
	v_mfma_f32_16x16x32_bf16 v[100:103], v[80:83], v[160:163], 0
	v_mfma_f32_16x16x32_bf16 v[96:99], v[104:107], v[160:163], 0
	v_mfma_f32_16x16x32_bf16 v[76:79], v[80:83], v[200:203], 0
	v_mfma_f32_16x16x32_bf16 v[72:75], v[104:107], v[200:203], 0
	v_mfma_f32_16x16x32_bf16 v[180:183], v[84:87], v[148:151], v[180:183]
	v_mfma_f32_16x16x32_bf16 v[176:179], v[108:111], v[148:151], v[176:179]
	v_mfma_f32_16x16x32_bf16 v[128:131], v[84:87], v[156:159], v[128:131]
	v_mfma_f32_16x16x32_bf16 v[120:123], v[108:111], v[156:159], v[120:123]
	v_mfma_f32_16x16x32_bf16 v[100:103], v[84:87], v[164:167], v[100:103]
	v_mfma_f32_16x16x32_bf16 v[96:99], v[108:111], v[164:167], v[96:99]
	v_mfma_f32_16x16x32_bf16 v[76:79], v[84:87], v[204:207], v[76:79]
	v_mfma_f32_16x16x32_bf16 v[72:75], v[108:111], v[204:207], v[72:75]
	v_mfma_f32_16x16x32_bf16 v[172:175], v[124:127], v[144:147], 0
	v_mfma_f32_16x16x32_bf16 v[116:119], v[124:127], v[152:155], 0
	v_mfma_f32_16x16x32_bf16 v[112:115], v[136:139], v[152:155], 0
	v_mfma_f32_16x16x32_bf16 v[92:95], v[124:127], v[160:163], 0
	v_mfma_f32_16x16x32_bf16 v[88:91], v[136:139], v[160:163], 0
	v_mfma_f32_16x16x32_bf16 v[68:71], v[124:127], v[200:203], 0
	v_mfma_f32_16x16x32_bf16 v[64:67], v[136:139], v[200:203], 0
	v_mfma_f32_16x16x32_bf16 v[172:175], v[132:135], v[148:151], v[172:175]
	v_mfma_f32_16x16x32_bf16 v[144:147], v[136:139], v[144:147], 0
	v_mfma_f32_16x16x32_bf16 v[116:119], v[132:135], v[156:159], v[116:119]
	v_mfma_f32_16x16x32_bf16 v[112:115], v[140:143], v[156:159], v[112:115]
	v_mfma_f32_16x16x32_bf16 v[92:95], v[132:135], v[164:167], v[92:95]
	v_mfma_f32_16x16x32_bf16 v[88:91], v[140:143], v[164:167], v[88:91]
	v_mfma_f32_16x16x32_bf16 v[68:71], v[132:135], v[204:207], v[68:71]
	v_mfma_f32_16x16x32_bf16 v[64:67], v[140:143], v[204:207], v[64:67]
	v_mfma_f32_16x16x32_bf16 v[144:147], v[140:143], v[148:151], v[144:147]
	s_barrier
	s_add_i32 s49, s49, s19
	v_lshl_add_u64 v[212:213], s[50:51], 0, v[184:185]
	s_mov_b32 m0, s49
	ds_read_b128 v[148:151], v251 offset:16384
	ds_read_b128 v[152:155], v251 offset:17408
	ds_read_b128 v[156:159], v251 offset:18432
	ds_read_b128 v[160:163], v251 offset:19456
	ds_read_b128 v[164:167], v251 offset:20480
	ds_read_b128 v[168:171], v251 offset:21504
	ds_read_b128 v[200:203], v251 offset:22528
	ds_read_b128 v[204:207], v251 offset:23552
	global_load_lds_dwordx4 v[212:213], off
	s_add_i32 m0, s49, 0x2000
	s_add_u32 s50, s50, s8
	v_lshl_add_u64 v[214:215], v[212:213], 0, s[70:71]
	s_addc_u32 s51, s51, 0
	s_add_i32 s24, s24, s19
	global_load_lds_dwordx4 v[214:215], off
	v_lshl_add_u64 v[216:217], s[50:51], 0, v[184:185]
	s_mov_b32 m0, s24
	v_lshl_add_u64 v[218:219], v[216:217], 0, s[70:71]
	global_load_lds_dwordx4 v[216:217], off
	s_add_i32 m0, s24, 0x2000
	v_lshl_add_u64 v[220:221], s[14:15], 0, v[194:195]
	global_load_lds_dwordx4 v[218:219], off
	s_mov_b32 m0, s20
	v_lshl_add_u64 v[222:223], v[220:221], 0, s[70:71]
	global_load_lds_dwordx4 v[220:221], off
	s_mov_b32 m0, s25
	s_nop 0
	global_load_lds_dwordx4 v[222:223], off
	s_waitcnt vmcnt(8)
	s_waitcnt lgkmcnt(0)
	s_barrier
	s_waitcnt lgkmcnt(0)
	v_mfma_f32_16x16x32_bf16 v[60:63], v[80:83], v[148:151], 0
	v_mfma_f32_16x16x32_bf16 v[56:59], v[104:107], v[148:151], 0
	v_mfma_f32_16x16x32_bf16 v[44:47], v[80:83], v[156:159], 0
	v_mfma_f32_16x16x32_bf16 v[40:43], v[104:107], v[156:159], 0
	v_mfma_f32_16x16x32_bf16 v[28:31], v[80:83], v[164:167], 0
	v_mfma_f32_16x16x32_bf16 v[24:27], v[104:107], v[164:167], 0
	v_mfma_f32_16x16x32_bf16 v[12:15], v[80:83], v[200:203], 0
	v_mfma_f32_16x16x32_bf16 v[8:11], v[104:107], v[200:203], 0
	v_mfma_f32_16x16x32_bf16 v[60:63], v[84:87], v[152:155], v[60:63]
	v_mfma_f32_16x16x32_bf16 v[56:59], v[108:111], v[152:155], v[56:59]
	v_mfma_f32_16x16x32_bf16 v[44:47], v[84:87], v[160:163], v[44:47]
	v_mfma_f32_16x16x32_bf16 v[40:43], v[108:111], v[160:163], v[40:43]
	v_mfma_f32_16x16x32_bf16 v[28:31], v[84:87], v[168:171], v[28:31]
	v_mfma_f32_16x16x32_bf16 v[24:27], v[108:111], v[168:171], v[24:27]
	v_mfma_f32_16x16x32_bf16 v[12:15], v[84:87], v[204:207], v[12:15]
	v_mfma_f32_16x16x32_bf16 v[8:11], v[108:111], v[204:207], v[8:11]
	v_mfma_f32_16x16x32_bf16 v[52:55], v[124:127], v[148:151], 0
	v_mfma_f32_16x16x32_bf16 v[48:51], v[136:139], v[148:151], 0
	v_mfma_f32_16x16x32_bf16 v[36:39], v[124:127], v[156:159], 0
	v_mfma_f32_16x16x32_bf16 v[32:35], v[136:139], v[156:159], 0
	v_mfma_f32_16x16x32_bf16 v[20:23], v[124:127], v[164:167], 0
	v_mfma_f32_16x16x32_bf16 v[16:19], v[136:139], v[164:167], 0
	v_mfma_f32_16x16x32_bf16 v[4:7], v[124:127], v[200:203], 0
	v_mfma_f32_16x16x32_bf16 v[0:3], v[136:139], v[200:203], 0
	v_mfma_f32_16x16x32_bf16 v[52:55], v[132:135], v[152:155], v[52:55]
	v_mfma_f32_16x16x32_bf16 v[48:51], v[140:143], v[152:155], v[48:51]
	v_mfma_f32_16x16x32_bf16 v[36:39], v[132:135], v[160:163], v[36:39]
	v_mfma_f32_16x16x32_bf16 v[32:35], v[140:143], v[160:163], v[32:35]
	v_mfma_f32_16x16x32_bf16 v[20:23], v[132:135], v[168:171], v[20:23]
	v_mfma_f32_16x16x32_bf16 v[16:19], v[140:143], v[168:171], v[16:19]
	v_mfma_f32_16x16x32_bf16 v[4:7], v[132:135], v[204:207], v[4:7]
	v_mfma_f32_16x16x32_bf16 v[0:3], v[140:143], v[204:207], v[0:3]
	s_barrier
	s_add_i32 s24, 0, 0x18000
	s_add_i32 s49, 0, 0x1c000
	v_add_u32_e32 v108, s24, v249
	v_add_u32_e32 v140, s49, v249
	ds_read_b128 v[80:83], v108
	ds_read_b128 v[84:87], v108 offset:1024
	ds_read_b128 v[104:107], v108 offset:2048
	ds_read_b128 v[108:111], v108 offset:3072
	ds_read_b128 v[124:127], v140
	ds_read_b128 v[132:135], v140 offset:1024
	ds_read_b128 v[136:139], v140 offset:2048
	ds_read_b128 v[140:143], v140 offset:3072
	s_add_u32 s14, s14, s8
	s_addc_u32 s15, s15, 0
	s_mov_b32 m0, s26
	v_lshl_add_u64 v[168:169], s[14:15], 0, v[194:195]
	ds_read_b128 v[148:151], v251 offset:32768
	ds_read_b128 v[152:155], v251 offset:33792
	ds_read_b128 v[156:159], v251 offset:34816
	ds_read_b128 v[160:163], v251 offset:35840
	ds_read_b128 v[164:167], v251 offset:36864
	ds_read_b128 v[200:203], v251 offset:37888
	ds_read_b128 v[204:207], v251 offset:38912
	ds_read_b128 v[208:211], v251 offset:39936
	global_load_lds_dwordx4 v[168:169], off
	v_lshl_add_u64 v[168:169], v[168:169], 0, s[70:71]
	s_mov_b32 m0, s27
	s_nop 0
	global_load_lds_dwordx4 v[168:169], off
	s_waitcnt vmcnt(8)
	s_waitcnt lgkmcnt(0)
	s_barrier
	s_waitcnt lgkmcnt(0)
	v_mfma_f32_16x16x32_bf16 v[168:171], v[80:83], v[148:151], v[180:183]
	v_mfma_f32_16x16x32_bf16 v[180:183], v[84:87], v[152:155], v[168:171]
	v_mfma_f32_16x16x32_bf16 v[168:171], v[104:107], v[148:151], v[176:179]
	v_mfma_f32_16x16x32_bf16 v[128:131], v[80:83], v[156:159], v[128:131]
	v_mfma_f32_16x16x32_bf16 v[120:123], v[104:107], v[156:159], v[120:123]
	v_mfma_f32_16x16x32_bf16 v[100:103], v[80:83], v[164:167], v[100:103]
	v_mfma_f32_16x16x32_bf16 v[96:99], v[104:107], v[164:167], v[96:99]
	v_mfma_f32_16x16x32_bf16 v[76:79], v[80:83], v[204:207], v[76:79]
	v_mfma_f32_16x16x32_bf16 v[72:75], v[104:107], v[204:207], v[72:75]
	v_mfma_f32_16x16x32_bf16 v[176:179], v[108:111], v[152:155], v[168:171]
	v_mfma_f32_16x16x32_bf16 v[128:131], v[84:87], v[160:163], v[128:131]
	v_mfma_f32_16x16x32_bf16 v[120:123], v[108:111], v[160:163], v[120:123]
	v_mfma_f32_16x16x32_bf16 v[100:103], v[84:87], v[200:203], v[100:103]
	v_mfma_f32_16x16x32_bf16 v[96:99], v[108:111], v[200:203], v[96:99]
	v_mfma_f32_16x16x32_bf16 v[76:79], v[84:87], v[208:211], v[76:79]
	v_mfma_f32_16x16x32_bf16 v[72:75], v[108:111], v[208:211], v[72:75]
	v_mfma_f32_16x16x32_bf16 v[168:171], v[124:127], v[148:151], v[172:175]
	v_mfma_f32_16x16x32_bf16 v[144:147], v[136:139], v[148:151], v[144:147]
	v_mfma_f32_16x16x32_bf16 v[116:119], v[124:127], v[156:159], v[116:119]
	v_mfma_f32_16x16x32_bf16 v[112:115], v[136:139], v[156:159], v[112:115]
	v_mfma_f32_16x16x32_bf16 v[92:95], v[124:127], v[164:167], v[92:95]
	v_mfma_f32_16x16x32_bf16 v[88:91], v[136:139], v[164:167], v[88:91]
	v_mfma_f32_16x16x32_bf16 v[68:71], v[124:127], v[204:207], v[68:71]
	v_mfma_f32_16x16x32_bf16 v[64:67], v[136:139], v[204:207], v[64:67]
	v_mfma_f32_16x16x32_bf16 v[172:175], v[132:135], v[152:155], v[168:171]
	v_mfma_f32_16x16x32_bf16 v[168:171], v[140:143], v[152:155], v[144:147]
	v_mfma_f32_16x16x32_bf16 v[116:119], v[132:135], v[160:163], v[116:119]
	v_mfma_f32_16x16x32_bf16 v[112:115], v[140:143], v[160:163], v[112:115]
	v_mfma_f32_16x16x32_bf16 v[92:95], v[132:135], v[200:203], v[92:95]
	v_mfma_f32_16x16x32_bf16 v[88:91], v[140:143], v[200:203], v[88:91]
	v_mfma_f32_16x16x32_bf16 v[68:71], v[132:135], v[208:211], v[68:71]
	v_mfma_f32_16x16x32_bf16 v[64:67], v[140:143], v[208:211], v[64:67]
	s_barrier
	s_add_i32 s14, s24, s19
	v_lshl_add_u64 v[208:209], v[212:213], 0, s[56:57]
	s_mov_b32 m0, s14
	ds_read_b128 v[144:147], v251 offset:49152
	ds_read_b128 v[148:151], v251 offset:50176
	ds_read_b128 v[152:155], v251 offset:51200
	ds_read_b128 v[156:159], v251 offset:52224
	ds_read_b128 v[160:163], v251 offset:53248
	ds_read_b128 v[164:167], v251 offset:54272
	ds_read_b128 v[200:203], v251 offset:55296
	ds_read_b128 v[204:207], v251 offset:56320
	global_load_lds_dwordx4 v[208:209], off
	v_lshl_add_u64 v[208:209], v[214:215], 0, s[56:57]
	s_add_i32 m0, s14, 0x2000
	s_add_i32 s14, s49, s19
	global_load_lds_dwordx4 v[208:209], off
	v_lshl_add_u64 v[208:209], v[216:217], 0, s[56:57]
	s_mov_b32 m0, s14
	s_nop 0
	global_load_lds_dwordx4 v[208:209], off
	v_lshl_add_u64 v[208:209], v[218:219], 0, s[56:57]
	s_add_i32 m0, s14, 0x2000
	s_nop 0
	global_load_lds_dwordx4 v[208:209], off
	v_lshl_add_u64 v[208:209], v[220:221], 0, s[56:57]
	s_mov_b32 m0, s29
	s_nop 0
	global_load_lds_dwordx4 v[208:209], off
	v_lshl_add_u64 v[208:209], v[222:223], 0, s[56:57]
	s_mov_b32 m0, s30
	s_nop 0
	global_load_lds_dwordx4 v[208:209], off
	s_waitcnt vmcnt(8)
	s_waitcnt lgkmcnt(0)
	s_barrier
	s_waitcnt lgkmcnt(0)
	v_mfma_f32_16x16x32_bf16 v[60:63], v[80:83], v[144:147], v[60:63]
	v_mfma_f32_16x16x32_bf16 v[56:59], v[104:107], v[144:147], v[56:59]
	v_mfma_f32_16x16x32_bf16 v[44:47], v[80:83], v[152:155], v[44:47]
	v_mfma_f32_16x16x32_bf16 v[40:43], v[104:107], v[152:155], v[40:43]
	v_mfma_f32_16x16x32_bf16 v[28:31], v[80:83], v[160:163], v[28:31]
	v_mfma_f32_16x16x32_bf16 v[24:27], v[104:107], v[160:163], v[24:27]
	v_mfma_f32_16x16x32_bf16 v[12:15], v[80:83], v[200:203], v[12:15]
	v_mfma_f32_16x16x32_bf16 v[8:11], v[104:107], v[200:203], v[8:11]
	v_mfma_f32_16x16x32_bf16 v[60:63], v[84:87], v[148:151], v[60:63]
	v_mfma_f32_16x16x32_bf16 v[56:59], v[108:111], v[148:151], v[56:59]
	v_mfma_f32_16x16x32_bf16 v[44:47], v[84:87], v[156:159], v[44:47]
	v_mfma_f32_16x16x32_bf16 v[40:43], v[108:111], v[156:159], v[40:43]
	v_mfma_f32_16x16x32_bf16 v[28:31], v[84:87], v[164:167], v[28:31]
	v_mfma_f32_16x16x32_bf16 v[24:27], v[108:111], v[164:167], v[24:27]
	v_mfma_f32_16x16x32_bf16 v[12:15], v[84:87], v[204:207], v[12:15]
	v_mfma_f32_16x16x32_bf16 v[8:11], v[108:111], v[204:207], v[8:11]
	v_mfma_f32_16x16x32_bf16 v[52:55], v[124:127], v[144:147], v[52:55]
	v_mfma_f32_16x16x32_bf16 v[48:51], v[136:139], v[144:147], v[48:51]
	v_mfma_f32_16x16x32_bf16 v[36:39], v[124:127], v[152:155], v[36:39]
	v_mfma_f32_16x16x32_bf16 v[32:35], v[136:139], v[152:155], v[32:35]
	v_mfma_f32_16x16x32_bf16 v[20:23], v[124:127], v[160:163], v[20:23]
	v_mfma_f32_16x16x32_bf16 v[16:19], v[136:139], v[160:163], v[16:19]
	v_mfma_f32_16x16x32_bf16 v[4:7], v[124:127], v[200:203], v[4:7]
	v_mfma_f32_16x16x32_bf16 v[0:3], v[136:139], v[200:203], v[0:3]
	v_mfma_f32_16x16x32_bf16 v[52:55], v[132:135], v[148:151], v[52:55]
	v_mfma_f32_16x16x32_bf16 v[48:51], v[140:143], v[148:151], v[48:51]
	v_mfma_f32_16x16x32_bf16 v[36:39], v[132:135], v[156:159], v[36:39]
	v_mfma_f32_16x16x32_bf16 v[32:35], v[140:143], v[156:159], v[32:35]
	v_mfma_f32_16x16x32_bf16 v[20:23], v[132:135], v[164:167], v[20:23]
	v_mfma_f32_16x16x32_bf16 v[16:19], v[140:143], v[164:167], v[16:19]
	v_mfma_f32_16x16x32_bf16 v[4:7], v[132:135], v[204:207], v[4:7]
	v_mfma_f32_16x16x32_bf16 v[0:3], v[140:143], v[204:207], v[0:3]
	s_barrier
	s_add_u32 s44, s44, 0x100
	s_addc_u32 s45, s45, 0
	s_add_u32 s16, s16, 0x100
	s_addc_u32 s17, s17, 0
	s_cmp_ge_u32 s23, s28
	s_mov_b32 s14, s23
.LBB0_422:
	s_add_i32 s23, s14, 2
	s_add_u32 s24, s44, 0x80
	s_addc_u32 s15, s45, 0
	s_add_i32 s49, 0, 0x10000
	s_cmp_eq_u32 s31, s14
	s_cselect_b32 s15, s1, s15
	s_cselect_b32 s14, s0, s24
	s_cselect_b32 s51, s43, s17
	s_cselect_b32 s50, s42, s16
	s_add_i32 s24, 0, 0x14000
	v_add_u32_e32 v108, s49, v249
	v_add_u32_e32 v140, s24, v249
	ds_read_b128 v[80:83], v108
	ds_read_b128 v[84:87], v108 offset:1024
	ds_read_b128 v[104:107], v108 offset:2048
	ds_read_b128 v[108:111], v108 offset:3072
	ds_read_b128 v[124:127], v140
	ds_read_b128 v[132:135], v140 offset:1024
	ds_read_b128 v[136:139], v140 offset:2048
	ds_read_b128 v[140:143], v140 offset:3072
	v_lshl_add_u64 v[208:209], s[44:45], 0, v[196:197]
	s_add_i32 m0, s20, 0xc000
	ds_read_b128 v[144:147], v251
	ds_read_b128 v[148:151], v251 offset:1024
	ds_read_b128 v[152:155], v251 offset:2048
	ds_read_b128 v[156:159], v251 offset:3072
	ds_read_b128 v[160:163], v251 offset:4096
	ds_read_b128 v[164:167], v251 offset:5120
	ds_read_b128 v[200:203], v251 offset:6144
	ds_read_b128 v[204:207], v251 offset:7168
	global_load_lds_dwordx4 v[208:209], off
	v_lshl_add_u64 v[208:209], s[44:45], 0, v[198:199]
	s_add_i32 m0, s20, 0xe000
	s_nop 0
	global_load_lds_dwordx4 v[208:209], off
	s_waitcnt vmcnt(8)
	s_waitcnt lgkmcnt(0)
	s_barrier
	s_waitcnt lgkmcnt(0)
	v_mfma_f32_16x16x32_bf16 v[180:183], v[80:83], v[144:147], v[180:183]
	v_mfma_f32_16x16x32_bf16 v[176:179], v[104:107], v[144:147], v[176:179]
	v_mfma_f32_16x16x32_bf16 v[128:131], v[80:83], v[152:155], v[128:131]
	v_mfma_f32_16x16x32_bf16 v[120:123], v[104:107], v[152:155], v[120:123]
	v_mfma_f32_16x16x32_bf16 v[100:103], v[80:83], v[160:163], v[100:103]
	v_mfma_f32_16x16x32_bf16 v[96:99], v[104:107], v[160:163], v[96:99]
	v_mfma_f32_16x16x32_bf16 v[76:79], v[80:83], v[200:203], v[76:79]
	v_mfma_f32_16x16x32_bf16 v[72:75], v[104:107], v[200:203], v[72:75]
	v_mfma_f32_16x16x32_bf16 v[180:183], v[84:87], v[148:151], v[180:183]
	v_mfma_f32_16x16x32_bf16 v[176:179], v[108:111], v[148:151], v[176:179]
	v_mfma_f32_16x16x32_bf16 v[128:131], v[84:87], v[156:159], v[128:131]
	v_mfma_f32_16x16x32_bf16 v[120:123], v[108:111], v[156:159], v[120:123]
	v_mfma_f32_16x16x32_bf16 v[100:103], v[84:87], v[164:167], v[100:103]
	v_mfma_f32_16x16x32_bf16 v[96:99], v[108:111], v[164:167], v[96:99]
	v_mfma_f32_16x16x32_bf16 v[76:79], v[84:87], v[204:207], v[76:79]
	v_mfma_f32_16x16x32_bf16 v[72:75], v[108:111], v[204:207], v[72:75]
	v_mfma_f32_16x16x32_bf16 v[172:175], v[124:127], v[144:147], v[172:175]
	v_mfma_f32_16x16x32_bf16 v[116:119], v[124:127], v[152:155], v[116:119]
	v_mfma_f32_16x16x32_bf16 v[112:115], v[136:139], v[152:155], v[112:115]
	v_mfma_f32_16x16x32_bf16 v[92:95], v[124:127], v[160:163], v[92:95]
	v_mfma_f32_16x16x32_bf16 v[88:91], v[136:139], v[160:163], v[88:91]
	v_mfma_f32_16x16x32_bf16 v[68:71], v[124:127], v[200:203], v[68:71]
	v_mfma_f32_16x16x32_bf16 v[64:67], v[136:139], v[200:203], v[64:67]
	v_mfma_f32_16x16x32_bf16 v[172:175], v[132:135], v[148:151], v[172:175]
	v_mfma_f32_16x16x32_bf16 v[144:147], v[136:139], v[144:147], v[168:171]
	v_mfma_f32_16x16x32_bf16 v[116:119], v[132:135], v[156:159], v[116:119]
	v_mfma_f32_16x16x32_bf16 v[112:115], v[140:143], v[156:159], v[112:115]
	v_mfma_f32_16x16x32_bf16 v[92:95], v[132:135], v[164:167], v[92:95]
	v_mfma_f32_16x16x32_bf16 v[88:91], v[140:143], v[164:167], v[88:91]
	v_mfma_f32_16x16x32_bf16 v[68:71], v[132:135], v[204:207], v[68:71]
	v_mfma_f32_16x16x32_bf16 v[64:67], v[140:143], v[204:207], v[64:67]
	v_mfma_f32_16x16x32_bf16 v[144:147], v[140:143], v[148:151], v[144:147]
	s_barrier
	s_add_i32 s49, s49, s19
	v_lshl_add_u64 v[212:213], s[50:51], 0, v[184:185]
	s_mov_b32 m0, s49
	ds_read_b128 v[148:151], v251 offset:16384
	ds_read_b128 v[152:155], v251 offset:17408
	ds_read_b128 v[156:159], v251 offset:18432
	ds_read_b128 v[160:163], v251 offset:19456
	ds_read_b128 v[164:167], v251 offset:20480
	ds_read_b128 v[168:171], v251 offset:21504
	ds_read_b128 v[200:203], v251 offset:22528
	ds_read_b128 v[204:207], v251 offset:23552
	global_load_lds_dwordx4 v[212:213], off
	s_add_i32 m0, s49, 0x2000
	s_add_u32 s50, s50, s8
	v_lshl_add_u64 v[214:215], v[212:213], 0, s[70:71]
	s_addc_u32 s51, s51, 0
	s_add_i32 s24, s24, s19
	global_load_lds_dwordx4 v[214:215], off
	v_lshl_add_u64 v[216:217], s[50:51], 0, v[184:185]
	s_mov_b32 m0, s24
	v_lshl_add_u64 v[218:219], v[216:217], 0, s[70:71]
	global_load_lds_dwordx4 v[216:217], off
	s_add_i32 m0, s24, 0x2000
	v_lshl_add_u64 v[220:221], s[14:15], 0, v[194:195]
	global_load_lds_dwordx4 v[218:219], off
	s_mov_b32 m0, s20
	v_lshl_add_u64 v[222:223], v[220:221], 0, s[70:71]
	global_load_lds_dwordx4 v[220:221], off
	s_mov_b32 m0, s25
	s_nop 0
	global_load_lds_dwordx4 v[222:223], off
	s_waitcnt vmcnt(8)
	s_waitcnt lgkmcnt(0)
	s_barrier
	s_waitcnt lgkmcnt(0)
	v_mfma_f32_16x16x32_bf16 v[60:63], v[80:83], v[148:151], v[60:63]
	v_mfma_f32_16x16x32_bf16 v[56:59], v[104:107], v[148:151], v[56:59]
	v_mfma_f32_16x16x32_bf16 v[44:47], v[80:83], v[156:159], v[44:47]
	v_mfma_f32_16x16x32_bf16 v[40:43], v[104:107], v[156:159], v[40:43]
	v_mfma_f32_16x16x32_bf16 v[28:31], v[80:83], v[164:167], v[28:31]
	v_mfma_f32_16x16x32_bf16 v[24:27], v[104:107], v[164:167], v[24:27]
	v_mfma_f32_16x16x32_bf16 v[12:15], v[80:83], v[200:203], v[12:15]
	v_mfma_f32_16x16x32_bf16 v[8:11], v[104:107], v[200:203], v[8:11]
	v_mfma_f32_16x16x32_bf16 v[60:63], v[84:87], v[152:155], v[60:63]
	v_mfma_f32_16x16x32_bf16 v[56:59], v[108:111], v[152:155], v[56:59]
	v_mfma_f32_16x16x32_bf16 v[44:47], v[84:87], v[160:163], v[44:47]
	v_mfma_f32_16x16x32_bf16 v[40:43], v[108:111], v[160:163], v[40:43]
	v_mfma_f32_16x16x32_bf16 v[28:31], v[84:87], v[168:171], v[28:31]
	v_mfma_f32_16x16x32_bf16 v[24:27], v[108:111], v[168:171], v[24:27]
	v_mfma_f32_16x16x32_bf16 v[12:15], v[84:87], v[204:207], v[12:15]
	v_mfma_f32_16x16x32_bf16 v[8:11], v[108:111], v[204:207], v[8:11]
	v_mfma_f32_16x16x32_bf16 v[52:55], v[124:127], v[148:151], v[52:55]
	v_mfma_f32_16x16x32_bf16 v[48:51], v[136:139], v[148:151], v[48:51]
	v_mfma_f32_16x16x32_bf16 v[36:39], v[124:127], v[156:159], v[36:39]
	v_mfma_f32_16x16x32_bf16 v[32:35], v[136:139], v[156:159], v[32:35]
	v_mfma_f32_16x16x32_bf16 v[20:23], v[124:127], v[164:167], v[20:23]
	v_mfma_f32_16x16x32_bf16 v[16:19], v[136:139], v[164:167], v[16:19]
	v_mfma_f32_16x16x32_bf16 v[4:7], v[124:127], v[200:203], v[4:7]
	v_mfma_f32_16x16x32_bf16 v[0:3], v[136:139], v[200:203], v[0:3]
	v_mfma_f32_16x16x32_bf16 v[52:55], v[132:135], v[152:155], v[52:55]
	v_mfma_f32_16x16x32_bf16 v[48:51], v[140:143], v[152:155], v[48:51]
	v_mfma_f32_16x16x32_bf16 v[36:39], v[132:135], v[160:163], v[36:39]
	v_mfma_f32_16x16x32_bf16 v[32:35], v[140:143], v[160:163], v[32:35]
	v_mfma_f32_16x16x32_bf16 v[20:23], v[132:135], v[168:171], v[20:23]
	v_mfma_f32_16x16x32_bf16 v[16:19], v[140:143], v[168:171], v[16:19]
	v_mfma_f32_16x16x32_bf16 v[4:7], v[132:135], v[204:207], v[4:7]
	v_mfma_f32_16x16x32_bf16 v[0:3], v[140:143], v[204:207], v[0:3]
	s_barrier
	s_add_i32 s24, 0, 0x18000
	s_add_i32 s49, 0, 0x1c000
	v_add_u32_e32 v108, s24, v249
	v_add_u32_e32 v140, s49, v249
	ds_read_b128 v[80:83], v108
	ds_read_b128 v[84:87], v108 offset:1024
	ds_read_b128 v[104:107], v108 offset:2048
	ds_read_b128 v[108:111], v108 offset:3072
	ds_read_b128 v[124:127], v140
	ds_read_b128 v[132:135], v140 offset:1024
	ds_read_b128 v[136:139], v140 offset:2048
	ds_read_b128 v[140:143], v140 offset:3072
	s_add_u32 s14, s14, s8
	s_addc_u32 s15, s15, 0
	s_mov_b32 m0, s26
	v_lshl_add_u64 v[168:169], s[14:15], 0, v[194:195]
	ds_read_b128 v[148:151], v251 offset:32768
	ds_read_b128 v[152:155], v251 offset:33792
	ds_read_b128 v[156:159], v251 offset:34816
	ds_read_b128 v[160:163], v251 offset:35840
	ds_read_b128 v[164:167], v251 offset:36864
	ds_read_b128 v[200:203], v251 offset:37888
	ds_read_b128 v[204:207], v251 offset:38912
	ds_read_b128 v[208:211], v251 offset:39936
	global_load_lds_dwordx4 v[168:169], off
	v_lshl_add_u64 v[168:169], v[168:169], 0, s[70:71]
	s_mov_b32 m0, s27
	s_nop 0
	global_load_lds_dwordx4 v[168:169], off
	s_waitcnt vmcnt(8)
	s_waitcnt lgkmcnt(0)
	s_barrier
	s_waitcnt lgkmcnt(0)
	v_mfma_f32_16x16x32_bf16 v[168:171], v[80:83], v[148:151], v[180:183]
	v_mfma_f32_16x16x32_bf16 v[180:183], v[84:87], v[152:155], v[168:171]
	v_mfma_f32_16x16x32_bf16 v[168:171], v[104:107], v[148:151], v[176:179]
	v_mfma_f32_16x16x32_bf16 v[128:131], v[80:83], v[156:159], v[128:131]
	v_mfma_f32_16x16x32_bf16 v[120:123], v[104:107], v[156:159], v[120:123]
	v_mfma_f32_16x16x32_bf16 v[100:103], v[80:83], v[164:167], v[100:103]
	v_mfma_f32_16x16x32_bf16 v[96:99], v[104:107], v[164:167], v[96:99]
	v_mfma_f32_16x16x32_bf16 v[76:79], v[80:83], v[204:207], v[76:79]
	v_mfma_f32_16x16x32_bf16 v[72:75], v[104:107], v[204:207], v[72:75]
	v_mfma_f32_16x16x32_bf16 v[176:179], v[108:111], v[152:155], v[168:171]
	v_mfma_f32_16x16x32_bf16 v[128:131], v[84:87], v[160:163], v[128:131]
	v_mfma_f32_16x16x32_bf16 v[120:123], v[108:111], v[160:163], v[120:123]
	v_mfma_f32_16x16x32_bf16 v[100:103], v[84:87], v[200:203], v[100:103]
	v_mfma_f32_16x16x32_bf16 v[96:99], v[108:111], v[200:203], v[96:99]
	v_mfma_f32_16x16x32_bf16 v[76:79], v[84:87], v[208:211], v[76:79]
	v_mfma_f32_16x16x32_bf16 v[72:75], v[108:111], v[208:211], v[72:75]
	v_mfma_f32_16x16x32_bf16 v[168:171], v[124:127], v[148:151], v[172:175]
	v_mfma_f32_16x16x32_bf16 v[144:147], v[136:139], v[148:151], v[144:147]
	v_mfma_f32_16x16x32_bf16 v[116:119], v[124:127], v[156:159], v[116:119]
	v_mfma_f32_16x16x32_bf16 v[112:115], v[136:139], v[156:159], v[112:115]
	v_mfma_f32_16x16x32_bf16 v[92:95], v[124:127], v[164:167], v[92:95]
	v_mfma_f32_16x16x32_bf16 v[88:91], v[136:139], v[164:167], v[88:91]
	v_mfma_f32_16x16x32_bf16 v[68:71], v[124:127], v[204:207], v[68:71]
	v_mfma_f32_16x16x32_bf16 v[64:67], v[136:139], v[204:207], v[64:67]
	v_mfma_f32_16x16x32_bf16 v[172:175], v[132:135], v[152:155], v[168:171]
	v_mfma_f32_16x16x32_bf16 v[168:171], v[140:143], v[152:155], v[144:147]
	v_mfma_f32_16x16x32_bf16 v[116:119], v[132:135], v[160:163], v[116:119]
	v_mfma_f32_16x16x32_bf16 v[112:115], v[140:143], v[160:163], v[112:115]
	v_mfma_f32_16x16x32_bf16 v[92:95], v[132:135], v[200:203], v[92:95]
	v_mfma_f32_16x16x32_bf16 v[88:91], v[140:143], v[200:203], v[88:91]
	v_mfma_f32_16x16x32_bf16 v[68:71], v[132:135], v[208:211], v[68:71]
	v_mfma_f32_16x16x32_bf16 v[64:67], v[140:143], v[208:211], v[64:67]
	s_barrier
	s_add_i32 s14, s24, s19
	v_lshl_add_u64 v[208:209], v[212:213], 0, s[56:57]
	s_mov_b32 m0, s14
	ds_read_b128 v[144:147], v251 offset:49152
	ds_read_b128 v[148:151], v251 offset:50176
	ds_read_b128 v[152:155], v251 offset:51200
	ds_read_b128 v[156:159], v251 offset:52224
	ds_read_b128 v[160:163], v251 offset:53248
	ds_read_b128 v[164:167], v251 offset:54272
	ds_read_b128 v[200:203], v251 offset:55296
	ds_read_b128 v[204:207], v251 offset:56320
	global_load_lds_dwordx4 v[208:209], off
	v_lshl_add_u64 v[208:209], v[214:215], 0, s[56:57]
	s_add_i32 m0, s14, 0x2000
	s_add_i32 s14, s49, s19
	global_load_lds_dwordx4 v[208:209], off
	v_lshl_add_u64 v[208:209], v[216:217], 0, s[56:57]
	s_mov_b32 m0, s14
	s_nop 0
	global_load_lds_dwordx4 v[208:209], off
	v_lshl_add_u64 v[208:209], v[218:219], 0, s[56:57]
	s_add_i32 m0, s14, 0x2000
	s_nop 0
	global_load_lds_dwordx4 v[208:209], off
	v_lshl_add_u64 v[208:209], v[220:221], 0, s[56:57]
	s_mov_b32 m0, s29
	s_nop 0
	global_load_lds_dwordx4 v[208:209], off
	v_lshl_add_u64 v[208:209], v[222:223], 0, s[56:57]
	s_mov_b32 m0, s30
	s_nop 0
	global_load_lds_dwordx4 v[208:209], off
	s_waitcnt vmcnt(8)
	s_waitcnt lgkmcnt(0)
	s_barrier
	s_waitcnt lgkmcnt(0)
	v_mfma_f32_16x16x32_bf16 v[60:63], v[80:83], v[144:147], v[60:63]
	v_mfma_f32_16x16x32_bf16 v[56:59], v[104:107], v[144:147], v[56:59]
	v_mfma_f32_16x16x32_bf16 v[44:47], v[80:83], v[152:155], v[44:47]
	v_mfma_f32_16x16x32_bf16 v[40:43], v[104:107], v[152:155], v[40:43]
	v_mfma_f32_16x16x32_bf16 v[28:31], v[80:83], v[160:163], v[28:31]
	v_mfma_f32_16x16x32_bf16 v[24:27], v[104:107], v[160:163], v[24:27]
	v_mfma_f32_16x16x32_bf16 v[12:15], v[80:83], v[200:203], v[12:15]
	v_mfma_f32_16x16x32_bf16 v[8:11], v[104:107], v[200:203], v[8:11]
	v_mfma_f32_16x16x32_bf16 v[60:63], v[84:87], v[148:151], v[60:63]
	v_mfma_f32_16x16x32_bf16 v[56:59], v[108:111], v[148:151], v[56:59]
	v_mfma_f32_16x16x32_bf16 v[44:47], v[84:87], v[156:159], v[44:47]
	v_mfma_f32_16x16x32_bf16 v[40:43], v[108:111], v[156:159], v[40:43]
	v_mfma_f32_16x16x32_bf16 v[28:31], v[84:87], v[164:167], v[28:31]
	v_mfma_f32_16x16x32_bf16 v[24:27], v[108:111], v[164:167], v[24:27]
	v_mfma_f32_16x16x32_bf16 v[12:15], v[84:87], v[204:207], v[12:15]
	v_mfma_f32_16x16x32_bf16 v[8:11], v[108:111], v[204:207], v[8:11]
	v_mfma_f32_16x16x32_bf16 v[52:55], v[124:127], v[144:147], v[52:55]
	v_mfma_f32_16x16x32_bf16 v[48:51], v[136:139], v[144:147], v[48:51]
	v_mfma_f32_16x16x32_bf16 v[36:39], v[124:127], v[152:155], v[36:39]
	v_mfma_f32_16x16x32_bf16 v[32:35], v[136:139], v[152:155], v[32:35]
	v_mfma_f32_16x16x32_bf16 v[20:23], v[124:127], v[160:163], v[20:23]
	v_mfma_f32_16x16x32_bf16 v[16:19], v[136:139], v[160:163], v[16:19]
	v_mfma_f32_16x16x32_bf16 v[4:7], v[124:127], v[200:203], v[4:7]
	v_mfma_f32_16x16x32_bf16 v[0:3], v[136:139], v[200:203], v[0:3]
	v_mfma_f32_16x16x32_bf16 v[52:55], v[132:135], v[148:151], v[52:55]
	v_mfma_f32_16x16x32_bf16 v[48:51], v[140:143], v[148:151], v[48:51]
	v_mfma_f32_16x16x32_bf16 v[36:39], v[132:135], v[156:159], v[36:39]
	v_mfma_f32_16x16x32_bf16 v[32:35], v[140:143], v[156:159], v[32:35]
	v_mfma_f32_16x16x32_bf16 v[20:23], v[132:135], v[164:167], v[20:23]
	v_mfma_f32_16x16x32_bf16 v[16:19], v[140:143], v[164:167], v[16:19]
	v_mfma_f32_16x16x32_bf16 v[4:7], v[132:135], v[204:207], v[4:7]
	v_mfma_f32_16x16x32_bf16 v[0:3], v[140:143], v[204:207], v[0:3]
	s_barrier
	s_add_u32 s44, s44, 0x100
	s_addc_u32 s45, s45, 0
	s_add_u32 s16, s16, 0x100
	s_addc_u32 s17, s17, 0
	s_cmp_ge_u32 s23, s28
	s_mov_b32 s14, s23
	s_cbranch_scc0 .LBB0_422
	s_and_b64 vcc, exec, s[12:13]
	s_cbranch_vccz .LBB0_425
	s_barrier

.LBB0_458:
	s_ashr_i32 s43, s42, 31
	s_lshl_b64 s[44:45], s[42:43], 19
	s_add_u32 s44, s64, s44
	s_addc_u32 s45, s65, s45
	s_and_b64 s[46:47], s[40:41], exec
	s_cselect_b32 s31, s45, s17
	s_cselect_b32 s43, s44, s16
	s_ashr_i32 s13, s12, 31
	s_lshl_b64 s[46:47], s[12:13], 19
	s_add_u32 s46, s22, s46
	s_addc_u32 s47, s23, s47
	s_and_b64 s[48:49], s[40:41], exec
	s_cselect_b32 s13, s47, s15
	s_cselect_b32 s50, s46, s14
	s_add_u32 s48, s16, 0x40080
	s_addc_u32 s49, s17, 0
	s_add_u32 s16, s14, 0x100
	s_addc_u32 s17, s15, 0
	s_mov_b32 s51, -2
	s_add_u32 s14, s48, 0xfffc0080
	s_addc_u32 s15, s49, -1
	s_add_i32 s70, 0, 0x10000
	s_cmp_eq_u32 s51, 12
	s_cselect_b32 s15, s31, s15
	s_cselect_b32 s14, s43, s14
	v_add_u32_e32 v138, s70, v142
	s_cselect_b32 s61, s13, s17
	s_cselect_b32 s60, s50, s16
	s_add_i32 s84, 0, 0x14000
	ds_read_b128 v[134:137], v138
	ds_read_b128 v[148:151], v138 offset:1024
	ds_read_b128 v[152:155], v138 offset:2048
	ds_read_b128 v[156:159], v138 offset:3072
	v_add_u32_e32 v138, s84, v142
	ds_read_b128 v[160:163], v138
	ds_read_b128 v[164:167], v138 offset:1024
	ds_read_b128 v[168:171], v138 offset:2048
	ds_read_b128 v[172:175], v138 offset:3072
	v_lshl_add_u64 v[138:139], s[48:49], 0, v[132:133]
	s_add_i32 m0, s19, 0xc000
	ds_read_b128 v[176:179], v146
	ds_read_b128 v[180:183], v146 offset:1024
	ds_read_b128 v[194:197], v146 offset:2048
	ds_read_b128 v[198:201], v146 offset:3072
	ds_read_b128 v[202:205], v146 offset:4096
	ds_read_b128 v[206:209], v146 offset:5120
	ds_read_b128 v[210:213], v146 offset:6144
	ds_read_b128 v[214:217], v146 offset:7168
	global_load_lds_dwordx4 v[138:139], off
	v_lshl_add_u64 v[138:139], v[138:139], 0, s[34:35]
	s_add_i32 m0, s19, 0xe000
	s_nop 0
	global_load_lds_dwordx4 v[138:139], off
	s_waitcnt vmcnt(8)
	s_waitcnt lgkmcnt(0)
	s_barrier
	s_waitcnt lgkmcnt(0)
	v_mfma_f32_16x16x32_bf16 v[124:127], v[134:137], v[176:179], 0
	v_mfma_f32_16x16x32_bf16 v[116:119], v[152:155], v[176:179], 0
	v_mfma_f32_16x16x32_bf16 v[108:111], v[134:137], v[194:197], 0
	v_mfma_f32_16x16x32_bf16 v[100:103], v[152:155], v[194:197], 0
	v_mfma_f32_16x16x32_bf16 v[92:95], v[134:137], v[202:205], 0
	v_mfma_f32_16x16x32_bf16 v[84:87], v[152:155], v[202:205], 0
	v_mfma_f32_16x16x32_bf16 v[76:79], v[134:137], v[210:213], 0
	v_mfma_f32_16x16x32_bf16 v[68:71], v[152:155], v[210:213], 0
	v_mfma_f32_16x16x32_bf16 v[124:127], v[148:151], v[180:183], v[124:127]
	v_mfma_f32_16x16x32_bf16 v[116:119], v[156:159], v[180:183], v[116:119]
	v_mfma_f32_16x16x32_bf16 v[108:111], v[148:151], v[198:201], v[108:111]
	v_mfma_f32_16x16x32_bf16 v[100:103], v[156:159], v[198:201], v[100:103]
	v_mfma_f32_16x16x32_bf16 v[92:95], v[148:151], v[206:209], v[92:95]
	v_mfma_f32_16x16x32_bf16 v[84:87], v[156:159], v[206:209], v[84:87]
	v_mfma_f32_16x16x32_bf16 v[76:79], v[148:151], v[214:217], v[76:79]
	v_mfma_f32_16x16x32_bf16 v[68:71], v[156:159], v[214:217], v[68:71]
	v_mfma_f32_16x16x32_bf16 v[120:123], v[160:163], v[176:179], 0
	v_mfma_f32_16x16x32_bf16 v[112:115], v[168:171], v[176:179], 0
	v_mfma_f32_16x16x32_bf16 v[104:107], v[160:163], v[194:197], 0
	v_mfma_f32_16x16x32_bf16 v[96:99], v[168:171], v[194:197], 0
	v_mfma_f32_16x16x32_bf16 v[88:91], v[160:163], v[202:205], 0
	v_mfma_f32_16x16x32_bf16 v[80:83], v[168:171], v[202:205], 0
	v_mfma_f32_16x16x32_bf16 v[72:75], v[160:163], v[210:213], 0
	v_mfma_f32_16x16x32_bf16 v[64:67], v[168:171], v[210:213], 0
	v_mfma_f32_16x16x32_bf16 v[120:123], v[164:167], v[180:183], v[120:123]
	v_mfma_f32_16x16x32_bf16 v[112:115], v[172:175], v[180:183], v[112:115]
	v_mfma_f32_16x16x32_bf16 v[104:107], v[164:167], v[198:201], v[104:107]
	v_mfma_f32_16x16x32_bf16 v[96:99], v[172:175], v[198:201], v[96:99]
	v_mfma_f32_16x16x32_bf16 v[88:91], v[164:167], v[206:209], v[88:91]
	v_mfma_f32_16x16x32_bf16 v[80:83], v[172:175], v[206:209], v[80:83]
	v_mfma_f32_16x16x32_bf16 v[72:75], v[164:167], v[214:217], v[72:75]
	v_mfma_f32_16x16x32_bf16 v[64:67], v[172:175], v[214:217], v[64:67]
	s_barrier
	v_lshl_add_u64 v[138:139], s[60:61], 0, v[184:185]
	s_add_i32 s60, s70, s6
	s_mov_b32 m0, s60
	ds_read_b128 v[176:179], v146 offset:16384
	ds_read_b128 v[180:183], v146 offset:17408
	ds_read_b128 v[194:197], v146 offset:18432
	ds_read_b128 v[198:201], v146 offset:19456
	ds_read_b128 v[202:205], v146 offset:20480
	ds_read_b128 v[206:209], v146 offset:21504
	ds_read_b128 v[210:213], v146 offset:22528
	ds_read_b128 v[214:217], v146 offset:23552
	global_load_lds_dwordx4 v[138:139], off
	v_lshl_add_u64 v[218:219], v[138:139], 0, s[34:35]
	s_add_i32 m0, s60, 0x2000
	s_add_i32 s60, s84, s6
	global_load_lds_dwordx4 v[218:219], off
	v_lshl_add_u64 v[218:219], v[138:139], 0, s[92:93]
	s_mov_b32 m0, s60
	s_nop 0
	global_load_lds_dwordx4 v[218:219], off
	v_lshl_add_u64 v[218:219], v[138:139], 0, s[52:53]
	s_add_i32 m0, s60, 0x2000
	s_nop 0
	global_load_lds_dwordx4 v[218:219], off
	v_lshl_add_u64 v[218:219], s[14:15], 0, v[128:129]
	s_mov_b32 m0, s19
	v_lshl_add_u64 v[220:221], v[218:219], 0, s[34:35]
	global_load_lds_dwordx4 v[218:219], off
	s_mov_b32 m0, s20
	s_nop 0
	global_load_lds_dwordx4 v[220:221], off
	s_waitcnt vmcnt(8)
	s_waitcnt lgkmcnt(0)
	s_barrier
	s_waitcnt lgkmcnt(0)
	v_mfma_f32_16x16x32_bf16 v[60:63], v[134:137], v[176:179], 0
	v_mfma_f32_16x16x32_bf16 v[52:55], v[152:155], v[176:179], 0
	v_mfma_f32_16x16x32_bf16 v[44:47], v[134:137], v[194:197], 0
	v_mfma_f32_16x16x32_bf16 v[36:39], v[152:155], v[194:197], 0
	v_mfma_f32_16x16x32_bf16 v[28:31], v[134:137], v[202:205], 0
	v_mfma_f32_16x16x32_bf16 v[20:23], v[152:155], v[202:205], 0
	v_mfma_f32_16x16x32_bf16 v[12:15], v[134:137], v[210:213], 0
	v_mfma_f32_16x16x32_bf16 v[4:7], v[152:155], v[210:213], 0
	v_mfma_f32_16x16x32_bf16 v[60:63], v[148:151], v[180:183], v[60:63]
	v_mfma_f32_16x16x32_bf16 v[52:55], v[156:159], v[180:183], v[52:55]
	v_mfma_f32_16x16x32_bf16 v[44:47], v[148:151], v[198:201], v[44:47]
	v_mfma_f32_16x16x32_bf16 v[36:39], v[156:159], v[198:201], v[36:39]
	v_mfma_f32_16x16x32_bf16 v[28:31], v[148:151], v[206:209], v[28:31]
	v_mfma_f32_16x16x32_bf16 v[20:23], v[156:159], v[206:209], v[20:23]
	v_mfma_f32_16x16x32_bf16 v[12:15], v[148:151], v[214:217], v[12:15]
	v_mfma_f32_16x16x32_bf16 v[4:7], v[156:159], v[214:217], v[4:7]
	v_mfma_f32_16x16x32_bf16 v[56:59], v[160:163], v[176:179], 0
	v_mfma_f32_16x16x32_bf16 v[48:51], v[168:171], v[176:179], 0
	v_mfma_f32_16x16x32_bf16 v[40:43], v[160:163], v[194:197], 0
	v_mfma_f32_16x16x32_bf16 v[32:35], v[168:171], v[194:197], 0
	v_mfma_f32_16x16x32_bf16 v[24:27], v[160:163], v[202:205], 0
	v_mfma_f32_16x16x32_bf16 v[16:19], v[168:171], v[202:205], 0
	v_mfma_f32_16x16x32_bf16 v[8:11], v[160:163], v[210:213], 0
	v_mfma_f32_16x16x32_bf16 v[0:3], v[168:171], v[210:213], 0
	v_mfma_f32_16x16x32_bf16 v[56:59], v[164:167], v[180:183], v[56:59]
	v_mfma_f32_16x16x32_bf16 v[48:51], v[172:175], v[180:183], v[48:51]
	v_mfma_f32_16x16x32_bf16 v[40:43], v[164:167], v[198:201], v[40:43]
	v_mfma_f32_16x16x32_bf16 v[32:35], v[172:175], v[198:201], v[32:35]
	v_mfma_f32_16x16x32_bf16 v[24:27], v[164:167], v[206:209], v[24:27]
	v_mfma_f32_16x16x32_bf16 v[16:19], v[172:175], v[206:209], v[16:19]
	v_mfma_f32_16x16x32_bf16 v[8:11], v[164:167], v[214:217], v[8:11]
	v_mfma_f32_16x16x32_bf16 v[0:3], v[172:175], v[214:217], v[0:3]
	s_barrier
	s_add_i32 s14, 0, 0x18000
	v_add_u32_e32 v147, s14, v142
	s_add_i32 s15, 0, 0x1c000
	ds_read_b128 v[134:137], v147
	ds_read_b128 v[148:151], v147 offset:1024
	ds_read_b128 v[152:155], v147 offset:2048
	ds_read_b128 v[156:159], v147 offset:3072
	v_add_u32_e32 v147, s15, v142
	ds_read_b128 v[160:163], v147
	ds_read_b128 v[164:167], v147 offset:1024
	ds_read_b128 v[168:171], v147 offset:2048
	ds_read_b128 v[172:175], v147 offset:3072
	s_mov_b32 m0, s24
	v_lshl_add_u64 v[220:221], v[218:219], 0, s[92:93]
	ds_read_b128 v[176:179], v146 offset:32768
	ds_read_b128 v[180:183], v146 offset:33792
	ds_read_b128 v[194:197], v146 offset:34816
	ds_read_b128 v[198:201], v146 offset:35840
	ds_read_b128 v[202:205], v146 offset:36864
	ds_read_b128 v[206:209], v146 offset:37888
	ds_read_b128 v[210:213], v146 offset:38912
	ds_read_b128 v[214:217], v146 offset:39936
	global_load_lds_dwordx4 v[220:221], off
	v_lshl_add_u64 v[220:221], v[218:219], 0, s[52:53]
	s_mov_b32 m0, s25
	s_nop 0
	global_load_lds_dwordx4 v[220:221], off
	s_waitcnt vmcnt(8)
	s_waitcnt lgkmcnt(0)
	s_barrier
	s_waitcnt lgkmcnt(0)
	v_mfma_f32_16x16x32_bf16 v[124:127], v[134:137], v[176:179], v[124:127]
	v_mfma_f32_16x16x32_bf16 v[116:119], v[152:155], v[176:179], v[116:119]
	v_mfma_f32_16x16x32_bf16 v[108:111], v[134:137], v[194:197], v[108:111]
	v_mfma_f32_16x16x32_bf16 v[100:103], v[152:155], v[194:197], v[100:103]
	v_mfma_f32_16x16x32_bf16 v[92:95], v[134:137], v[202:205], v[92:95]
	v_mfma_f32_16x16x32_bf16 v[84:87], v[152:155], v[202:205], v[84:87]
	v_mfma_f32_16x16x32_bf16 v[76:79], v[134:137], v[210:213], v[76:79]
	v_mfma_f32_16x16x32_bf16 v[68:71], v[152:155], v[210:213], v[68:71]
	v_mfma_f32_16x16x32_bf16 v[124:127], v[148:151], v[180:183], v[124:127]
	v_mfma_f32_16x16x32_bf16 v[116:119], v[156:159], v[180:183], v[116:119]
	v_mfma_f32_16x16x32_bf16 v[108:111], v[148:151], v[198:201], v[108:111]
	v_mfma_f32_16x16x32_bf16 v[100:103], v[156:159], v[198:201], v[100:103]
	v_mfma_f32_16x16x32_bf16 v[92:95], v[148:151], v[206:209], v[92:95]
	v_mfma_f32_16x16x32_bf16 v[84:87], v[156:159], v[206:209], v[84:87]
	v_mfma_f32_16x16x32_bf16 v[76:79], v[148:151], v[214:217], v[76:79]
	v_mfma_f32_16x16x32_bf16 v[68:71], v[156:159], v[214:217], v[68:71]
	v_mfma_f32_16x16x32_bf16 v[120:123], v[160:163], v[176:179], v[120:123]
	v_mfma_f32_16x16x32_bf16 v[112:115], v[168:171], v[176:179], v[112:115]
	v_mfma_f32_16x16x32_bf16 v[104:107], v[160:163], v[194:197], v[104:107]
	v_mfma_f32_16x16x32_bf16 v[96:99], v[168:171], v[194:197], v[96:99]
	v_mfma_f32_16x16x32_bf16 v[88:91], v[160:163], v[202:205], v[88:91]
	v_mfma_f32_16x16x32_bf16 v[80:83], v[168:171], v[202:205], v[80:83]
	v_mfma_f32_16x16x32_bf16 v[72:75], v[160:163], v[210:213], v[72:75]
	v_mfma_f32_16x16x32_bf16 v[64:67], v[168:171], v[210:213], v[64:67]
	v_mfma_f32_16x16x32_bf16 v[120:123], v[164:167], v[180:183], v[120:123]
	v_mfma_f32_16x16x32_bf16 v[112:115], v[172:175], v[180:183], v[112:115]
	v_mfma_f32_16x16x32_bf16 v[104:107], v[164:167], v[198:201], v[104:107]
	v_mfma_f32_16x16x32_bf16 v[96:99], v[172:175], v[198:201], v[96:99]
	v_mfma_f32_16x16x32_bf16 v[88:91], v[164:167], v[206:209], v[88:91]
	v_mfma_f32_16x16x32_bf16 v[80:83], v[172:175], v[206:209], v[80:83]
	v_mfma_f32_16x16x32_bf16 v[72:75], v[164:167], v[214:217], v[72:75]
	v_mfma_f32_16x16x32_bf16 v[64:67], v[172:175], v[214:217], v[64:67]
	s_barrier
	s_add_i32 s14, s14, s6
	v_lshl_add_u64 v[220:221], v[138:139], 0, s[56:57]
	s_mov_b32 m0, s14
	ds_read_b128 v[176:179], v146 offset:49152
	ds_read_b128 v[180:183], v146 offset:50176
	ds_read_b128 v[194:197], v146 offset:51200
	ds_read_b128 v[198:201], v146 offset:52224
	ds_read_b128 v[202:205], v146 offset:53248
	ds_read_b128 v[206:209], v146 offset:54272
	ds_read_b128 v[210:213], v146 offset:55296
	ds_read_b128 v[214:217], v146 offset:56320
	global_load_lds_dwordx4 v[220:221], off
	v_lshl_add_u64 v[220:221], v[138:139], 0, s[96:97]
	s_add_i32 m0, s14, 0x2000
	s_add_i32 s14, s15, s6
	global_load_lds_dwordx4 v[220:221], off
	v_lshl_add_u64 v[220:221], v[138:139], 0, s[88:89]
	s_mov_b32 m0, s14
	v_lshl_add_u64 v[138:139], v[138:139], 0, s[68:69]
	global_load_lds_dwordx4 v[220:221], off
	s_add_i32 m0, s14, 0x2000
	s_nop 0
	global_load_lds_dwordx4 v[138:139], off
	v_lshl_add_u64 v[138:139], v[218:219], 0, s[56:57]
	s_mov_b32 m0, s26
	s_nop 0
	global_load_lds_dwordx4 v[138:139], off
	v_lshl_add_u64 v[138:139], v[218:219], 0, s[96:97]
	s_mov_b32 m0, s27
	s_nop 0
	global_load_lds_dwordx4 v[138:139], off
	s_waitcnt vmcnt(8)
	s_waitcnt lgkmcnt(0)
	s_barrier
	s_waitcnt lgkmcnt(0)
	v_mfma_f32_16x16x32_bf16 v[60:63], v[134:137], v[176:179], v[60:63]
	v_mfma_f32_16x16x32_bf16 v[52:55], v[152:155], v[176:179], v[52:55]
	v_mfma_f32_16x16x32_bf16 v[44:47], v[134:137], v[194:197], v[44:47]
	v_mfma_f32_16x16x32_bf16 v[36:39], v[152:155], v[194:197], v[36:39]
	v_mfma_f32_16x16x32_bf16 v[28:31], v[134:137], v[202:205], v[28:31]
	v_mfma_f32_16x16x32_bf16 v[20:23], v[152:155], v[202:205], v[20:23]
	v_mfma_f32_16x16x32_bf16 v[12:15], v[134:137], v[210:213], v[12:15]
	v_mfma_f32_16x16x32_bf16 v[4:7], v[152:155], v[210:213], v[4:7]
	v_mfma_f32_16x16x32_bf16 v[60:63], v[148:151], v[180:183], v[60:63]
	v_mfma_f32_16x16x32_bf16 v[52:55], v[156:159], v[180:183], v[52:55]
	v_mfma_f32_16x16x32_bf16 v[44:47], v[148:151], v[198:201], v[44:47]
	v_mfma_f32_16x16x32_bf16 v[36:39], v[156:159], v[198:201], v[36:39]
	v_mfma_f32_16x16x32_bf16 v[28:31], v[148:151], v[206:209], v[28:31]
	v_mfma_f32_16x16x32_bf16 v[20:23], v[156:159], v[206:209], v[20:23]
	v_mfma_f32_16x16x32_bf16 v[12:15], v[148:151], v[214:217], v[12:15]
	v_mfma_f32_16x16x32_bf16 v[4:7], v[156:159], v[214:217], v[4:7]
	v_mfma_f32_16x16x32_bf16 v[56:59], v[160:163], v[176:179], v[56:59]
	v_mfma_f32_16x16x32_bf16 v[48:51], v[168:171], v[176:179], v[48:51]
	v_mfma_f32_16x16x32_bf16 v[40:43], v[160:163], v[194:197], v[40:43]
	v_mfma_f32_16x16x32_bf16 v[32:35], v[168:171], v[194:197], v[32:35]
	v_mfma_f32_16x16x32_bf16 v[24:27], v[160:163], v[202:205], v[24:27]
	v_mfma_f32_16x16x32_bf16 v[16:19], v[168:171], v[202:205], v[16:19]
	v_mfma_f32_16x16x32_bf16 v[8:11], v[160:163], v[210:213], v[8:11]
	v_mfma_f32_16x16x32_bf16 v[0:3], v[168:171], v[210:213], v[0:3]
	v_mfma_f32_16x16x32_bf16 v[56:59], v[164:167], v[180:183], v[56:59]
	v_mfma_f32_16x16x32_bf16 v[48:51], v[172:175], v[180:183], v[48:51]
	v_mfma_f32_16x16x32_bf16 v[40:43], v[164:167], v[198:201], v[40:43]
	v_mfma_f32_16x16x32_bf16 v[32:35], v[172:175], v[198:201], v[32:35]
	v_mfma_f32_16x16x32_bf16 v[24:27], v[164:167], v[206:209], v[24:27]
	v_mfma_f32_16x16x32_bf16 v[16:19], v[172:175], v[206:209], v[16:19]
	v_mfma_f32_16x16x32_bf16 v[8:11], v[164:167], v[214:217], v[8:11]
	v_mfma_f32_16x16x32_bf16 v[0:3], v[172:175], v[214:217], v[0:3]
	s_barrier
	s_add_i32 s51, s51, 2
	s_add_u32 s48, s48, 0x100
	s_addc_u32 s49, s49, 0
	s_add_u32 s16, s16, 0x100
	s_addc_u32 s17, s17, 0
	s_cmp_gt_u32 s51, 13
.LBB0_459:
	s_add_u32 s14, s48, 0xfffc0080
	s_addc_u32 s15, s49, -1
	s_add_i32 s70, 0, 0x10000
	s_cmp_eq_u32 s51, 12
	s_cselect_b32 s15, s31, s15
	s_cselect_b32 s14, s43, s14
	v_add_u32_e32 v138, s70, v142
	s_cselect_b32 s61, s13, s17
	s_cselect_b32 s60, s50, s16
	s_add_i32 s84, 0, 0x14000
	ds_read_b128 v[134:137], v138
	ds_read_b128 v[148:151], v138 offset:1024
	ds_read_b128 v[152:155], v138 offset:2048
	ds_read_b128 v[156:159], v138 offset:3072
	v_add_u32_e32 v138, s84, v142
	ds_read_b128 v[160:163], v138
	ds_read_b128 v[164:167], v138 offset:1024
	ds_read_b128 v[168:171], v138 offset:2048
	ds_read_b128 v[172:175], v138 offset:3072
	v_lshl_add_u64 v[138:139], s[48:49], 0, v[132:133]
	s_add_i32 m0, s19, 0xc000
	ds_read_b128 v[176:179], v146
	ds_read_b128 v[180:183], v146 offset:1024
	ds_read_b128 v[194:197], v146 offset:2048
	ds_read_b128 v[198:201], v146 offset:3072
	ds_read_b128 v[202:205], v146 offset:4096
	ds_read_b128 v[206:209], v146 offset:5120
	ds_read_b128 v[210:213], v146 offset:6144
	ds_read_b128 v[214:217], v146 offset:7168
	global_load_lds_dwordx4 v[138:139], off
	v_lshl_add_u64 v[138:139], v[138:139], 0, s[34:35]
	s_add_i32 m0, s19, 0xe000
	s_nop 0
	global_load_lds_dwordx4 v[138:139], off
	s_waitcnt vmcnt(8)
	s_waitcnt lgkmcnt(0)
	s_barrier
	s_waitcnt lgkmcnt(0)
	v_mfma_f32_16x16x32_bf16 v[124:127], v[134:137], v[176:179], v[124:127]
	v_mfma_f32_16x16x32_bf16 v[116:119], v[152:155], v[176:179], v[116:119]
	v_mfma_f32_16x16x32_bf16 v[108:111], v[134:137], v[194:197], v[108:111]
	v_mfma_f32_16x16x32_bf16 v[100:103], v[152:155], v[194:197], v[100:103]
	v_mfma_f32_16x16x32_bf16 v[92:95], v[134:137], v[202:205], v[92:95]
	v_mfma_f32_16x16x32_bf16 v[84:87], v[152:155], v[202:205], v[84:87]
	v_mfma_f32_16x16x32_bf16 v[76:79], v[134:137], v[210:213], v[76:79]
	v_mfma_f32_16x16x32_bf16 v[68:71], v[152:155], v[210:213], v[68:71]
	v_mfma_f32_16x16x32_bf16 v[124:127], v[148:151], v[180:183], v[124:127]
	v_mfma_f32_16x16x32_bf16 v[116:119], v[156:159], v[180:183], v[116:119]
	v_mfma_f32_16x16x32_bf16 v[108:111], v[148:151], v[198:201], v[108:111]
	v_mfma_f32_16x16x32_bf16 v[100:103], v[156:159], v[198:201], v[100:103]
	v_mfma_f32_16x16x32_bf16 v[92:95], v[148:151], v[206:209], v[92:95]
	v_mfma_f32_16x16x32_bf16 v[84:87], v[156:159], v[206:209], v[84:87]
	v_mfma_f32_16x16x32_bf16 v[76:79], v[148:151], v[214:217], v[76:79]
	v_mfma_f32_16x16x32_bf16 v[68:71], v[156:159], v[214:217], v[68:71]
	v_mfma_f32_16x16x32_bf16 v[120:123], v[160:163], v[176:179], v[120:123]
	v_mfma_f32_16x16x32_bf16 v[112:115], v[168:171], v[176:179], v[112:115]
	v_mfma_f32_16x16x32_bf16 v[104:107], v[160:163], v[194:197], v[104:107]
	v_mfma_f32_16x16x32_bf16 v[96:99], v[168:171], v[194:197], v[96:99]
	v_mfma_f32_16x16x32_bf16 v[88:91], v[160:163], v[202:205], v[88:91]
	v_mfma_f32_16x16x32_bf16 v[80:83], v[168:171], v[202:205], v[80:83]
	v_mfma_f32_16x16x32_bf16 v[72:75], v[160:163], v[210:213], v[72:75]
	v_mfma_f32_16x16x32_bf16 v[64:67], v[168:171], v[210:213], v[64:67]
	v_mfma_f32_16x16x32_bf16 v[120:123], v[164:167], v[180:183], v[120:123]
	v_mfma_f32_16x16x32_bf16 v[112:115], v[172:175], v[180:183], v[112:115]
	v_mfma_f32_16x16x32_bf16 v[104:107], v[164:167], v[198:201], v[104:107]
	v_mfma_f32_16x16x32_bf16 v[96:99], v[172:175], v[198:201], v[96:99]
	v_mfma_f32_16x16x32_bf16 v[88:91], v[164:167], v[206:209], v[88:91]
	v_mfma_f32_16x16x32_bf16 v[80:83], v[172:175], v[206:209], v[80:83]
	v_mfma_f32_16x16x32_bf16 v[72:75], v[164:167], v[214:217], v[72:75]
	v_mfma_f32_16x16x32_bf16 v[64:67], v[172:175], v[214:217], v[64:67]
	s_barrier
	v_lshl_add_u64 v[138:139], s[60:61], 0, v[184:185]
	s_add_i32 s60, s70, s6
	s_mov_b32 m0, s60
	ds_read_b128 v[176:179], v146 offset:16384
	ds_read_b128 v[180:183], v146 offset:17408
	ds_read_b128 v[194:197], v146 offset:18432
	ds_read_b128 v[198:201], v146 offset:19456
	ds_read_b128 v[202:205], v146 offset:20480
	ds_read_b128 v[206:209], v146 offset:21504
	ds_read_b128 v[210:213], v146 offset:22528
	ds_read_b128 v[214:217], v146 offset:23552
	global_load_lds_dwordx4 v[138:139], off
	v_lshl_add_u64 v[218:219], v[138:139], 0, s[34:35]
	s_add_i32 m0, s60, 0x2000
	s_add_i32 s60, s84, s6
	global_load_lds_dwordx4 v[218:219], off
	v_lshl_add_u64 v[218:219], v[138:139], 0, s[92:93]
	s_mov_b32 m0, s60
	s_nop 0
	global_load_lds_dwordx4 v[218:219], off
	v_lshl_add_u64 v[218:219], v[138:139], 0, s[52:53]
	s_add_i32 m0, s60, 0x2000
	s_nop 0
	global_load_lds_dwordx4 v[218:219], off
	v_lshl_add_u64 v[218:219], s[14:15], 0, v[128:129]
	s_mov_b32 m0, s19
	v_lshl_add_u64 v[220:221], v[218:219], 0, s[34:35]
	global_load_lds_dwordx4 v[218:219], off
	s_mov_b32 m0, s20
	s_nop 0
	global_load_lds_dwordx4 v[220:221], off
	s_waitcnt vmcnt(8)
	s_waitcnt lgkmcnt(0)
	s_barrier
	s_waitcnt lgkmcnt(0)
	v_mfma_f32_16x16x32_bf16 v[60:63], v[134:137], v[176:179], v[60:63]
	v_mfma_f32_16x16x32_bf16 v[52:55], v[152:155], v[176:179], v[52:55]
	v_mfma_f32_16x16x32_bf16 v[44:47], v[134:137], v[194:197], v[44:47]
	v_mfma_f32_16x16x32_bf16 v[36:39], v[152:155], v[194:197], v[36:39]
	v_mfma_f32_16x16x32_bf16 v[28:31], v[134:137], v[202:205], v[28:31]
	v_mfma_f32_16x16x32_bf16 v[20:23], v[152:155], v[202:205], v[20:23]
	v_mfma_f32_16x16x32_bf16 v[12:15], v[134:137], v[210:213], v[12:15]
	v_mfma_f32_16x16x32_bf16 v[4:7], v[152:155], v[210:213], v[4:7]
	v_mfma_f32_16x16x32_bf16 v[60:63], v[148:151], v[180:183], v[60:63]
	v_mfma_f32_16x16x32_bf16 v[52:55], v[156:159], v[180:183], v[52:55]
	v_mfma_f32_16x16x32_bf16 v[44:47], v[148:151], v[198:201], v[44:47]
	v_mfma_f32_16x16x32_bf16 v[36:39], v[156:159], v[198:201], v[36:39]
	v_mfma_f32_16x16x32_bf16 v[28:31], v[148:151], v[206:209], v[28:31]
	v_mfma_f32_16x16x32_bf16 v[20:23], v[156:159], v[206:209], v[20:23]
	v_mfma_f32_16x16x32_bf16 v[12:15], v[148:151], v[214:217], v[12:15]
	v_mfma_f32_16x16x32_bf16 v[4:7], v[156:159], v[214:217], v[4:7]
	v_mfma_f32_16x16x32_bf16 v[56:59], v[160:163], v[176:179], v[56:59]
	v_mfma_f32_16x16x32_bf16 v[48:51], v[168:171], v[176:179], v[48:51]
	v_mfma_f32_16x16x32_bf16 v[40:43], v[160:163], v[194:197], v[40:43]
	v_mfma_f32_16x16x32_bf16 v[32:35], v[168:171], v[194:197], v[32:35]
	v_mfma_f32_16x16x32_bf16 v[24:27], v[160:163], v[202:205], v[24:27]
	v_mfma_f32_16x16x32_bf16 v[16:19], v[168:171], v[202:205], v[16:19]
	v_mfma_f32_16x16x32_bf16 v[8:11], v[160:163], v[210:213], v[8:11]
	v_mfma_f32_16x16x32_bf16 v[0:3], v[168:171], v[210:213], v[0:3]
	v_mfma_f32_16x16x32_bf16 v[56:59], v[164:167], v[180:183], v[56:59]
	v_mfma_f32_16x16x32_bf16 v[48:51], v[172:175], v[180:183], v[48:51]
	v_mfma_f32_16x16x32_bf16 v[40:43], v[164:167], v[198:201], v[40:43]
	v_mfma_f32_16x16x32_bf16 v[32:35], v[172:175], v[198:201], v[32:35]
	v_mfma_f32_16x16x32_bf16 v[24:27], v[164:167], v[206:209], v[24:27]
	v_mfma_f32_16x16x32_bf16 v[16:19], v[172:175], v[206:209], v[16:19]
	v_mfma_f32_16x16x32_bf16 v[8:11], v[164:167], v[214:217], v[8:11]
	v_mfma_f32_16x16x32_bf16 v[0:3], v[172:175], v[214:217], v[0:3]
	s_barrier
	s_add_i32 s14, 0, 0x18000
	v_add_u32_e32 v147, s14, v142
	s_add_i32 s15, 0, 0x1c000
	ds_read_b128 v[134:137], v147
	ds_read_b128 v[148:151], v147 offset:1024
	ds_read_b128 v[152:155], v147 offset:2048
	ds_read_b128 v[156:159], v147 offset:3072
	v_add_u32_e32 v147, s15, v142
	ds_read_b128 v[160:163], v147
	ds_read_b128 v[164:167], v147 offset:1024
	ds_read_b128 v[168:171], v147 offset:2048
	ds_read_b128 v[172:175], v147 offset:3072
	s_mov_b32 m0, s24
	v_lshl_add_u64 v[220:221], v[218:219], 0, s[92:93]
	ds_read_b128 v[176:179], v146 offset:32768
	ds_read_b128 v[180:183], v146 offset:33792
	ds_read_b128 v[194:197], v146 offset:34816
	ds_read_b128 v[198:201], v146 offset:35840
	ds_read_b128 v[202:205], v146 offset:36864
	ds_read_b128 v[206:209], v146 offset:37888
	ds_read_b128 v[210:213], v146 offset:38912
	ds_read_b128 v[214:217], v146 offset:39936
	global_load_lds_dwordx4 v[220:221], off
	v_lshl_add_u64 v[220:221], v[218:219], 0, s[52:53]
	s_mov_b32 m0, s25
	s_nop 0
	global_load_lds_dwordx4 v[220:221], off
	s_waitcnt vmcnt(8)
	s_waitcnt lgkmcnt(0)
	s_barrier
	s_waitcnt lgkmcnt(0)
	v_mfma_f32_16x16x32_bf16 v[124:127], v[134:137], v[176:179], v[124:127]
	v_mfma_f32_16x16x32_bf16 v[116:119], v[152:155], v[176:179], v[116:119]
	v_mfma_f32_16x16x32_bf16 v[108:111], v[134:137], v[194:197], v[108:111]
	v_mfma_f32_16x16x32_bf16 v[100:103], v[152:155], v[194:197], v[100:103]
	v_mfma_f32_16x16x32_bf16 v[92:95], v[134:137], v[202:205], v[92:95]
	v_mfma_f32_16x16x32_bf16 v[84:87], v[152:155], v[202:205], v[84:87]
	v_mfma_f32_16x16x32_bf16 v[76:79], v[134:137], v[210:213], v[76:79]
	v_mfma_f32_16x16x32_bf16 v[68:71], v[152:155], v[210:213], v[68:71]
	v_mfma_f32_16x16x32_bf16 v[124:127], v[148:151], v[180:183], v[124:127]
	v_mfma_f32_16x16x32_bf16 v[116:119], v[156:159], v[180:183], v[116:119]
	v_mfma_f32_16x16x32_bf16 v[108:111], v[148:151], v[198:201], v[108:111]
	v_mfma_f32_16x16x32_bf16 v[100:103], v[156:159], v[198:201], v[100:103]
	v_mfma_f32_16x16x32_bf16 v[92:95], v[148:151], v[206:209], v[92:95]
	v_mfma_f32_16x16x32_bf16 v[84:87], v[156:159], v[206:209], v[84:87]
	v_mfma_f32_16x16x32_bf16 v[76:79], v[148:151], v[214:217], v[76:79]
	v_mfma_f32_16x16x32_bf16 v[68:71], v[156:159], v[214:217], v[68:71]
	v_mfma_f32_16x16x32_bf16 v[120:123], v[160:163], v[176:179], v[120:123]
	v_mfma_f32_16x16x32_bf16 v[112:115], v[168:171], v[176:179], v[112:115]
	v_mfma_f32_16x16x32_bf16 v[104:107], v[160:163], v[194:197], v[104:107]
	v_mfma_f32_16x16x32_bf16 v[96:99], v[168:171], v[194:197], v[96:99]
	v_mfma_f32_16x16x32_bf16 v[88:91], v[160:163], v[202:205], v[88:91]
	v_mfma_f32_16x16x32_bf16 v[80:83], v[168:171], v[202:205], v[80:83]
	v_mfma_f32_16x16x32_bf16 v[72:75], v[160:163], v[210:213], v[72:75]
	v_mfma_f32_16x16x32_bf16 v[64:67], v[168:171], v[210:213], v[64:67]
	v_mfma_f32_16x16x32_bf16 v[120:123], v[164:167], v[180:183], v[120:123]
	v_mfma_f32_16x16x32_bf16 v[112:115], v[172:175], v[180:183], v[112:115]
	v_mfma_f32_16x16x32_bf16 v[104:107], v[164:167], v[198:201], v[104:107]
	v_mfma_f32_16x16x32_bf16 v[96:99], v[172:175], v[198:201], v[96:99]
	v_mfma_f32_16x16x32_bf16 v[88:91], v[164:167], v[206:209], v[88:91]
	v_mfma_f32_16x16x32_bf16 v[80:83], v[172:175], v[206:209], v[80:83]
	v_mfma_f32_16x16x32_bf16 v[72:75], v[164:167], v[214:217], v[72:75]
	v_mfma_f32_16x16x32_bf16 v[64:67], v[172:175], v[214:217], v[64:67]
	s_barrier
	s_add_i32 s14, s14, s6
	v_lshl_add_u64 v[220:221], v[138:139], 0, s[56:57]
	s_mov_b32 m0, s14
	ds_read_b128 v[176:179], v146 offset:49152
	ds_read_b128 v[180:183], v146 offset:50176
	ds_read_b128 v[194:197], v146 offset:51200
	ds_read_b128 v[198:201], v146 offset:52224
	ds_read_b128 v[202:205], v146 offset:53248
	ds_read_b128 v[206:209], v146 offset:54272
	ds_read_b128 v[210:213], v146 offset:55296
	ds_read_b128 v[214:217], v146 offset:56320
	global_load_lds_dwordx4 v[220:221], off
	v_lshl_add_u64 v[220:221], v[138:139], 0, s[96:97]
	s_add_i32 m0, s14, 0x2000
	s_add_i32 s14, s15, s6
	global_load_lds_dwordx4 v[220:221], off
	v_lshl_add_u64 v[220:221], v[138:139], 0, s[88:89]
	s_mov_b32 m0, s14
	v_lshl_add_u64 v[138:139], v[138:139], 0, s[68:69]
	global_load_lds_dwordx4 v[220:221], off
	s_add_i32 m0, s14, 0x2000
	s_nop 0
	global_load_lds_dwordx4 v[138:139], off
	v_lshl_add_u64 v[138:139], v[218:219], 0, s[56:57]
	s_mov_b32 m0, s26
	s_nop 0
	global_load_lds_dwordx4 v[138:139], off
	v_lshl_add_u64 v[138:139], v[218:219], 0, s[96:97]
	s_mov_b32 m0, s27
	s_nop 0
	global_load_lds_dwordx4 v[138:139], off
	s_waitcnt vmcnt(8)
	s_waitcnt lgkmcnt(0)
	s_barrier
	s_waitcnt lgkmcnt(0)
	v_mfma_f32_16x16x32_bf16 v[60:63], v[134:137], v[176:179], v[60:63]
	v_mfma_f32_16x16x32_bf16 v[52:55], v[152:155], v[176:179], v[52:55]
	v_mfma_f32_16x16x32_bf16 v[44:47], v[134:137], v[194:197], v[44:47]
	v_mfma_f32_16x16x32_bf16 v[36:39], v[152:155], v[194:197], v[36:39]
	v_mfma_f32_16x16x32_bf16 v[28:31], v[134:137], v[202:205], v[28:31]
	v_mfma_f32_16x16x32_bf16 v[20:23], v[152:155], v[202:205], v[20:23]
	v_mfma_f32_16x16x32_bf16 v[12:15], v[134:137], v[210:213], v[12:15]
	v_mfma_f32_16x16x32_bf16 v[4:7], v[152:155], v[210:213], v[4:7]
	v_mfma_f32_16x16x32_bf16 v[60:63], v[148:151], v[180:183], v[60:63]
	v_mfma_f32_16x16x32_bf16 v[52:55], v[156:159], v[180:183], v[52:55]
	v_mfma_f32_16x16x32_bf16 v[44:47], v[148:151], v[198:201], v[44:47]
	v_mfma_f32_16x16x32_bf16 v[36:39], v[156:159], v[198:201], v[36:39]
	v_mfma_f32_16x16x32_bf16 v[28:31], v[148:151], v[206:209], v[28:31]
	v_mfma_f32_16x16x32_bf16 v[20:23], v[156:159], v[206:209], v[20:23]
	v_mfma_f32_16x16x32_bf16 v[12:15], v[148:151], v[214:217], v[12:15]
	v_mfma_f32_16x16x32_bf16 v[4:7], v[156:159], v[214:217], v[4:7]
	v_mfma_f32_16x16x32_bf16 v[56:59], v[160:163], v[176:179], v[56:59]
	v_mfma_f32_16x16x32_bf16 v[48:51], v[168:171], v[176:179], v[48:51]
	v_mfma_f32_16x16x32_bf16 v[40:43], v[160:163], v[194:197], v[40:43]
	v_mfma_f32_16x16x32_bf16 v[32:35], v[168:171], v[194:197], v[32:35]
	v_mfma_f32_16x16x32_bf16 v[24:27], v[160:163], v[202:205], v[24:27]
	v_mfma_f32_16x16x32_bf16 v[16:19], v[168:171], v[202:205], v[16:19]
	v_mfma_f32_16x16x32_bf16 v[8:11], v[160:163], v[210:213], v[8:11]
	v_mfma_f32_16x16x32_bf16 v[0:3], v[168:171], v[210:213], v[0:3]
	v_mfma_f32_16x16x32_bf16 v[56:59], v[164:167], v[180:183], v[56:59]
	v_mfma_f32_16x16x32_bf16 v[48:51], v[172:175], v[180:183], v[48:51]
	v_mfma_f32_16x16x32_bf16 v[40:43], v[164:167], v[198:201], v[40:43]
	v_mfma_f32_16x16x32_bf16 v[32:35], v[172:175], v[198:201], v[32:35]
	v_mfma_f32_16x16x32_bf16 v[24:27], v[164:167], v[206:209], v[24:27]
	v_mfma_f32_16x16x32_bf16 v[16:19], v[172:175], v[206:209], v[16:19]
	v_mfma_f32_16x16x32_bf16 v[8:11], v[164:167], v[214:217], v[8:11]
	v_mfma_f32_16x16x32_bf16 v[0:3], v[172:175], v[214:217], v[0:3]
	s_barrier
	s_add_i32 s51, s51, 2
	s_add_u32 s48, s48, 0x100
	s_addc_u32 s49, s49, 0
	s_add_u32 s16, s16, 0x100
	s_addc_u32 s17, s17, 0
	s_cmp_gt_u32 s51, 13
	s_cbranch_scc0 .LBB0_459
	s_and_b64 vcc, exec, s[10:11]
	s_cbranch_vccz .LBB0_462
	s_barrier

.LBB0_480:
	s_ashr_i32 s41, s40, 31
	s_lshl_b64 s[42:43], s[40:41], 19
	s_add_u32 s42, s64, s42
	s_addc_u32 s43, s65, s43
	s_and_b64 s[44:45], s[38:39], exec
	s_cselect_b32 s31, s43, s17
	s_cselect_b32 s41, s42, s16
	s_ashr_i32 s13, s12, 31
	s_lshl_b64 s[44:45], s[12:13], 19
	s_add_u32 s44, s22, s44
	s_addc_u32 s45, s23, s45
	s_and_b64 s[46:47], s[38:39], exec
	s_cselect_b32 s13, s45, s15
	s_cselect_b32 s48, s44, s14
	s_add_u32 s46, s16, 0x40080
	s_addc_u32 s47, s17, 0
	s_add_u32 s16, s14, 0x100
	s_addc_u32 s17, s15, 0
	s_mov_b32 s49, -2
	s_add_u32 s14, s46, 0xfffc0080
	s_addc_u32 s15, s47, -1
	s_add_i32 s60, 0, 0x10000
	s_cmp_eq_u32 s49, 12
	s_cselect_b32 s15, s31, s15
	s_cselect_b32 s14, s41, s14
	v_add_u32_e32 v135, s60, v143
	s_cselect_b32 s51, s13, s17
	s_cselect_b32 s50, s48, s16
	s_add_i32 s61, 0, 0x14000
	ds_read_b128 v[136:139], v135
	ds_read_b128 v[148:151], v135 offset:1024
	ds_read_b128 v[152:155], v135 offset:2048
	ds_read_b128 v[156:159], v135 offset:3072
	v_add_u32_e32 v135, s61, v143
	ds_read_b128 v[160:163], v135
	ds_read_b128 v[164:167], v135 offset:1024
	ds_read_b128 v[168:171], v135 offset:2048
	ds_read_b128 v[172:175], v135 offset:3072
	v_lshl_add_u64 v[140:141], s[46:47], 0, v[184:185]
	s_add_i32 m0, s19, 0xc000
	ds_read_b128 v[176:179], v147
	ds_read_b128 v[180:183], v147 offset:1024
	ds_read_b128 v[194:197], v147 offset:2048
	ds_read_b128 v[198:201], v147 offset:3072
	ds_read_b128 v[202:205], v147 offset:4096
	ds_read_b128 v[206:209], v147 offset:5120
	ds_read_b128 v[210:213], v147 offset:6144
	ds_read_b128 v[214:217], v147 offset:7168
	global_load_lds_dwordx4 v[140:141], off
	v_lshl_add_u64 v[140:141], v[140:141], 0, s[34:35]
	s_add_i32 m0, s19, 0xe000
	s_nop 0
	global_load_lds_dwordx4 v[140:141], off
	s_waitcnt vmcnt(8)
	s_waitcnt lgkmcnt(0)
	s_barrier
	s_waitcnt lgkmcnt(0)
	v_mfma_f32_16x16x32_bf16 v[124:127], v[136:139], v[176:179], 0
	v_mfma_f32_16x16x32_bf16 v[116:119], v[152:155], v[176:179], 0
	v_mfma_f32_16x16x32_bf16 v[108:111], v[136:139], v[194:197], 0
	v_mfma_f32_16x16x32_bf16 v[100:103], v[152:155], v[194:197], 0
	v_mfma_f32_16x16x32_bf16 v[92:95], v[136:139], v[202:205], 0
	v_mfma_f32_16x16x32_bf16 v[84:87], v[152:155], v[202:205], 0
	v_mfma_f32_16x16x32_bf16 v[76:79], v[136:139], v[210:213], 0
	v_mfma_f32_16x16x32_bf16 v[68:71], v[152:155], v[210:213], 0
	v_mfma_f32_16x16x32_bf16 v[124:127], v[148:151], v[180:183], v[124:127]
	v_mfma_f32_16x16x32_bf16 v[116:119], v[156:159], v[180:183], v[116:119]
	v_mfma_f32_16x16x32_bf16 v[108:111], v[148:151], v[198:201], v[108:111]
	v_mfma_f32_16x16x32_bf16 v[100:103], v[156:159], v[198:201], v[100:103]
	v_mfma_f32_16x16x32_bf16 v[92:95], v[148:151], v[206:209], v[92:95]
	v_mfma_f32_16x16x32_bf16 v[84:87], v[156:159], v[206:209], v[84:87]
	v_mfma_f32_16x16x32_bf16 v[76:79], v[148:151], v[214:217], v[76:79]
	v_mfma_f32_16x16x32_bf16 v[68:71], v[156:159], v[214:217], v[68:71]
	v_mfma_f32_16x16x32_bf16 v[120:123], v[160:163], v[176:179], 0
	v_mfma_f32_16x16x32_bf16 v[112:115], v[168:171], v[176:179], 0
	v_mfma_f32_16x16x32_bf16 v[104:107], v[160:163], v[194:197], 0
	v_mfma_f32_16x16x32_bf16 v[96:99], v[168:171], v[194:197], 0
	v_mfma_f32_16x16x32_bf16 v[88:91], v[160:163], v[202:205], 0
	v_mfma_f32_16x16x32_bf16 v[80:83], v[168:171], v[202:205], 0
	v_mfma_f32_16x16x32_bf16 v[72:75], v[160:163], v[210:213], 0
	v_mfma_f32_16x16x32_bf16 v[64:67], v[168:171], v[210:213], 0
	v_mfma_f32_16x16x32_bf16 v[120:123], v[164:167], v[180:183], v[120:123]
	v_mfma_f32_16x16x32_bf16 v[112:115], v[172:175], v[180:183], v[112:115]
	v_mfma_f32_16x16x32_bf16 v[104:107], v[164:167], v[198:201], v[104:107]
	v_mfma_f32_16x16x32_bf16 v[96:99], v[172:175], v[198:201], v[96:99]
	v_mfma_f32_16x16x32_bf16 v[88:91], v[164:167], v[206:209], v[88:91]
	v_mfma_f32_16x16x32_bf16 v[80:83], v[172:175], v[206:209], v[80:83]
	v_mfma_f32_16x16x32_bf16 v[72:75], v[164:167], v[214:217], v[72:75]
	v_mfma_f32_16x16x32_bf16 v[64:67], v[172:175], v[214:217], v[64:67]
	s_barrier
	v_lshl_add_u64 v[140:141], s[50:51], 0, v[128:129]
	s_add_i32 s50, s60, s6
	s_mov_b32 m0, s50
	ds_read_b128 v[176:179], v147 offset:16384
	ds_read_b128 v[180:183], v147 offset:17408
	ds_read_b128 v[194:197], v147 offset:18432
	ds_read_b128 v[198:201], v147 offset:19456
	ds_read_b128 v[202:205], v147 offset:20480
	ds_read_b128 v[206:209], v147 offset:21504
	ds_read_b128 v[210:213], v147 offset:22528
	ds_read_b128 v[214:217], v147 offset:23552
	global_load_lds_dwordx4 v[140:141], off
	v_lshl_add_u64 v[218:219], v[140:141], 0, s[34:35]
	s_add_i32 m0, s50, 0x2000
	s_add_i32 s50, s61, s6
	global_load_lds_dwordx4 v[218:219], off
	v_lshl_add_u64 v[218:219], v[140:141], 0, s[92:93]
	s_mov_b32 m0, s50
	s_nop 0
	global_load_lds_dwordx4 v[218:219], off
	v_lshl_add_u64 v[218:219], v[140:141], 0, s[52:53]
	s_add_i32 m0, s50, 0x2000
	s_nop 0
	global_load_lds_dwordx4 v[218:219], off
	v_lshl_add_u64 v[218:219], s[14:15], 0, v[130:131]
	s_mov_b32 m0, s19
	v_lshl_add_u64 v[220:221], v[218:219], 0, s[34:35]
	global_load_lds_dwordx4 v[218:219], off
	s_mov_b32 m0, s20
	s_nop 0
	global_load_lds_dwordx4 v[220:221], off
	s_waitcnt vmcnt(8)
	s_waitcnt lgkmcnt(0)
	s_barrier
	s_waitcnt lgkmcnt(0)
	v_mfma_f32_16x16x32_bf16 v[60:63], v[136:139], v[176:179], 0
	v_mfma_f32_16x16x32_bf16 v[52:55], v[152:155], v[176:179], 0
	v_mfma_f32_16x16x32_bf16 v[44:47], v[136:139], v[194:197], 0
	v_mfma_f32_16x16x32_bf16 v[36:39], v[152:155], v[194:197], 0
	v_mfma_f32_16x16x32_bf16 v[28:31], v[136:139], v[202:205], 0
	v_mfma_f32_16x16x32_bf16 v[20:23], v[152:155], v[202:205], 0
	v_mfma_f32_16x16x32_bf16 v[12:15], v[136:139], v[210:213], 0
	v_mfma_f32_16x16x32_bf16 v[4:7], v[152:155], v[210:213], 0
	v_mfma_f32_16x16x32_bf16 v[60:63], v[148:151], v[180:183], v[60:63]
	v_mfma_f32_16x16x32_bf16 v[52:55], v[156:159], v[180:183], v[52:55]
	v_mfma_f32_16x16x32_bf16 v[44:47], v[148:151], v[198:201], v[44:47]
	v_mfma_f32_16x16x32_bf16 v[36:39], v[156:159], v[198:201], v[36:39]
	v_mfma_f32_16x16x32_bf16 v[28:31], v[148:151], v[206:209], v[28:31]
	v_mfma_f32_16x16x32_bf16 v[20:23], v[156:159], v[206:209], v[20:23]
	v_mfma_f32_16x16x32_bf16 v[12:15], v[148:151], v[214:217], v[12:15]
	v_mfma_f32_16x16x32_bf16 v[4:7], v[156:159], v[214:217], v[4:7]
	v_mfma_f32_16x16x32_bf16 v[56:59], v[160:163], v[176:179], 0
	v_mfma_f32_16x16x32_bf16 v[48:51], v[168:171], v[176:179], 0
	v_mfma_f32_16x16x32_bf16 v[40:43], v[160:163], v[194:197], 0
	v_mfma_f32_16x16x32_bf16 v[32:35], v[168:171], v[194:197], 0
	v_mfma_f32_16x16x32_bf16 v[24:27], v[160:163], v[202:205], 0
	v_mfma_f32_16x16x32_bf16 v[16:19], v[168:171], v[202:205], 0
	v_mfma_f32_16x16x32_bf16 v[8:11], v[160:163], v[210:213], 0
	v_mfma_f32_16x16x32_bf16 v[0:3], v[168:171], v[210:213], 0
	v_mfma_f32_16x16x32_bf16 v[56:59], v[164:167], v[180:183], v[56:59]
	v_mfma_f32_16x16x32_bf16 v[48:51], v[172:175], v[180:183], v[48:51]
	v_mfma_f32_16x16x32_bf16 v[40:43], v[164:167], v[198:201], v[40:43]
	v_mfma_f32_16x16x32_bf16 v[32:35], v[172:175], v[198:201], v[32:35]
	v_mfma_f32_16x16x32_bf16 v[24:27], v[164:167], v[206:209], v[24:27]
	v_mfma_f32_16x16x32_bf16 v[16:19], v[172:175], v[206:209], v[16:19]
	v_mfma_f32_16x16x32_bf16 v[8:11], v[164:167], v[214:217], v[8:11]
	v_mfma_f32_16x16x32_bf16 v[0:3], v[172:175], v[214:217], v[0:3]
	s_barrier
	s_add_i32 s14, 0, 0x18000
	v_add_u32_e32 v135, s14, v143
	s_add_i32 s15, 0, 0x1c000
	ds_read_b128 v[136:139], v135
	ds_read_b128 v[148:151], v135 offset:1024
	ds_read_b128 v[152:155], v135 offset:2048
	ds_read_b128 v[156:159], v135 offset:3072
	v_add_u32_e32 v135, s15, v143
	ds_read_b128 v[160:163], v135
	ds_read_b128 v[164:167], v135 offset:1024
	ds_read_b128 v[168:171], v135 offset:2048
	ds_read_b128 v[172:175], v135 offset:3072
	s_mov_b32 m0, s24
	v_lshl_add_u64 v[220:221], v[218:219], 0, s[92:93]
	ds_read_b128 v[176:179], v147 offset:32768
	ds_read_b128 v[180:183], v147 offset:33792
	ds_read_b128 v[194:197], v147 offset:34816
	ds_read_b128 v[198:201], v147 offset:35840
	ds_read_b128 v[202:205], v147 offset:36864
	ds_read_b128 v[206:209], v147 offset:37888
	ds_read_b128 v[210:213], v147 offset:38912
	ds_read_b128 v[214:217], v147 offset:39936
	global_load_lds_dwordx4 v[220:221], off
	v_lshl_add_u64 v[220:221], v[218:219], 0, s[52:53]
	s_mov_b32 m0, s25
	s_nop 0
	global_load_lds_dwordx4 v[220:221], off
	s_waitcnt vmcnt(8)
	s_waitcnt lgkmcnt(0)
	s_barrier
	s_waitcnt lgkmcnt(0)
	v_mfma_f32_16x16x32_bf16 v[124:127], v[136:139], v[176:179], v[124:127]
	v_mfma_f32_16x16x32_bf16 v[116:119], v[152:155], v[176:179], v[116:119]
	v_mfma_f32_16x16x32_bf16 v[108:111], v[136:139], v[194:197], v[108:111]
	v_mfma_f32_16x16x32_bf16 v[100:103], v[152:155], v[194:197], v[100:103]
	v_mfma_f32_16x16x32_bf16 v[92:95], v[136:139], v[202:205], v[92:95]
	v_mfma_f32_16x16x32_bf16 v[84:87], v[152:155], v[202:205], v[84:87]
	v_mfma_f32_16x16x32_bf16 v[76:79], v[136:139], v[210:213], v[76:79]
	v_mfma_f32_16x16x32_bf16 v[68:71], v[152:155], v[210:213], v[68:71]
	v_mfma_f32_16x16x32_bf16 v[124:127], v[148:151], v[180:183], v[124:127]
	v_mfma_f32_16x16x32_bf16 v[116:119], v[156:159], v[180:183], v[116:119]
	v_mfma_f32_16x16x32_bf16 v[108:111], v[148:151], v[198:201], v[108:111]
	v_mfma_f32_16x16x32_bf16 v[100:103], v[156:159], v[198:201], v[100:103]
	v_mfma_f32_16x16x32_bf16 v[92:95], v[148:151], v[206:209], v[92:95]
	v_mfma_f32_16x16x32_bf16 v[84:87], v[156:159], v[206:209], v[84:87]
	v_mfma_f32_16x16x32_bf16 v[76:79], v[148:151], v[214:217], v[76:79]
	v_mfma_f32_16x16x32_bf16 v[68:71], v[156:159], v[214:217], v[68:71]
	v_mfma_f32_16x16x32_bf16 v[120:123], v[160:163], v[176:179], v[120:123]
	v_mfma_f32_16x16x32_bf16 v[112:115], v[168:171], v[176:179], v[112:115]
	v_mfma_f32_16x16x32_bf16 v[104:107], v[160:163], v[194:197], v[104:107]
	v_mfma_f32_16x16x32_bf16 v[96:99], v[168:171], v[194:197], v[96:99]
	v_mfma_f32_16x16x32_bf16 v[88:91], v[160:163], v[202:205], v[88:91]
	v_mfma_f32_16x16x32_bf16 v[80:83], v[168:171], v[202:205], v[80:83]
	v_mfma_f32_16x16x32_bf16 v[72:75], v[160:163], v[210:213], v[72:75]
	v_mfma_f32_16x16x32_bf16 v[64:67], v[168:171], v[210:213], v[64:67]
	v_mfma_f32_16x16x32_bf16 v[120:123], v[164:167], v[180:183], v[120:123]
	v_mfma_f32_16x16x32_bf16 v[112:115], v[172:175], v[180:183], v[112:115]
	v_mfma_f32_16x16x32_bf16 v[104:107], v[164:167], v[198:201], v[104:107]
	v_mfma_f32_16x16x32_bf16 v[96:99], v[172:175], v[198:201], v[96:99]
	v_mfma_f32_16x16x32_bf16 v[88:91], v[164:167], v[206:209], v[88:91]
	v_mfma_f32_16x16x32_bf16 v[80:83], v[172:175], v[206:209], v[80:83]
	v_mfma_f32_16x16x32_bf16 v[72:75], v[164:167], v[214:217], v[72:75]
	v_mfma_f32_16x16x32_bf16 v[64:67], v[172:175], v[214:217], v[64:67]
	s_barrier
	s_add_i32 s14, s14, s6
	v_lshl_add_u64 v[220:221], v[140:141], 0, s[56:57]
	s_mov_b32 m0, s14
	ds_read_b128 v[176:179], v147 offset:49152
	ds_read_b128 v[180:183], v147 offset:50176
	ds_read_b128 v[194:197], v147 offset:51200
	ds_read_b128 v[198:201], v147 offset:52224
	ds_read_b128 v[202:205], v147 offset:53248
	ds_read_b128 v[206:209], v147 offset:54272
	ds_read_b128 v[210:213], v147 offset:55296
	ds_read_b128 v[214:217], v147 offset:56320
	global_load_lds_dwordx4 v[220:221], off
	v_lshl_add_u64 v[220:221], v[140:141], 0, s[96:97]
	s_add_i32 m0, s14, 0x2000
	s_add_i32 s14, s15, s6
	global_load_lds_dwordx4 v[220:221], off
	v_lshl_add_u64 v[220:221], v[140:141], 0, s[88:89]
	s_mov_b32 m0, s14
	v_lshl_add_u64 v[140:141], v[140:141], 0, s[68:69]
	global_load_lds_dwordx4 v[220:221], off
	s_add_i32 m0, s14, 0x2000
	s_nop 0
	global_load_lds_dwordx4 v[140:141], off
	v_lshl_add_u64 v[140:141], v[218:219], 0, s[56:57]
	s_mov_b32 m0, s26
	s_nop 0
	global_load_lds_dwordx4 v[140:141], off
	v_lshl_add_u64 v[140:141], v[218:219], 0, s[96:97]
	s_mov_b32 m0, s27
	s_nop 0
	global_load_lds_dwordx4 v[140:141], off
	s_waitcnt vmcnt(8)
	s_waitcnt lgkmcnt(0)
	s_barrier
	s_waitcnt lgkmcnt(0)
	v_mfma_f32_16x16x32_bf16 v[60:63], v[136:139], v[176:179], v[60:63]
	v_mfma_f32_16x16x32_bf16 v[52:55], v[152:155], v[176:179], v[52:55]
	v_mfma_f32_16x16x32_bf16 v[44:47], v[136:139], v[194:197], v[44:47]
	v_mfma_f32_16x16x32_bf16 v[36:39], v[152:155], v[194:197], v[36:39]
	v_mfma_f32_16x16x32_bf16 v[28:31], v[136:139], v[202:205], v[28:31]
	v_mfma_f32_16x16x32_bf16 v[20:23], v[152:155], v[202:205], v[20:23]
	v_mfma_f32_16x16x32_bf16 v[12:15], v[136:139], v[210:213], v[12:15]
	v_mfma_f32_16x16x32_bf16 v[4:7], v[152:155], v[210:213], v[4:7]
	v_mfma_f32_16x16x32_bf16 v[60:63], v[148:151], v[180:183], v[60:63]
	v_mfma_f32_16x16x32_bf16 v[52:55], v[156:159], v[180:183], v[52:55]
	v_mfma_f32_16x16x32_bf16 v[44:47], v[148:151], v[198:201], v[44:47]
	v_mfma_f32_16x16x32_bf16 v[36:39], v[156:159], v[198:201], v[36:39]
	v_mfma_f32_16x16x32_bf16 v[28:31], v[148:151], v[206:209], v[28:31]
	v_mfma_f32_16x16x32_bf16 v[20:23], v[156:159], v[206:209], v[20:23]
	v_mfma_f32_16x16x32_bf16 v[12:15], v[148:151], v[214:217], v[12:15]
	v_mfma_f32_16x16x32_bf16 v[4:7], v[156:159], v[214:217], v[4:7]
	v_mfma_f32_16x16x32_bf16 v[56:59], v[160:163], v[176:179], v[56:59]
	v_mfma_f32_16x16x32_bf16 v[48:51], v[168:171], v[176:179], v[48:51]
	v_mfma_f32_16x16x32_bf16 v[40:43], v[160:163], v[194:197], v[40:43]
	v_mfma_f32_16x16x32_bf16 v[32:35], v[168:171], v[194:197], v[32:35]
	v_mfma_f32_16x16x32_bf16 v[24:27], v[160:163], v[202:205], v[24:27]
	v_mfma_f32_16x16x32_bf16 v[16:19], v[168:171], v[202:205], v[16:19]
	v_mfma_f32_16x16x32_bf16 v[8:11], v[160:163], v[210:213], v[8:11]
	v_mfma_f32_16x16x32_bf16 v[0:3], v[168:171], v[210:213], v[0:3]
	v_mfma_f32_16x16x32_bf16 v[56:59], v[164:167], v[180:183], v[56:59]
	v_mfma_f32_16x16x32_bf16 v[48:51], v[172:175], v[180:183], v[48:51]
	v_mfma_f32_16x16x32_bf16 v[40:43], v[164:167], v[198:201], v[40:43]
	v_mfma_f32_16x16x32_bf16 v[32:35], v[172:175], v[198:201], v[32:35]
	v_mfma_f32_16x16x32_bf16 v[24:27], v[164:167], v[206:209], v[24:27]
	v_mfma_f32_16x16x32_bf16 v[16:19], v[172:175], v[206:209], v[16:19]
	v_mfma_f32_16x16x32_bf16 v[8:11], v[164:167], v[214:217], v[8:11]
	v_mfma_f32_16x16x32_bf16 v[0:3], v[172:175], v[214:217], v[0:3]
	s_barrier
	s_add_i32 s49, s49, 2
	s_add_u32 s46, s46, 0x100
	s_addc_u32 s47, s47, 0
	s_add_u32 s16, s16, 0x100
	s_addc_u32 s17, s17, 0
	s_cmp_gt_u32 s49, 13
.LBB0_481:
	s_add_u32 s14, s46, 0xfffc0080
	s_addc_u32 s15, s47, -1
	s_add_i32 s60, 0, 0x10000
	s_cmp_eq_u32 s49, 12
	s_cselect_b32 s15, s31, s15
	s_cselect_b32 s14, s41, s14
	v_add_u32_e32 v135, s60, v143
	s_cselect_b32 s51, s13, s17
	s_cselect_b32 s50, s48, s16
	s_add_i32 s61, 0, 0x14000
	ds_read_b128 v[136:139], v135
	ds_read_b128 v[148:151], v135 offset:1024
	ds_read_b128 v[152:155], v135 offset:2048
	ds_read_b128 v[156:159], v135 offset:3072
	v_add_u32_e32 v135, s61, v143
	ds_read_b128 v[160:163], v135
	ds_read_b128 v[164:167], v135 offset:1024
	ds_read_b128 v[168:171], v135 offset:2048
	ds_read_b128 v[172:175], v135 offset:3072
	v_lshl_add_u64 v[140:141], s[46:47], 0, v[184:185]
	s_add_i32 m0, s19, 0xc000
	ds_read_b128 v[176:179], v147
	ds_read_b128 v[180:183], v147 offset:1024
	ds_read_b128 v[194:197], v147 offset:2048
	ds_read_b128 v[198:201], v147 offset:3072
	ds_read_b128 v[202:205], v147 offset:4096
	ds_read_b128 v[206:209], v147 offset:5120
	ds_read_b128 v[210:213], v147 offset:6144
	ds_read_b128 v[214:217], v147 offset:7168
	global_load_lds_dwordx4 v[140:141], off
	v_lshl_add_u64 v[140:141], v[140:141], 0, s[34:35]
	s_add_i32 m0, s19, 0xe000
	s_nop 0
	global_load_lds_dwordx4 v[140:141], off
	s_waitcnt vmcnt(8)
	s_waitcnt lgkmcnt(0)
	s_barrier
	s_waitcnt lgkmcnt(0)
	v_mfma_f32_16x16x32_bf16 v[124:127], v[136:139], v[176:179], v[124:127]
	v_mfma_f32_16x16x32_bf16 v[116:119], v[152:155], v[176:179], v[116:119]
	v_mfma_f32_16x16x32_bf16 v[108:111], v[136:139], v[194:197], v[108:111]
	v_mfma_f32_16x16x32_bf16 v[100:103], v[152:155], v[194:197], v[100:103]
	v_mfma_f32_16x16x32_bf16 v[92:95], v[136:139], v[202:205], v[92:95]
	v_mfma_f32_16x16x32_bf16 v[84:87], v[152:155], v[202:205], v[84:87]
	v_mfma_f32_16x16x32_bf16 v[76:79], v[136:139], v[210:213], v[76:79]
	v_mfma_f32_16x16x32_bf16 v[68:71], v[152:155], v[210:213], v[68:71]
	v_mfma_f32_16x16x32_bf16 v[124:127], v[148:151], v[180:183], v[124:127]
	v_mfma_f32_16x16x32_bf16 v[116:119], v[156:159], v[180:183], v[116:119]
	v_mfma_f32_16x16x32_bf16 v[108:111], v[148:151], v[198:201], v[108:111]
	v_mfma_f32_16x16x32_bf16 v[100:103], v[156:159], v[198:201], v[100:103]
	v_mfma_f32_16x16x32_bf16 v[92:95], v[148:151], v[206:209], v[92:95]
	v_mfma_f32_16x16x32_bf16 v[84:87], v[156:159], v[206:209], v[84:87]
	v_mfma_f32_16x16x32_bf16 v[76:79], v[148:151], v[214:217], v[76:79]
	v_mfma_f32_16x16x32_bf16 v[68:71], v[156:159], v[214:217], v[68:71]
	v_mfma_f32_16x16x32_bf16 v[120:123], v[160:163], v[176:179], v[120:123]
	v_mfma_f32_16x16x32_bf16 v[112:115], v[168:171], v[176:179], v[112:115]
	v_mfma_f32_16x16x32_bf16 v[104:107], v[160:163], v[194:197], v[104:107]
	v_mfma_f32_16x16x32_bf16 v[96:99], v[168:171], v[194:197], v[96:99]
	v_mfma_f32_16x16x32_bf16 v[88:91], v[160:163], v[202:205], v[88:91]
	v_mfma_f32_16x16x32_bf16 v[80:83], v[168:171], v[202:205], v[80:83]
	v_mfma_f32_16x16x32_bf16 v[72:75], v[160:163], v[210:213], v[72:75]
	v_mfma_f32_16x16x32_bf16 v[64:67], v[168:171], v[210:213], v[64:67]
	v_mfma_f32_16x16x32_bf16 v[120:123], v[164:167], v[180:183], v[120:123]
	v_mfma_f32_16x16x32_bf16 v[112:115], v[172:175], v[180:183], v[112:115]
	v_mfma_f32_16x16x32_bf16 v[104:107], v[164:167], v[198:201], v[104:107]
	v_mfma_f32_16x16x32_bf16 v[96:99], v[172:175], v[198:201], v[96:99]
	v_mfma_f32_16x16x32_bf16 v[88:91], v[164:167], v[206:209], v[88:91]
	v_mfma_f32_16x16x32_bf16 v[80:83], v[172:175], v[206:209], v[80:83]
	v_mfma_f32_16x16x32_bf16 v[72:75], v[164:167], v[214:217], v[72:75]
	v_mfma_f32_16x16x32_bf16 v[64:67], v[172:175], v[214:217], v[64:67]
	s_barrier
	v_lshl_add_u64 v[140:141], s[50:51], 0, v[128:129]
	s_add_i32 s50, s60, s6
	s_mov_b32 m0, s50
	ds_read_b128 v[176:179], v147 offset:16384
	ds_read_b128 v[180:183], v147 offset:17408
	ds_read_b128 v[194:197], v147 offset:18432
	ds_read_b128 v[198:201], v147 offset:19456
	ds_read_b128 v[202:205], v147 offset:20480
	ds_read_b128 v[206:209], v147 offset:21504
	ds_read_b128 v[210:213], v147 offset:22528
	ds_read_b128 v[214:217], v147 offset:23552
	global_load_lds_dwordx4 v[140:141], off
	v_lshl_add_u64 v[218:219], v[140:141], 0, s[34:35]
	s_add_i32 m0, s50, 0x2000
	s_add_i32 s50, s61, s6
	global_load_lds_dwordx4 v[218:219], off
	v_lshl_add_u64 v[218:219], v[140:141], 0, s[92:93]
	s_mov_b32 m0, s50
	s_nop 0
	global_load_lds_dwordx4 v[218:219], off
	v_lshl_add_u64 v[218:219], v[140:141], 0, s[52:53]
	s_add_i32 m0, s50, 0x2000
	s_nop 0
	global_load_lds_dwordx4 v[218:219], off
	v_lshl_add_u64 v[218:219], s[14:15], 0, v[130:131]
	s_mov_b32 m0, s19
	v_lshl_add_u64 v[220:221], v[218:219], 0, s[34:35]
	global_load_lds_dwordx4 v[218:219], off
	s_mov_b32 m0, s20
	s_nop 0
	global_load_lds_dwordx4 v[220:221], off
	s_waitcnt vmcnt(8)
	s_waitcnt lgkmcnt(0)
	s_barrier
	s_waitcnt lgkmcnt(0)
	v_mfma_f32_16x16x32_bf16 v[60:63], v[136:139], v[176:179], v[60:63]
	v_mfma_f32_16x16x32_bf16 v[52:55], v[152:155], v[176:179], v[52:55]
	v_mfma_f32_16x16x32_bf16 v[44:47], v[136:139], v[194:197], v[44:47]
	v_mfma_f32_16x16x32_bf16 v[36:39], v[152:155], v[194:197], v[36:39]
	v_mfma_f32_16x16x32_bf16 v[28:31], v[136:139], v[202:205], v[28:31]
	v_mfma_f32_16x16x32_bf16 v[20:23], v[152:155], v[202:205], v[20:23]
	v_mfma_f32_16x16x32_bf16 v[12:15], v[136:139], v[210:213], v[12:15]
	v_mfma_f32_16x16x32_bf16 v[4:7], v[152:155], v[210:213], v[4:7]
	v_mfma_f32_16x16x32_bf16 v[60:63], v[148:151], v[180:183], v[60:63]
	v_mfma_f32_16x16x32_bf16 v[52:55], v[156:159], v[180:183], v[52:55]
	v_mfma_f32_16x16x32_bf16 v[44:47], v[148:151], v[198:201], v[44:47]
	v_mfma_f32_16x16x32_bf16 v[36:39], v[156:159], v[198:201], v[36:39]
	v_mfma_f32_16x16x32_bf16 v[28:31], v[148:151], v[206:209], v[28:31]
	v_mfma_f32_16x16x32_bf16 v[20:23], v[156:159], v[206:209], v[20:23]
	v_mfma_f32_16x16x32_bf16 v[12:15], v[148:151], v[214:217], v[12:15]
	v_mfma_f32_16x16x32_bf16 v[4:7], v[156:159], v[214:217], v[4:7]
	v_mfma_f32_16x16x32_bf16 v[56:59], v[160:163], v[176:179], v[56:59]
	v_mfma_f32_16x16x32_bf16 v[48:51], v[168:171], v[176:179], v[48:51]
	v_mfma_f32_16x16x32_bf16 v[40:43], v[160:163], v[194:197], v[40:43]
	v_mfma_f32_16x16x32_bf16 v[32:35], v[168:171], v[194:197], v[32:35]
	v_mfma_f32_16x16x32_bf16 v[24:27], v[160:163], v[202:205], v[24:27]
	v_mfma_f32_16x16x32_bf16 v[16:19], v[168:171], v[202:205], v[16:19]
	v_mfma_f32_16x16x32_bf16 v[8:11], v[160:163], v[210:213], v[8:11]
	v_mfma_f32_16x16x32_bf16 v[0:3], v[168:171], v[210:213], v[0:3]
	v_mfma_f32_16x16x32_bf16 v[56:59], v[164:167], v[180:183], v[56:59]
	v_mfma_f32_16x16x32_bf16 v[48:51], v[172:175], v[180:183], v[48:51]
	v_mfma_f32_16x16x32_bf16 v[40:43], v[164:167], v[198:201], v[40:43]
	v_mfma_f32_16x16x32_bf16 v[32:35], v[172:175], v[198:201], v[32:35]
	v_mfma_f32_16x16x32_bf16 v[24:27], v[164:167], v[206:209], v[24:27]
	v_mfma_f32_16x16x32_bf16 v[16:19], v[172:175], v[206:209], v[16:19]
	v_mfma_f32_16x16x32_bf16 v[8:11], v[164:167], v[214:217], v[8:11]
	v_mfma_f32_16x16x32_bf16 v[0:3], v[172:175], v[214:217], v[0:3]
	s_barrier
	s_add_i32 s14, 0, 0x18000
	v_add_u32_e32 v135, s14, v143
	s_add_i32 s15, 0, 0x1c000
	ds_read_b128 v[136:139], v135
	ds_read_b128 v[148:151], v135 offset:1024
	ds_read_b128 v[152:155], v135 offset:2048
	ds_read_b128 v[156:159], v135 offset:3072
	v_add_u32_e32 v135, s15, v143
	ds_read_b128 v[160:163], v135
	ds_read_b128 v[164:167], v135 offset:1024
	ds_read_b128 v[168:171], v135 offset:2048
	ds_read_b128 v[172:175], v135 offset:3072
	s_mov_b32 m0, s24
	v_lshl_add_u64 v[220:221], v[218:219], 0, s[92:93]
	ds_read_b128 v[176:179], v147 offset:32768
	ds_read_b128 v[180:183], v147 offset:33792
	ds_read_b128 v[194:197], v147 offset:34816
	ds_read_b128 v[198:201], v147 offset:35840
	ds_read_b128 v[202:205], v147 offset:36864
	ds_read_b128 v[206:209], v147 offset:37888
	ds_read_b128 v[210:213], v147 offset:38912
	ds_read_b128 v[214:217], v147 offset:39936
	global_load_lds_dwordx4 v[220:221], off
	v_lshl_add_u64 v[220:221], v[218:219], 0, s[52:53]
	s_mov_b32 m0, s25
	s_nop 0
	global_load_lds_dwordx4 v[220:221], off
	s_waitcnt vmcnt(8)
	s_waitcnt lgkmcnt(0)
	s_barrier
	s_waitcnt lgkmcnt(0)
	v_mfma_f32_16x16x32_bf16 v[124:127], v[136:139], v[176:179], v[124:127]
	v_mfma_f32_16x16x32_bf16 v[116:119], v[152:155], v[176:179], v[116:119]
	v_mfma_f32_16x16x32_bf16 v[108:111], v[136:139], v[194:197], v[108:111]
	v_mfma_f32_16x16x32_bf16 v[100:103], v[152:155], v[194:197], v[100:103]
	v_mfma_f32_16x16x32_bf16 v[92:95], v[136:139], v[202:205], v[92:95]
	v_mfma_f32_16x16x32_bf16 v[84:87], v[152:155], v[202:205], v[84:87]
	v_mfma_f32_16x16x32_bf16 v[76:79], v[136:139], v[210:213], v[76:79]
	v_mfma_f32_16x16x32_bf16 v[68:71], v[152:155], v[210:213], v[68:71]
	v_mfma_f32_16x16x32_bf16 v[124:127], v[148:151], v[180:183], v[124:127]
	v_mfma_f32_16x16x32_bf16 v[116:119], v[156:159], v[180:183], v[116:119]
	v_mfma_f32_16x16x32_bf16 v[108:111], v[148:151], v[198:201], v[108:111]
	v_mfma_f32_16x16x32_bf16 v[100:103], v[156:159], v[198:201], v[100:103]
	v_mfma_f32_16x16x32_bf16 v[92:95], v[148:151], v[206:209], v[92:95]
	v_mfma_f32_16x16x32_bf16 v[84:87], v[156:159], v[206:209], v[84:87]
	v_mfma_f32_16x16x32_bf16 v[76:79], v[148:151], v[214:217], v[76:79]
	v_mfma_f32_16x16x32_bf16 v[68:71], v[156:159], v[214:217], v[68:71]
	v_mfma_f32_16x16x32_bf16 v[120:123], v[160:163], v[176:179], v[120:123]
	v_mfma_f32_16x16x32_bf16 v[112:115], v[168:171], v[176:179], v[112:115]
	v_mfma_f32_16x16x32_bf16 v[104:107], v[160:163], v[194:197], v[104:107]
	v_mfma_f32_16x16x32_bf16 v[96:99], v[168:171], v[194:197], v[96:99]
	v_mfma_f32_16x16x32_bf16 v[88:91], v[160:163], v[202:205], v[88:91]
	v_mfma_f32_16x16x32_bf16 v[80:83], v[168:171], v[202:205], v[80:83]
	v_mfma_f32_16x16x32_bf16 v[72:75], v[160:163], v[210:213], v[72:75]
	v_mfma_f32_16x16x32_bf16 v[64:67], v[168:171], v[210:213], v[64:67]
	v_mfma_f32_16x16x32_bf16 v[120:123], v[164:167], v[180:183], v[120:123]
	v_mfma_f32_16x16x32_bf16 v[112:115], v[172:175], v[180:183], v[112:115]
	v_mfma_f32_16x16x32_bf16 v[104:107], v[164:167], v[198:201], v[104:107]
	v_mfma_f32_16x16x32_bf16 v[96:99], v[172:175], v[198:201], v[96:99]
	v_mfma_f32_16x16x32_bf16 v[88:91], v[164:167], v[206:209], v[88:91]
	v_mfma_f32_16x16x32_bf16 v[80:83], v[172:175], v[206:209], v[80:83]
	v_mfma_f32_16x16x32_bf16 v[72:75], v[164:167], v[214:217], v[72:75]
	v_mfma_f32_16x16x32_bf16 v[64:67], v[172:175], v[214:217], v[64:67]
	s_barrier
	s_add_i32 s14, s14, s6
	v_lshl_add_u64 v[220:221], v[140:141], 0, s[56:57]
	s_mov_b32 m0, s14
	ds_read_b128 v[176:179], v147 offset:49152
	ds_read_b128 v[180:183], v147 offset:50176
	ds_read_b128 v[194:197], v147 offset:51200
	ds_read_b128 v[198:201], v147 offset:52224
	ds_read_b128 v[202:205], v147 offset:53248
	ds_read_b128 v[206:209], v147 offset:54272
	ds_read_b128 v[210:213], v147 offset:55296
	ds_read_b128 v[214:217], v147 offset:56320
	global_load_lds_dwordx4 v[220:221], off
	v_lshl_add_u64 v[220:221], v[140:141], 0, s[96:97]
	s_add_i32 m0, s14, 0x2000
	s_add_i32 s14, s15, s6
	global_load_lds_dwordx4 v[220:221], off
	v_lshl_add_u64 v[220:221], v[140:141], 0, s[88:89]
	s_mov_b32 m0, s14
	v_lshl_add_u64 v[140:141], v[140:141], 0, s[68:69]
	global_load_lds_dwordx4 v[220:221], off
	s_add_i32 m0, s14, 0x2000
	s_nop 0
	global_load_lds_dwordx4 v[140:141], off
	v_lshl_add_u64 v[140:141], v[218:219], 0, s[56:57]
	s_mov_b32 m0, s26
	s_nop 0
	global_load_lds_dwordx4 v[140:141], off
	v_lshl_add_u64 v[140:141], v[218:219], 0, s[96:97]
	s_mov_b32 m0, s27
	s_nop 0
	global_load_lds_dwordx4 v[140:141], off
	s_waitcnt vmcnt(8)
	s_waitcnt lgkmcnt(0)
	s_barrier
	s_waitcnt lgkmcnt(0)
	v_mfma_f32_16x16x32_bf16 v[60:63], v[136:139], v[176:179], v[60:63]
	v_mfma_f32_16x16x32_bf16 v[52:55], v[152:155], v[176:179], v[52:55]
	v_mfma_f32_16x16x32_bf16 v[44:47], v[136:139], v[194:197], v[44:47]
	v_mfma_f32_16x16x32_bf16 v[36:39], v[152:155], v[194:197], v[36:39]
	v_mfma_f32_16x16x32_bf16 v[28:31], v[136:139], v[202:205], v[28:31]
	v_mfma_f32_16x16x32_bf16 v[20:23], v[152:155], v[202:205], v[20:23]
	v_mfma_f32_16x16x32_bf16 v[12:15], v[136:139], v[210:213], v[12:15]
	v_mfma_f32_16x16x32_bf16 v[4:7], v[152:155], v[210:213], v[4:7]
	v_mfma_f32_16x16x32_bf16 v[60:63], v[148:151], v[180:183], v[60:63]
	v_mfma_f32_16x16x32_bf16 v[52:55], v[156:159], v[180:183], v[52:55]
	v_mfma_f32_16x16x32_bf16 v[44:47], v[148:151], v[198:201], v[44:47]
	v_mfma_f32_16x16x32_bf16 v[36:39], v[156:159], v[198:201], v[36:39]
	v_mfma_f32_16x16x32_bf16 v[28:31], v[148:151], v[206:209], v[28:31]
	v_mfma_f32_16x16x32_bf16 v[20:23], v[156:159], v[206:209], v[20:23]
	v_mfma_f32_16x16x32_bf16 v[12:15], v[148:151], v[214:217], v[12:15]
	v_mfma_f32_16x16x32_bf16 v[4:7], v[156:159], v[214:217], v[4:7]
	v_mfma_f32_16x16x32_bf16 v[56:59], v[160:163], v[176:179], v[56:59]
	v_mfma_f32_16x16x32_bf16 v[48:51], v[168:171], v[176:179], v[48:51]
	v_mfma_f32_16x16x32_bf16 v[40:43], v[160:163], v[194:197], v[40:43]
	v_mfma_f32_16x16x32_bf16 v[32:35], v[168:171], v[194:197], v[32:35]
	v_mfma_f32_16x16x32_bf16 v[24:27], v[160:163], v[202:205], v[24:27]
	v_mfma_f32_16x16x32_bf16 v[16:19], v[168:171], v[202:205], v[16:19]
	v_mfma_f32_16x16x32_bf16 v[8:11], v[160:163], v[210:213], v[8:11]
	v_mfma_f32_16x16x32_bf16 v[0:3], v[168:171], v[210:213], v[0:3]
	v_mfma_f32_16x16x32_bf16 v[56:59], v[164:167], v[180:183], v[56:59]
	v_mfma_f32_16x16x32_bf16 v[48:51], v[172:175], v[180:183], v[48:51]
	v_mfma_f32_16x16x32_bf16 v[40:43], v[164:167], v[198:201], v[40:43]
	v_mfma_f32_16x16x32_bf16 v[32:35], v[172:175], v[198:201], v[32:35]
	v_mfma_f32_16x16x32_bf16 v[24:27], v[164:167], v[206:209], v[24:27]
	v_mfma_f32_16x16x32_bf16 v[16:19], v[172:175], v[206:209], v[16:19]
	v_mfma_f32_16x16x32_bf16 v[8:11], v[164:167], v[214:217], v[8:11]
	v_mfma_f32_16x16x32_bf16 v[0:3], v[172:175], v[214:217], v[0:3]
	s_barrier
	s_add_i32 s49, s49, 2
	s_add_u32 s46, s46, 0x100
	s_addc_u32 s47, s47, 0
	s_add_u32 s16, s16, 0x100
	s_addc_u32 s17, s17, 0
	s_cmp_gt_u32 s49, 13
	s_cbranch_scc0 .LBB0_481
	s_and_b64 vcc, exec, s[10:11]
	s_cbranch_vccz .LBB0_484
	s_barrier

.LBB0_502:
	s_ashr_i32 s13, s12, 31
	s_lshl_b64 s[42:43], s[12:13], 18
	s_add_u32 s42, s54, s42
	s_addc_u32 s43, s55, s43
	s_and_b64 s[44:45], s[40:41], exec
	s_cselect_b32 s13, s43, s17
	s_cselect_b32 s31, s42, s16
	s_ashr_i32 s11, s10, 31
	s_lshl_b64 s[44:45], s[10:11], 18
	s_add_u32 s44, s22, s44
	s_addc_u32 s45, s23, s45
	s_and_b64 s[46:47], s[40:41], exec
	s_cselect_b32 s11, s45, s15
	s_cselect_b32 s48, s44, s14
	s_add_u32 s46, s16, 0x20080
	s_addc_u32 s47, s17, 0
	s_add_u32 s49, s14, 0x100
	s_addc_u32 s50, s15, 0
	s_mov_b32 s51, -2
	s_add_u32 s14, s46, 0xfffe0080
	s_addc_u32 s15, s47, -1
	s_add_i32 s60, 0, 0x10000
	s_cmp_eq_u32 s51, 4
	s_cselect_b32 s15, s13, s15
	s_cselect_b32 s14, s31, s14
	s_cselect_b32 s17, s11, s50
	s_cselect_b32 s16, s48, s49
	s_add_i32 s61, 0, 0x14000
	v_add_u32_e32 v0, s60, v172
	v_add_u32_e32 v4, s61, v172
	ds_read_b128 v[24:27], v0
	ds_read_b128 v[28:31], v0 offset:1024
	ds_read_b128 v[16:19], v0 offset:2048
	ds_read_b128 v[20:23], v0 offset:3072
	ds_read_b128 v[8:11], v4
	ds_read_b128 v[12:15], v4 offset:1024
	ds_read_b128 v[0:3], v4 offset:2048
	ds_read_b128 v[4:7], v4 offset:3072
	v_lshl_add_u64 v[166:167], s[46:47], 0, v[164:165]
	s_add_i32 m0, s19, 0xc000
	ds_read_b128 v[194:197], v176
	ds_read_b128 v[198:201], v176 offset:1024
	ds_read_b128 v[202:205], v176 offset:2048
	ds_read_b128 v[206:209], v176 offset:3072
	ds_read_b128 v[210:213], v176 offset:4096
	ds_read_b128 v[214:217], v176 offset:5120
	ds_read_b128 v[218:221], v176 offset:6144
	ds_read_b128 v[222:225], v176 offset:7168
	global_load_lds_dwordx4 v[166:167], off
	v_lshl_add_u64 v[166:167], v[166:167], 0, s[94:95]
	s_add_i32 m0, s19, 0xe000
	s_nop 0
	global_load_lds_dwordx4 v[166:167], off
	s_waitcnt vmcnt(8)
	s_waitcnt lgkmcnt(0)
	s_barrier
	s_waitcnt lgkmcnt(0)
	v_mfma_scale_f32_16x16x128_f8f6f4 v[156:159], v[24:31], v[194:201], 0, v240, v240 op_sel_hi:[0,0,0]
	v_mfma_scale_f32_16x16x128_f8f6f4 v[148:151], v[16:23], v[194:201], 0, v240, v240 op_sel_hi:[0,0,0]
	v_mfma_scale_f32_16x16x128_f8f6f4 v[140:143], v[24:31], v[202:209], 0, v240, v240 op_sel_hi:[0,0,0]
	v_mfma_scale_f32_16x16x128_f8f6f4 v[132:135], v[16:23], v[202:209], 0, v240, v240 op_sel_hi:[0,0,0]
	v_mfma_scale_f32_16x16x128_f8f6f4 v[124:127], v[24:31], v[210:217], 0, v240, v240 op_sel_hi:[0,0,0]
	v_mfma_scale_f32_16x16x128_f8f6f4 v[116:119], v[16:23], v[210:217], 0, v240, v240 op_sel_hi:[0,0,0]
	v_mfma_scale_f32_16x16x128_f8f6f4 v[108:111], v[24:31], v[218:225], 0, v240, v240 op_sel_hi:[0,0,0]
	v_mfma_scale_f32_16x16x128_f8f6f4 v[100:103], v[16:23], v[218:225], 0, v240, v240 op_sel_hi:[0,0,0]
	v_mfma_scale_f32_16x16x128_f8f6f4 v[152:155], v[8:15], v[194:201], 0, v240, v240 op_sel_hi:[0,0,0]
	v_mfma_scale_f32_16x16x128_f8f6f4 v[144:147], v[0:7], v[194:201], 0, v240, v240 op_sel_hi:[0,0,0]
	v_mfma_scale_f32_16x16x128_f8f6f4 v[136:139], v[8:15], v[202:209], 0, v240, v240 op_sel_hi:[0,0,0]
	v_mfma_scale_f32_16x16x128_f8f6f4 v[128:131], v[0:7], v[202:209], 0, v240, v240 op_sel_hi:[0,0,0]
	v_mfma_scale_f32_16x16x128_f8f6f4 v[120:123], v[8:15], v[210:217], 0, v240, v240 op_sel_hi:[0,0,0]
	v_mfma_scale_f32_16x16x128_f8f6f4 v[112:115], v[0:7], v[210:217], 0, v240, v240 op_sel_hi:[0,0,0]
	v_mfma_scale_f32_16x16x128_f8f6f4 v[104:107], v[8:15], v[218:225], 0, v240, v240 op_sel_hi:[0,0,0]
	v_mfma_scale_f32_16x16x128_f8f6f4 v[96:99], v[0:7], v[218:225], 0, v240, v240 op_sel_hi:[0,0,0]
	s_barrier
	v_lshl_add_u64 v[166:167], s[16:17], 0, v[184:185]
	s_add_i32 s16, s60, s6
	s_mov_b32 m0, s16
	ds_read_b128 v[194:197], v176 offset:16384
	ds_read_b128 v[198:201], v176 offset:17408
	ds_read_b128 v[202:205], v176 offset:18432
	ds_read_b128 v[206:209], v176 offset:19456
	ds_read_b128 v[210:213], v176 offset:20480
	ds_read_b128 v[214:217], v176 offset:21504
	ds_read_b128 v[218:221], v176 offset:22528
	ds_read_b128 v[222:225], v176 offset:23552
	global_load_lds_dwordx4 v[166:167], off
	v_lshl_add_u64 v[168:169], v[166:167], 0, s[94:95]
	s_add_i32 m0, s16, 0x2000
	s_add_i32 s16, s61, s6
	global_load_lds_dwordx4 v[168:169], off
	v_lshl_add_u64 v[168:169], v[166:167], 0, s[34:35]
	s_mov_b32 m0, s16
	s_nop 0
	global_load_lds_dwordx4 v[168:169], off
	v_lshl_add_u64 v[168:169], v[166:167], 0, s[90:91]
	s_add_i32 m0, s16, 0x2000
	s_nop 0
	global_load_lds_dwordx4 v[168:169], off
	v_lshl_add_u64 v[168:169], s[14:15], 0, v[160:161]
	s_mov_b32 m0, s19
	v_lshl_add_u64 v[178:179], v[168:169], 0, s[94:95]
	global_load_lds_dwordx4 v[168:169], off
	s_mov_b32 m0, s20
	s_nop 0
	global_load_lds_dwordx4 v[178:179], off
	s_waitcnt vmcnt(8)
	s_waitcnt lgkmcnt(0)
	s_barrier
	s_waitcnt lgkmcnt(0)
	v_mfma_scale_f32_16x16x128_f8f6f4 v[92:95], v[24:31], v[194:201], 0, v240, v240 op_sel_hi:[0,0,0]
	v_mfma_scale_f32_16x16x128_f8f6f4 v[84:87], v[16:23], v[194:201], 0, v240, v240 op_sel_hi:[0,0,0]
	v_mfma_scale_f32_16x16x128_f8f6f4 v[76:79], v[24:31], v[202:209], 0, v240, v240 op_sel_hi:[0,0,0]
	v_mfma_scale_f32_16x16x128_f8f6f4 v[68:71], v[16:23], v[202:209], 0, v240, v240 op_sel_hi:[0,0,0]
	v_mfma_scale_f32_16x16x128_f8f6f4 v[60:63], v[24:31], v[210:217], 0, v240, v240 op_sel_hi:[0,0,0]
	v_mfma_scale_f32_16x16x128_f8f6f4 v[52:55], v[16:23], v[210:217], 0, v240, v240 op_sel_hi:[0,0,0]
	v_mfma_scale_f32_16x16x128_f8f6f4 v[44:47], v[24:31], v[218:225], 0, v240, v240 op_sel_hi:[0,0,0]
	v_mfma_scale_f32_16x16x128_f8f6f4 v[36:39], v[16:23], v[218:225], 0, v240, v240 op_sel_hi:[0,0,0]
	v_mfma_scale_f32_16x16x128_f8f6f4 v[88:91], v[8:15], v[194:201], 0, v240, v240 op_sel_hi:[0,0,0]
	v_mfma_scale_f32_16x16x128_f8f6f4 v[80:83], v[0:7], v[194:201], 0, v240, v240 op_sel_hi:[0,0,0]
	v_mfma_scale_f32_16x16x128_f8f6f4 v[72:75], v[8:15], v[202:209], 0, v240, v240 op_sel_hi:[0,0,0]
	v_mfma_scale_f32_16x16x128_f8f6f4 v[64:67], v[0:7], v[202:209], 0, v240, v240 op_sel_hi:[0,0,0]
	v_mfma_scale_f32_16x16x128_f8f6f4 v[56:59], v[8:15], v[210:217], 0, v240, v240 op_sel_hi:[0,0,0]
	v_mfma_scale_f32_16x16x128_f8f6f4 v[48:51], v[0:7], v[210:217], 0, v240, v240 op_sel_hi:[0,0,0]
	v_mfma_scale_f32_16x16x128_f8f6f4 v[40:43], v[8:15], v[218:225], 0, v240, v240 op_sel_hi:[0,0,0]
	v_mfma_scale_f32_16x16x128_f8f6f4 v[32:35], v[0:7], v[218:225], 0, v240, v240 op_sel_hi:[0,0,0]
	s_barrier
	s_add_i32 s14, 0, 0x18000
	s_add_i32 s15, 0, 0x1c000
	v_add_u32_e32 v12, s14, v172
	v_add_u32_e32 v28, s15, v172
	ds_read_b128 v[0:3], v12
	ds_read_b128 v[4:7], v12 offset:1024
	ds_read_b128 v[8:11], v12 offset:2048
	ds_read_b128 v[12:15], v12 offset:3072
	ds_read_b128 v[16:19], v28
	ds_read_b128 v[20:23], v28 offset:1024
	ds_read_b128 v[24:27], v28 offset:2048
	ds_read_b128 v[28:31], v28 offset:3072
	s_mov_b32 m0, s24
	v_lshl_add_u64 v[178:179], v[168:169], 0, s[34:35]
	ds_read_b128 v[194:197], v176 offset:32768
	ds_read_b128 v[198:201], v176 offset:33792
	ds_read_b128 v[202:205], v176 offset:34816
	ds_read_b128 v[206:209], v176 offset:35840
	ds_read_b128 v[210:213], v176 offset:36864
	ds_read_b128 v[214:217], v176 offset:37888
	ds_read_b128 v[218:221], v176 offset:38912
	ds_read_b128 v[222:225], v176 offset:39936
	global_load_lds_dwordx4 v[178:179], off
	v_lshl_add_u64 v[178:179], v[168:169], 0, s[90:91]
	s_mov_b32 m0, s25
	s_nop 0
	global_load_lds_dwordx4 v[178:179], off
	s_waitcnt vmcnt(8)
	s_waitcnt lgkmcnt(0)
	s_barrier
	s_waitcnt lgkmcnt(0)
	v_mfma_scale_f32_16x16x128_f8f6f4 v[156:159], v[0:7], v[194:201], v[156:159], v240, v240 op_sel_hi:[0,0,0]
	v_mfma_scale_f32_16x16x128_f8f6f4 v[148:151], v[8:15], v[194:201], v[148:151], v240, v240 op_sel_hi:[0,0,0]
	v_mfma_scale_f32_16x16x128_f8f6f4 v[140:143], v[0:7], v[202:209], v[140:143], v240, v240 op_sel_hi:[0,0,0]
	v_mfma_scale_f32_16x16x128_f8f6f4 v[132:135], v[8:15], v[202:209], v[132:135], v240, v240 op_sel_hi:[0,0,0]
	v_mfma_scale_f32_16x16x128_f8f6f4 v[124:127], v[0:7], v[210:217], v[124:127], v240, v240 op_sel_hi:[0,0,0]
	v_mfma_scale_f32_16x16x128_f8f6f4 v[116:119], v[8:15], v[210:217], v[116:119], v240, v240 op_sel_hi:[0,0,0]
	v_mfma_scale_f32_16x16x128_f8f6f4 v[108:111], v[0:7], v[218:225], v[108:111], v240, v240 op_sel_hi:[0,0,0]
	v_mfma_scale_f32_16x16x128_f8f6f4 v[100:103], v[8:15], v[218:225], v[100:103], v240, v240 op_sel_hi:[0,0,0]
	v_mfma_scale_f32_16x16x128_f8f6f4 v[152:155], v[16:23], v[194:201], v[152:155], v240, v240 op_sel_hi:[0,0,0]
	v_mfma_scale_f32_16x16x128_f8f6f4 v[144:147], v[24:31], v[194:201], v[144:147], v240, v240 op_sel_hi:[0,0,0]
	v_mfma_scale_f32_16x16x128_f8f6f4 v[136:139], v[16:23], v[202:209], v[136:139], v240, v240 op_sel_hi:[0,0,0]
	v_mfma_scale_f32_16x16x128_f8f6f4 v[128:131], v[24:31], v[202:209], v[128:131], v240, v240 op_sel_hi:[0,0,0]
	v_mfma_scale_f32_16x16x128_f8f6f4 v[120:123], v[16:23], v[210:217], v[120:123], v240, v240 op_sel_hi:[0,0,0]
	v_mfma_scale_f32_16x16x128_f8f6f4 v[112:115], v[24:31], v[210:217], v[112:115], v240, v240 op_sel_hi:[0,0,0]
	v_mfma_scale_f32_16x16x128_f8f6f4 v[104:107], v[16:23], v[218:225], v[104:107], v240, v240 op_sel_hi:[0,0,0]
	v_mfma_scale_f32_16x16x128_f8f6f4 v[96:99], v[24:31], v[218:225], v[96:99], v240, v240 op_sel_hi:[0,0,0]
	s_barrier
	s_add_i32 s14, s14, s6
	v_lshl_add_u64 v[178:179], v[166:167], 0, s[56:57]
	s_mov_b32 m0, s14
	ds_read_b128 v[194:197], v176 offset:49152
	ds_read_b128 v[198:201], v176 offset:50176
	ds_read_b128 v[202:205], v176 offset:51200
	ds_read_b128 v[206:209], v176 offset:52224
	ds_read_b128 v[210:213], v176 offset:53248
	ds_read_b128 v[214:217], v176 offset:54272
	ds_read_b128 v[218:221], v176 offset:55296
	ds_read_b128 v[222:225], v176 offset:56320
	global_load_lds_dwordx4 v[178:179], off
	v_lshl_add_u64 v[178:179], v[166:167], 0, s[58:59]
	s_add_i32 m0, s14, 0x2000
	s_add_i32 s14, s15, s6
	global_load_lds_dwordx4 v[178:179], off
	v_lshl_add_u64 v[178:179], v[166:167], 0, s[96:97]
	s_mov_b32 m0, s14
	v_lshl_add_u64 v[166:167], v[166:167], 0, s[4:5]
	global_load_lds_dwordx4 v[178:179], off
	s_add_i32 m0, s14, 0x2000
	s_nop 0
	global_load_lds_dwordx4 v[166:167], off
	v_lshl_add_u64 v[166:167], v[168:169], 0, s[56:57]
	s_mov_b32 m0, s26
	s_nop 0
	global_load_lds_dwordx4 v[166:167], off
	v_lshl_add_u64 v[166:167], v[168:169], 0, s[58:59]
	s_mov_b32 m0, s27
	s_nop 0
	global_load_lds_dwordx4 v[166:167], off
	s_waitcnt vmcnt(8)
	s_waitcnt lgkmcnt(0)
	s_barrier
	s_waitcnt lgkmcnt(0)
	v_mfma_scale_f32_16x16x128_f8f6f4 v[92:95], v[0:7], v[194:201], v[92:95], v240, v240 op_sel_hi:[0,0,0]
	v_mfma_scale_f32_16x16x128_f8f6f4 v[84:87], v[8:15], v[194:201], v[84:87], v240, v240 op_sel_hi:[0,0,0]
	v_mfma_scale_f32_16x16x128_f8f6f4 v[76:79], v[0:7], v[202:209], v[76:79], v240, v240 op_sel_hi:[0,0,0]
	v_mfma_scale_f32_16x16x128_f8f6f4 v[68:71], v[8:15], v[202:209], v[68:71], v240, v240 op_sel_hi:[0,0,0]
	v_mfma_scale_f32_16x16x128_f8f6f4 v[60:63], v[0:7], v[210:217], v[60:63], v240, v240 op_sel_hi:[0,0,0]
	v_mfma_scale_f32_16x16x128_f8f6f4 v[52:55], v[8:15], v[210:217], v[52:55], v240, v240 op_sel_hi:[0,0,0]
	v_mfma_scale_f32_16x16x128_f8f6f4 v[44:47], v[0:7], v[218:225], v[44:47], v240, v240 op_sel_hi:[0,0,0]
	v_mfma_scale_f32_16x16x128_f8f6f4 v[36:39], v[8:15], v[218:225], v[36:39], v240, v240 op_sel_hi:[0,0,0]
	v_mfma_scale_f32_16x16x128_f8f6f4 v[88:91], v[16:23], v[194:201], v[88:91], v240, v240 op_sel_hi:[0,0,0]
	v_mfma_scale_f32_16x16x128_f8f6f4 v[80:83], v[24:31], v[194:201], v[80:83], v240, v240 op_sel_hi:[0,0,0]
	v_mfma_scale_f32_16x16x128_f8f6f4 v[72:75], v[16:23], v[202:209], v[72:75], v240, v240 op_sel_hi:[0,0,0]
	v_mfma_scale_f32_16x16x128_f8f6f4 v[64:67], v[24:31], v[202:209], v[64:67], v240, v240 op_sel_hi:[0,0,0]
	v_mfma_scale_f32_16x16x128_f8f6f4 v[56:59], v[16:23], v[210:217], v[56:59], v240, v240 op_sel_hi:[0,0,0]
	v_mfma_scale_f32_16x16x128_f8f6f4 v[48:51], v[24:31], v[210:217], v[48:51], v240, v240 op_sel_hi:[0,0,0]
	v_mfma_scale_f32_16x16x128_f8f6f4 v[40:43], v[16:23], v[218:225], v[40:43], v240, v240 op_sel_hi:[0,0,0]
	v_mfma_scale_f32_16x16x128_f8f6f4 v[32:35], v[24:31], v[218:225], v[32:35], v240, v240 op_sel_hi:[0,0,0]
	s_barrier
	s_add_i32 s51, s51, 2
	s_add_u32 s46, s46, 0x100
	s_addc_u32 s47, s47, 0
	s_add_u32 s49, s49, 0x100
	s_addc_u32 s50, s50, 0
	s_cmp_gt_u32 s51, 5
.LBB0_503:
	s_add_u32 s14, s46, 0xfffe0080
	s_addc_u32 s15, s47, -1
	s_add_i32 s60, 0, 0x10000
	s_cmp_eq_u32 s51, 4
	s_cselect_b32 s15, s13, s15
	s_cselect_b32 s14, s31, s14
	s_cselect_b32 s17, s11, s50
	s_cselect_b32 s16, s48, s49
	s_add_i32 s61, 0, 0x14000
	v_add_u32_e32 v0, s60, v172
	v_add_u32_e32 v4, s61, v172
	ds_read_b128 v[24:27], v0
	ds_read_b128 v[28:31], v0 offset:1024
	ds_read_b128 v[16:19], v0 offset:2048
	ds_read_b128 v[20:23], v0 offset:3072
	ds_read_b128 v[8:11], v4
	ds_read_b128 v[12:15], v4 offset:1024
	ds_read_b128 v[0:3], v4 offset:2048
	ds_read_b128 v[4:7], v4 offset:3072
	v_lshl_add_u64 v[166:167], s[46:47], 0, v[164:165]
	s_add_i32 m0, s19, 0xc000
	ds_read_b128 v[194:197], v176
	ds_read_b128 v[198:201], v176 offset:1024
	ds_read_b128 v[202:205], v176 offset:2048
	ds_read_b128 v[206:209], v176 offset:3072
	ds_read_b128 v[210:213], v176 offset:4096
	ds_read_b128 v[214:217], v176 offset:5120
	ds_read_b128 v[218:221], v176 offset:6144
	ds_read_b128 v[222:225], v176 offset:7168
	global_load_lds_dwordx4 v[166:167], off
	v_lshl_add_u64 v[166:167], v[166:167], 0, s[94:95]
	s_add_i32 m0, s19, 0xe000
	s_nop 0
	global_load_lds_dwordx4 v[166:167], off
	s_waitcnt vmcnt(8)
	s_waitcnt lgkmcnt(0)
	s_barrier
	s_waitcnt lgkmcnt(0)
	v_mfma_scale_f32_16x16x128_f8f6f4 v[156:159], v[24:31], v[194:201], v[156:159], v240, v240 op_sel_hi:[0,0,0]
	v_mfma_scale_f32_16x16x128_f8f6f4 v[148:151], v[16:23], v[194:201], v[148:151], v240, v240 op_sel_hi:[0,0,0]
	v_mfma_scale_f32_16x16x128_f8f6f4 v[140:143], v[24:31], v[202:209], v[140:143], v240, v240 op_sel_hi:[0,0,0]
	v_mfma_scale_f32_16x16x128_f8f6f4 v[132:135], v[16:23], v[202:209], v[132:135], v240, v240 op_sel_hi:[0,0,0]
	v_mfma_scale_f32_16x16x128_f8f6f4 v[124:127], v[24:31], v[210:217], v[124:127], v240, v240 op_sel_hi:[0,0,0]
	v_mfma_scale_f32_16x16x128_f8f6f4 v[116:119], v[16:23], v[210:217], v[116:119], v240, v240 op_sel_hi:[0,0,0]
	v_mfma_scale_f32_16x16x128_f8f6f4 v[108:111], v[24:31], v[218:225], v[108:111], v240, v240 op_sel_hi:[0,0,0]
	v_mfma_scale_f32_16x16x128_f8f6f4 v[100:103], v[16:23], v[218:225], v[100:103], v240, v240 op_sel_hi:[0,0,0]
	v_mfma_scale_f32_16x16x128_f8f6f4 v[152:155], v[8:15], v[194:201], v[152:155], v240, v240 op_sel_hi:[0,0,0]
	v_mfma_scale_f32_16x16x128_f8f6f4 v[144:147], v[0:7], v[194:201], v[144:147], v240, v240 op_sel_hi:[0,0,0]
	v_mfma_scale_f32_16x16x128_f8f6f4 v[136:139], v[8:15], v[202:209], v[136:139], v240, v240 op_sel_hi:[0,0,0]
	v_mfma_scale_f32_16x16x128_f8f6f4 v[128:131], v[0:7], v[202:209], v[128:131], v240, v240 op_sel_hi:[0,0,0]
	v_mfma_scale_f32_16x16x128_f8f6f4 v[120:123], v[8:15], v[210:217], v[120:123], v240, v240 op_sel_hi:[0,0,0]
	v_mfma_scale_f32_16x16x128_f8f6f4 v[112:115], v[0:7], v[210:217], v[112:115], v240, v240 op_sel_hi:[0,0,0]
	v_mfma_scale_f32_16x16x128_f8f6f4 v[104:107], v[8:15], v[218:225], v[104:107], v240, v240 op_sel_hi:[0,0,0]
	v_mfma_scale_f32_16x16x128_f8f6f4 v[96:99], v[0:7], v[218:225], v[96:99], v240, v240 op_sel_hi:[0,0,0]
	s_barrier
	v_lshl_add_u64 v[166:167], s[16:17], 0, v[184:185]
	s_add_i32 s16, s60, s6
	s_mov_b32 m0, s16
	ds_read_b128 v[194:197], v176 offset:16384
	ds_read_b128 v[198:201], v176 offset:17408
	ds_read_b128 v[202:205], v176 offset:18432
	ds_read_b128 v[206:209], v176 offset:19456
	ds_read_b128 v[210:213], v176 offset:20480
	ds_read_b128 v[214:217], v176 offset:21504
	ds_read_b128 v[218:221], v176 offset:22528
	ds_read_b128 v[222:225], v176 offset:23552
	global_load_lds_dwordx4 v[166:167], off
	v_lshl_add_u64 v[168:169], v[166:167], 0, s[94:95]
	s_add_i32 m0, s16, 0x2000
	s_add_i32 s16, s61, s6
	global_load_lds_dwordx4 v[168:169], off
	v_lshl_add_u64 v[168:169], v[166:167], 0, s[34:35]
	s_mov_b32 m0, s16
	s_nop 0
	global_load_lds_dwordx4 v[168:169], off
	v_lshl_add_u64 v[168:169], v[166:167], 0, s[90:91]
	s_add_i32 m0, s16, 0x2000
	s_nop 0
	global_load_lds_dwordx4 v[168:169], off
	v_lshl_add_u64 v[168:169], s[14:15], 0, v[160:161]
	s_mov_b32 m0, s19
	v_lshl_add_u64 v[178:179], v[168:169], 0, s[94:95]
	global_load_lds_dwordx4 v[168:169], off
	s_mov_b32 m0, s20
	s_nop 0
	global_load_lds_dwordx4 v[178:179], off
	s_waitcnt vmcnt(8)
	s_waitcnt lgkmcnt(0)
	s_barrier
	s_waitcnt lgkmcnt(0)
	v_mfma_scale_f32_16x16x128_f8f6f4 v[92:95], v[24:31], v[194:201], v[92:95], v240, v240 op_sel_hi:[0,0,0]
	v_mfma_scale_f32_16x16x128_f8f6f4 v[84:87], v[16:23], v[194:201], v[84:87], v240, v240 op_sel_hi:[0,0,0]
	v_mfma_scale_f32_16x16x128_f8f6f4 v[76:79], v[24:31], v[202:209], v[76:79], v240, v240 op_sel_hi:[0,0,0]
	v_mfma_scale_f32_16x16x128_f8f6f4 v[68:71], v[16:23], v[202:209], v[68:71], v240, v240 op_sel_hi:[0,0,0]
	v_mfma_scale_f32_16x16x128_f8f6f4 v[60:63], v[24:31], v[210:217], v[60:63], v240, v240 op_sel_hi:[0,0,0]
	v_mfma_scale_f32_16x16x128_f8f6f4 v[52:55], v[16:23], v[210:217], v[52:55], v240, v240 op_sel_hi:[0,0,0]
	v_mfma_scale_f32_16x16x128_f8f6f4 v[44:47], v[24:31], v[218:225], v[44:47], v240, v240 op_sel_hi:[0,0,0]
	v_mfma_scale_f32_16x16x128_f8f6f4 v[36:39], v[16:23], v[218:225], v[36:39], v240, v240 op_sel_hi:[0,0,0]
	v_mfma_scale_f32_16x16x128_f8f6f4 v[88:91], v[8:15], v[194:201], v[88:91], v240, v240 op_sel_hi:[0,0,0]
	v_mfma_scale_f32_16x16x128_f8f6f4 v[80:83], v[0:7], v[194:201], v[80:83], v240, v240 op_sel_hi:[0,0,0]
	v_mfma_scale_f32_16x16x128_f8f6f4 v[72:75], v[8:15], v[202:209], v[72:75], v240, v240 op_sel_hi:[0,0,0]
	v_mfma_scale_f32_16x16x128_f8f6f4 v[64:67], v[0:7], v[202:209], v[64:67], v240, v240 op_sel_hi:[0,0,0]
	v_mfma_scale_f32_16x16x128_f8f6f4 v[56:59], v[8:15], v[210:217], v[56:59], v240, v240 op_sel_hi:[0,0,0]
	v_mfma_scale_f32_16x16x128_f8f6f4 v[48:51], v[0:7], v[210:217], v[48:51], v240, v240 op_sel_hi:[0,0,0]
	v_mfma_scale_f32_16x16x128_f8f6f4 v[40:43], v[8:15], v[218:225], v[40:43], v240, v240 op_sel_hi:[0,0,0]
	v_mfma_scale_f32_16x16x128_f8f6f4 v[32:35], v[0:7], v[218:225], v[32:35], v240, v240 op_sel_hi:[0,0,0]
	s_barrier
	s_add_i32 s14, 0, 0x18000
	s_add_i32 s15, 0, 0x1c000
	v_add_u32_e32 v12, s14, v172
	v_add_u32_e32 v28, s15, v172
	ds_read_b128 v[0:3], v12
	ds_read_b128 v[4:7], v12 offset:1024
	ds_read_b128 v[8:11], v12 offset:2048
	ds_read_b128 v[12:15], v12 offset:3072
	ds_read_b128 v[16:19], v28
	ds_read_b128 v[20:23], v28 offset:1024
	ds_read_b128 v[24:27], v28 offset:2048
	ds_read_b128 v[28:31], v28 offset:3072
	s_mov_b32 m0, s24
	v_lshl_add_u64 v[178:179], v[168:169], 0, s[34:35]
	ds_read_b128 v[194:197], v176 offset:32768
	ds_read_b128 v[198:201], v176 offset:33792
	ds_read_b128 v[202:205], v176 offset:34816
	ds_read_b128 v[206:209], v176 offset:35840
	ds_read_b128 v[210:213], v176 offset:36864
	ds_read_b128 v[214:217], v176 offset:37888
	ds_read_b128 v[218:221], v176 offset:38912
	ds_read_b128 v[222:225], v176 offset:39936
	global_load_lds_dwordx4 v[178:179], off
	v_lshl_add_u64 v[178:179], v[168:169], 0, s[90:91]
	s_mov_b32 m0, s25
	s_nop 0
	global_load_lds_dwordx4 v[178:179], off
	s_waitcnt vmcnt(8)
	s_waitcnt lgkmcnt(0)
	s_barrier
	s_waitcnt lgkmcnt(0)
	v_mfma_scale_f32_16x16x128_f8f6f4 v[156:159], v[0:7], v[194:201], v[156:159], v240, v240 op_sel_hi:[0,0,0]
	v_mfma_scale_f32_16x16x128_f8f6f4 v[148:151], v[8:15], v[194:201], v[148:151], v240, v240 op_sel_hi:[0,0,0]
	v_mfma_scale_f32_16x16x128_f8f6f4 v[140:143], v[0:7], v[202:209], v[140:143], v240, v240 op_sel_hi:[0,0,0]
	v_mfma_scale_f32_16x16x128_f8f6f4 v[132:135], v[8:15], v[202:209], v[132:135], v240, v240 op_sel_hi:[0,0,0]
	v_mfma_scale_f32_16x16x128_f8f6f4 v[124:127], v[0:7], v[210:217], v[124:127], v240, v240 op_sel_hi:[0,0,0]
	v_mfma_scale_f32_16x16x128_f8f6f4 v[116:119], v[8:15], v[210:217], v[116:119], v240, v240 op_sel_hi:[0,0,0]
	v_mfma_scale_f32_16x16x128_f8f6f4 v[108:111], v[0:7], v[218:225], v[108:111], v240, v240 op_sel_hi:[0,0,0]
	v_mfma_scale_f32_16x16x128_f8f6f4 v[100:103], v[8:15], v[218:225], v[100:103], v240, v240 op_sel_hi:[0,0,0]
	v_mfma_scale_f32_16x16x128_f8f6f4 v[152:155], v[16:23], v[194:201], v[152:155], v240, v240 op_sel_hi:[0,0,0]
	v_mfma_scale_f32_16x16x128_f8f6f4 v[144:147], v[24:31], v[194:201], v[144:147], v240, v240 op_sel_hi:[0,0,0]
	v_mfma_scale_f32_16x16x128_f8f6f4 v[136:139], v[16:23], v[202:209], v[136:139], v240, v240 op_sel_hi:[0,0,0]
	v_mfma_scale_f32_16x16x128_f8f6f4 v[128:131], v[24:31], v[202:209], v[128:131], v240, v240 op_sel_hi:[0,0,0]
	v_mfma_scale_f32_16x16x128_f8f6f4 v[120:123], v[16:23], v[210:217], v[120:123], v240, v240 op_sel_hi:[0,0,0]
	v_mfma_scale_f32_16x16x128_f8f6f4 v[112:115], v[24:31], v[210:217], v[112:115], v240, v240 op_sel_hi:[0,0,0]
	v_mfma_scale_f32_16x16x128_f8f6f4 v[104:107], v[16:23], v[218:225], v[104:107], v240, v240 op_sel_hi:[0,0,0]
	v_mfma_scale_f32_16x16x128_f8f6f4 v[96:99], v[24:31], v[218:225], v[96:99], v240, v240 op_sel_hi:[0,0,0]
	s_barrier
	s_add_i32 s14, s14, s6
	v_lshl_add_u64 v[178:179], v[166:167], 0, s[56:57]
	s_mov_b32 m0, s14
	ds_read_b128 v[194:197], v176 offset:49152
	ds_read_b128 v[198:201], v176 offset:50176
	ds_read_b128 v[202:205], v176 offset:51200
	ds_read_b128 v[206:209], v176 offset:52224
	ds_read_b128 v[210:213], v176 offset:53248
	ds_read_b128 v[214:217], v176 offset:54272
	ds_read_b128 v[218:221], v176 offset:55296
	ds_read_b128 v[222:225], v176 offset:56320
	global_load_lds_dwordx4 v[178:179], off
	v_lshl_add_u64 v[178:179], v[166:167], 0, s[58:59]
	s_add_i32 m0, s14, 0x2000
	s_add_i32 s14, s15, s6
	global_load_lds_dwordx4 v[178:179], off
	v_lshl_add_u64 v[178:179], v[166:167], 0, s[96:97]
	s_mov_b32 m0, s14
	v_lshl_add_u64 v[166:167], v[166:167], 0, s[4:5]
	global_load_lds_dwordx4 v[178:179], off
	s_add_i32 m0, s14, 0x2000
	s_nop 0
	global_load_lds_dwordx4 v[166:167], off
	v_lshl_add_u64 v[166:167], v[168:169], 0, s[56:57]
	s_mov_b32 m0, s26
	s_nop 0
	global_load_lds_dwordx4 v[166:167], off
	v_lshl_add_u64 v[166:167], v[168:169], 0, s[58:59]
	s_mov_b32 m0, s27
	s_nop 0
	global_load_lds_dwordx4 v[166:167], off
	s_waitcnt vmcnt(8)
	s_waitcnt lgkmcnt(0)
	s_barrier
	s_waitcnt lgkmcnt(0)
	v_mfma_scale_f32_16x16x128_f8f6f4 v[92:95], v[0:7], v[194:201], v[92:95], v240, v240 op_sel_hi:[0,0,0]
	v_mfma_scale_f32_16x16x128_f8f6f4 v[84:87], v[8:15], v[194:201], v[84:87], v240, v240 op_sel_hi:[0,0,0]
	v_mfma_scale_f32_16x16x128_f8f6f4 v[76:79], v[0:7], v[202:209], v[76:79], v240, v240 op_sel_hi:[0,0,0]
	v_mfma_scale_f32_16x16x128_f8f6f4 v[68:71], v[8:15], v[202:209], v[68:71], v240, v240 op_sel_hi:[0,0,0]
	v_mfma_scale_f32_16x16x128_f8f6f4 v[60:63], v[0:7], v[210:217], v[60:63], v240, v240 op_sel_hi:[0,0,0]
	v_mfma_scale_f32_16x16x128_f8f6f4 v[52:55], v[8:15], v[210:217], v[52:55], v240, v240 op_sel_hi:[0,0,0]
	v_mfma_scale_f32_16x16x128_f8f6f4 v[44:47], v[0:7], v[218:225], v[44:47], v240, v240 op_sel_hi:[0,0,0]
	v_mfma_scale_f32_16x16x128_f8f6f4 v[36:39], v[8:15], v[218:225], v[36:39], v240, v240 op_sel_hi:[0,0,0]
	v_mfma_scale_f32_16x16x128_f8f6f4 v[88:91], v[16:23], v[194:201], v[88:91], v240, v240 op_sel_hi:[0,0,0]
	v_mfma_scale_f32_16x16x128_f8f6f4 v[80:83], v[24:31], v[194:201], v[80:83], v240, v240 op_sel_hi:[0,0,0]
	v_mfma_scale_f32_16x16x128_f8f6f4 v[72:75], v[16:23], v[202:209], v[72:75], v240, v240 op_sel_hi:[0,0,0]
	v_mfma_scale_f32_16x16x128_f8f6f4 v[64:67], v[24:31], v[202:209], v[64:67], v240, v240 op_sel_hi:[0,0,0]
	v_mfma_scale_f32_16x16x128_f8f6f4 v[56:59], v[16:23], v[210:217], v[56:59], v240, v240 op_sel_hi:[0,0,0]
	v_mfma_scale_f32_16x16x128_f8f6f4 v[48:51], v[24:31], v[210:217], v[48:51], v240, v240 op_sel_hi:[0,0,0]
	v_mfma_scale_f32_16x16x128_f8f6f4 v[40:43], v[16:23], v[218:225], v[40:43], v240, v240 op_sel_hi:[0,0,0]
	v_mfma_scale_f32_16x16x128_f8f6f4 v[32:35], v[24:31], v[218:225], v[32:35], v240, v240 op_sel_hi:[0,0,0]
	s_barrier
	s_add_i32 s51, s51, 2
	s_add_u32 s46, s46, 0x100
	s_addc_u32 s47, s47, 0
	s_add_u32 s49, s49, 0x100
	s_addc_u32 s50, s50, 0
	s_cmp_gt_u32 s51, 5
	s_cbranch_scc0 .LBB0_503
	s_and_b64 vcc, exec, s[8:9]
	s_cbranch_vccz .LBB0_506
	s_barrier
